# v45 + removed the 36 redundant s_waitcnt lgkmcnt(0) that followed the pre-MFMA barrier (an identical wait already precedes the barrier)
# baseline (speedup 1.0000x reference)
; #define PG8_STAGE(bufoff, gbase, voff) do { _Pragma("unroll") for (int _i = 0; _i < 2; ++_i) \
;         __builtin_amdgcn_global_load_lds((const unsigned*)((const char*)(gbase) + (voff)[_i]), (LAS unsigned*)(lds + (bufoff) + ldsw + _i * 8192), 16, 0, 0); } while (0)
; #define PG8_LDA(dst, b, h) do { _Pragma("unroll") for (int m = 0; m < 4; ++m) _Pragma("unroll") for (int k = 0; k < 2; ++k) dst[m][k] = *(const LAS bf16x8*)(lds + PG8_SA(b, h) + aoff + m * 2048 + k * 1024); } while (0)
; #define PG8_LDB(dst, b, h) do { _Pragma("unroll") for (int n = 0; n < 2; ++n) _Pragma("unroll") for (int k = 0; k < 2; ++k) dst[n][k] = *(const LAS bf16x8*)(lds + PG8_SB(b, h) + boff + n * 2048 + k * 1024); } while (0)
; #define PG8_WAIT_V(n) asm volatile("s_waitcnt vmcnt(" #n ")" ::: "memory")
; #define PG8_WAIT_L(n) asm volatile("s_waitcnt lgkmcnt(" #n ")" ::: "memory")
; #define PG8_BAR __builtin_amdgcn_s_barrier()
; #define PG8_SCHED __builtin_amdgcn_sched_barrier(0)
; template <class Epi, class Sched>
; __device__ __forceinline__ void gemm_phase(LAS unsigned char* lds, const Gemm g, const Sched& S, const Epi& E) {
;     ...
;             const bool last = (t == nt - 2);
;             const char* a1 = cA + (size_t)(t + 1) * kstep;
;             const char* a2 = last ? nA : cA + (size_t)(t + 2) * kstep; const char* b2 = last ? nB : cB + (size_t)(t + 2) * kstep;
;             const char* a3 = a2 + kstep; const char* b3 = b2 + kstep;
;             if constexpr (Epi::MIDK) { if (t == (nt >> 1)) { int fr_ = fr, fq_ = fq; asm volatile("" : "+v"(fr_), "+v"(fq_)); E.mid(acc, cur, wr, wc, fr_, fq_); } }
;             PG8_LDB(B0, 0, 0); PG8_LDB(B1, 0, 1); PG8_SCHED; PG8_LDA(At, 0, 0); PG8_STAGE(PG8_SA(1, 1), a1 + hsA, voffA);
;             PG8_WAIT_V(8); PG8_WAIT_L(0); PG8_BAR; PG8_MMA(0, 0, At, B0); PG8_MMA(0, 1, At, B1); PG8_BAR; PG8_SCHED;
;             PG8_LDA(At, 0, 1); PG8_STAGE(PG8_SB(0, 0), b2, voffB); PG8_STAGE(PG8_SB(0, 1), b2 + hsB, voffB); PG8_STAGE(PG8_SA(0, 0), a2, voffA);
;             PG8_WAIT_V(8); PG8_WAIT_L(0); PG8_BAR; PG8_MMA(1, 0, At, B0); PG8_MMA(1, 1, At, B1); PG8_BAR; PG8_SCHED;
;             PG8_LDB(B0, 1, 0); PG8_LDB(B1, 1, 1); PG8_SCHED; PG8_LDA(At, 1, 0); PG8_STAGE(PG8_SA(0, 1), a2 + hsA, voffA);
;             PG8_WAIT_V(8); PG8_WAIT_L(0); PG8_BAR; PG8_MMA(0, 0, At, B0); PG8_MMA(0, 1, At, B1); PG8_BAR; PG8_SCHED;
.Lnp_222:
.LBB0_222:
	s_add_i32 s96, s9, 2
	s_add_u32 s20, s0, 0xfffc0080
	s_addc_u32 s21, s1, -1
	s_add_i32 s74, 0, 0x10000
	s_cmp_eq_u32 s82, s9
	s_cselect_b32 s85, s10, s21
	s_cselect_b32 s84, s43, s20
	s_cselect_b32 s39, s45, s8
	s_cselect_b32 s38, vcc_lo, vcc_hi
	s_add_i32 s9, 0, 0x14000
	v_add_u32_e32 v154, s74, v160
	v_add_u32_e32 v174, s9, v160
	ds_read_b128 v[142:145], v154
	ds_read_b128 v[146:149], v154 offset:1024
	ds_read_b128 v[150:153], v154 offset:2048
	ds_read_b128 v[154:157], v154 offset:3072
	ds_read_b128 v[162:165], v174
	ds_read_b128 v[166:169], v174 offset:1024
	ds_read_b128 v[170:173], v174 offset:2048
	ds_read_b128 v[174:177], v174 offset:3072
	s_add_i32 m0, s16, 0xc000
	ds_read_b128 v[178:181], v161
	ds_read_b128 v[182:185], v161 offset:1024
	ds_read_b128 v[186:189], v161 offset:2048
	ds_read_b128 v[208:211], v161 offset:3072
	ds_read_b128 v[212:215], v161 offset:4096
	ds_read_b128 v[216:219], v161 offset:5120
	ds_read_b128 v[220:223], v161 offset:6144
	global_load_lds_dwordx4 v138, s[0:1]
	s_add_i32 m0, s16, 0xe000
	ds_read_b128 v[224:227], v161 offset:7168
	global_load_lds_dwordx4 v140, s[0:1]
	s_waitcnt vmcnt(8)
	s_waitcnt lgkmcnt(0)
	s_barrier
	v_mfma_f32_16x16x32_bf16 v[122:125], v[142:145], v[178:181], v[122:125]
	v_mfma_f32_16x16x32_bf16 v[114:117], v[150:153], v[178:181], v[114:117]
	v_mfma_f32_16x16x32_bf16 v[106:109], v[142:145], v[186:189], v[106:109]
	v_mfma_f32_16x16x32_bf16 v[98:101], v[150:153], v[186:189], v[98:101]
	v_mfma_f32_16x16x32_bf16 v[90:93], v[142:145], v[212:215], v[90:93]
	v_mfma_f32_16x16x32_bf16 v[82:85], v[150:153], v[212:215], v[82:85]
	v_mfma_f32_16x16x32_bf16 v[74:77], v[142:145], v[220:223], v[74:77]
	v_mfma_f32_16x16x32_bf16 v[66:69], v[150:153], v[220:223], v[66:69]
	v_mfma_f32_16x16x32_bf16 v[122:125], v[146:149], v[182:185], v[122:125]
	v_mfma_f32_16x16x32_bf16 v[114:117], v[154:157], v[182:185], v[114:117]
	v_mfma_f32_16x16x32_bf16 v[106:109], v[146:149], v[208:211], v[106:109]
	v_mfma_f32_16x16x32_bf16 v[98:101], v[154:157], v[208:211], v[98:101]
	v_mfma_f32_16x16x32_bf16 v[90:93], v[146:149], v[216:219], v[90:93]
	v_mfma_f32_16x16x32_bf16 v[82:85], v[154:157], v[216:219], v[82:85]
	v_mfma_f32_16x16x32_bf16 v[74:77], v[146:149], v[224:227], v[74:77]
	v_mfma_f32_16x16x32_bf16 v[66:69], v[154:157], v[224:227], v[66:69]
	v_mfma_f32_16x16x32_bf16 v[126:129], v[162:165], v[178:181], v[126:129]
	v_mfma_f32_16x16x32_bf16 v[118:121], v[170:173], v[178:181], v[118:121]
	v_mfma_f32_16x16x32_bf16 v[110:113], v[162:165], v[186:189], v[110:113]
	v_mfma_f32_16x16x32_bf16 v[102:105], v[170:173], v[186:189], v[102:105]
	v_mfma_f32_16x16x32_bf16 v[94:97], v[162:165], v[212:215], v[94:97]
	v_mfma_f32_16x16x32_bf16 v[86:89], v[170:173], v[212:215], v[86:89]
	v_mfma_f32_16x16x32_bf16 v[78:81], v[162:165], v[220:223], v[78:81]
	v_mfma_f32_16x16x32_bf16 v[70:73], v[170:173], v[220:223], v[70:73]
	v_mfma_f32_16x16x32_bf16 v[126:129], v[166:169], v[182:185], v[126:129]
	v_mfma_f32_16x16x32_bf16 v[118:121], v[174:177], v[182:185], v[118:121]
	v_mfma_f32_16x16x32_bf16 v[110:113], v[166:169], v[208:211], v[110:113]
	v_mfma_f32_16x16x32_bf16 v[102:105], v[174:177], v[208:211], v[102:105]
	v_mfma_f32_16x16x32_bf16 v[94:97], v[166:169], v[216:219], v[94:97]
	v_mfma_f32_16x16x32_bf16 v[86:89], v[174:177], v[216:219], v[86:89]
	v_mfma_f32_16x16x32_bf16 v[78:81], v[166:169], v[224:227], v[78:81]
	v_mfma_f32_16x16x32_bf16 v[70:73], v[174:177], v[224:227], v[70:73]
	s_barrier
	s_add_i32 s20, s74, s12
	s_mov_b32 m0, s20
	ds_read_b128 v[178:181], v161 offset:16384
	ds_read_b128 v[182:185], v161 offset:17408
	ds_read_b128 v[186:189], v161 offset:18432
	ds_read_b128 v[208:211], v161 offset:19456
	global_load_lds_dwordx4 v0, s[38:39]
	s_add_i32 m0, s20, 0x2000
	s_add_u32 s20, s38, 0x40000
	s_addc_u32 s21, s39, 0
	s_add_i32 s9, s9, s12
	global_load_lds_dwordx4 v130, s[38:39]
	s_mov_b32 m0, s9
	ds_read_b128 v[212:215], v161 offset:20480
	global_load_lds_dwordx4 v0, s[20:21]
	s_add_i32 m0, s9, 0x2000
	ds_read_b128 v[216:219], v161 offset:21504
	global_load_lds_dwordx4 v130, s[20:21]
	s_mov_b32 m0, s16
	ds_read_b128 v[220:223], v161 offset:22528
	global_load_lds_dwordx4 v134, s[84:85]
	s_mov_b32 m0, s30
	ds_read_b128 v[224:227], v161 offset:23552
	global_load_lds_dwordx4 v132, s[84:85]
	s_waitcnt vmcnt(8)
	s_waitcnt lgkmcnt(0)
	s_barrier
	v_mfma_f32_16x16x32_bf16 v[58:61], v[142:145], v[178:181], v[58:61]
	v_mfma_f32_16x16x32_bf16 v[50:53], v[150:153], v[178:181], v[50:53]
	v_mfma_f32_16x16x32_bf16 v[42:45], v[142:145], v[186:189], v[42:45]
	v_mfma_f32_16x16x32_bf16 v[34:37], v[150:153], v[186:189], v[34:37]
	v_mfma_f32_16x16x32_bf16 v[26:29], v[142:145], v[212:215], v[26:29]
	v_mfma_f32_16x16x32_bf16 v[18:21], v[150:153], v[212:215], v[18:21]
	v_mfma_f32_16x16x32_bf16 v[10:13], v[142:145], v[220:223], v[10:13]
	v_mfma_f32_16x16x32_bf16 v[2:5], v[150:153], v[220:223], v[2:5]
	v_mfma_f32_16x16x32_bf16 v[58:61], v[146:149], v[182:185], v[58:61]
	v_mfma_f32_16x16x32_bf16 v[50:53], v[154:157], v[182:185], v[50:53]
	v_mfma_f32_16x16x32_bf16 v[42:45], v[146:149], v[208:211], v[42:45]
	v_mfma_f32_16x16x32_bf16 v[34:37], v[154:157], v[208:211], v[34:37]
	v_mfma_f32_16x16x32_bf16 v[26:29], v[146:149], v[216:219], v[26:29]
	v_mfma_f32_16x16x32_bf16 v[18:21], v[154:157], v[216:219], v[18:21]
	v_mfma_f32_16x16x32_bf16 v[10:13], v[146:149], v[224:227], v[10:13]
	v_mfma_f32_16x16x32_bf16 v[2:5], v[154:157], v[224:227], v[2:5]
	v_mfma_f32_16x16x32_bf16 v[62:65], v[162:165], v[178:181], v[62:65]
	v_mfma_f32_16x16x32_bf16 v[54:57], v[170:173], v[178:181], v[54:57]
	v_mfma_f32_16x16x32_bf16 v[46:49], v[162:165], v[186:189], v[46:49]
	v_mfma_f32_16x16x32_bf16 v[38:41], v[170:173], v[186:189], v[38:41]
	v_mfma_f32_16x16x32_bf16 v[30:33], v[162:165], v[212:215], v[30:33]
	v_mfma_f32_16x16x32_bf16 v[22:25], v[170:173], v[212:215], v[22:25]
	v_mfma_f32_16x16x32_bf16 v[14:17], v[162:165], v[220:223], v[14:17]
	v_mfma_f32_16x16x32_bf16 v[6:9], v[170:173], v[220:223], v[6:9]
	v_mfma_f32_16x16x32_bf16 v[62:65], v[166:169], v[182:185], v[62:65]
	v_mfma_f32_16x16x32_bf16 v[54:57], v[174:177], v[182:185], v[54:57]
	v_mfma_f32_16x16x32_bf16 v[46:49], v[166:169], v[208:211], v[46:49]
	v_mfma_f32_16x16x32_bf16 v[38:41], v[174:177], v[208:211], v[38:41]
	v_mfma_f32_16x16x32_bf16 v[30:33], v[166:169], v[216:219], v[30:33]
	v_mfma_f32_16x16x32_bf16 v[22:25], v[174:177], v[216:219], v[22:25]
	v_mfma_f32_16x16x32_bf16 v[14:17], v[166:169], v[224:227], v[14:17]
	v_mfma_f32_16x16x32_bf16 v[6:9], v[174:177], v[224:227], v[6:9]
	s_barrier
; #define PG8_STAGE(bufoff, gbase, voff) do { _Pragma("unroll") for (int _i = 0; _i < 2; ++_i) \
;         __builtin_amdgcn_global_load_lds((const unsigned*)((const char*)(gbase) + (voff)[_i]), (LAS unsigned*)(lds + (bufoff) + ldsw + _i * 8192), 16, 0, 0); } while (0)
; #define PG8_LDA(dst, b, h) do { _Pragma("unroll") for (int m = 0; m < 4; ++m) _Pragma("unroll") for (int k = 0; k < 2; ++k) dst[m][k] = *(const LAS bf16x8*)(lds + PG8_SA(b, h) + aoff + m * 2048 + k * 1024); } while (0)
; #define PG8_LDB(dst, b, h) do { _Pragma("unroll") for (int n = 0; n < 2; ++n) _Pragma("unroll") for (int k = 0; k < 2; ++k) dst[n][k] = *(const LAS bf16x8*)(lds + PG8_SB(b, h) + boff + n * 2048 + k * 1024); } while (0)
; #define PG8_MMA(ai, bj, At, Bt) do { __builtin_amdgcn_s_setprio(1); _Pragma("unroll") for (int m = 0; m < 4; ++m) _Pragma("unroll") for (int n = 0; n < 2; ++n) _Pragma("unroll") for (int k = 0; k < 2; ++k) \
;         acc[ai][bj][m][n] = __builtin_amdgcn_mfma_f32_16x16x32_bf16(Bt[n][k], At[m][k], acc[ai][bj][m][n], 0, 0, 0); __builtin_amdgcn_s_setprio(0); } while (0)
; #define PG8_WAIT_V(n) asm volatile("s_waitcnt vmcnt(" #n ")" ::: "memory")
; #define PG8_WAIT_L(n) asm volatile("s_waitcnt lgkmcnt(" #n ")" ::: "memory")
; #define PG8_BAR __builtin_amdgcn_s_barrier()
; #define PG8_SCHED __builtin_amdgcn_sched_barrier(0)
; template <class Epi, class Sched>
; __device__ __forceinline__ void gemm_phase(LAS unsigned char* lds, const Gemm g, const Sched& S, const Epi& E) {
;     ...
;             PG8_LDB(B0, 1, 0); PG8_LDB(B1, 1, 1); PG8_SCHED; PG8_LDA(At, 1, 0); PG8_STAGE(PG8_SA(0, 1), a2 + hsA, voffA);
;             PG8_WAIT_V(8); PG8_WAIT_L(0); PG8_BAR; PG8_MMA(0, 0, At, B0); PG8_MMA(0, 1, At, B1); PG8_BAR; PG8_SCHED;
;             PG8_LDA(At, 1, 1); PG8_STAGE(PG8_SB(1, 0), b3, voffB); PG8_STAGE(PG8_SB(1, 1), b3 + hsB, voffB); PG8_STAGE(PG8_SA(1, 0), a3, voffA);
;             PG8_WAIT_V(8); PG8_WAIT_L(0); PG8_BAR; PG8_MMA(1, 0, At, B0); PG8_MMA(1, 1, At, B1); PG8_BAR; PG8_SCHED;
;         }
	s_add_i32 s9, 0, 0x18000
	s_add_i32 s74, 0, 0x1c000
	v_add_u32_e32 v154, s9, v160
	v_add_u32_e32 v174, s74, v160
	ds_read_b128 v[142:145], v154
	ds_read_b128 v[146:149], v154 offset:1024
	ds_read_b128 v[150:153], v154 offset:2048
	ds_read_b128 v[154:157], v154 offset:3072
	ds_read_b128 v[162:165], v174
	ds_read_b128 v[166:169], v174 offset:1024
	ds_read_b128 v[170:173], v174 offset:2048
	ds_read_b128 v[174:177], v174 offset:3072
	s_add_u32 s20, s84, 0x40000
	s_addc_u32 s21, s85, 0
	s_mov_b32 m0, s52
	ds_read_b128 v[178:181], v161 offset:32768
	ds_read_b128 v[182:185], v161 offset:33792
	ds_read_b128 v[186:189], v161 offset:34816
	ds_read_b128 v[208:211], v161 offset:35840
	ds_read_b128 v[212:215], v161 offset:36864
	ds_read_b128 v[216:219], v161 offset:37888
	ds_read_b128 v[220:223], v161 offset:38912
	global_load_lds_dwordx4 v134, s[20:21]
	s_mov_b32 m0, s56
	ds_read_b128 v[224:227], v161 offset:39936
	global_load_lds_dwordx4 v132, s[20:21]
	s_waitcnt vmcnt(8)
	s_waitcnt lgkmcnt(0)
	s_barrier
	v_mfma_f32_16x16x32_bf16 v[122:125], v[142:145], v[178:181], v[122:125]
	v_mfma_f32_16x16x32_bf16 v[114:117], v[150:153], v[178:181], v[114:117]
	v_mfma_f32_16x16x32_bf16 v[106:109], v[142:145], v[186:189], v[106:109]
	v_mfma_f32_16x16x32_bf16 v[98:101], v[150:153], v[186:189], v[98:101]
	v_mfma_f32_16x16x32_bf16 v[90:93], v[142:145], v[212:215], v[90:93]
	v_mfma_f32_16x16x32_bf16 v[82:85], v[150:153], v[212:215], v[82:85]
	v_mfma_f32_16x16x32_bf16 v[74:77], v[142:145], v[220:223], v[74:77]
	v_mfma_f32_16x16x32_bf16 v[66:69], v[150:153], v[220:223], v[66:69]
	v_mfma_f32_16x16x32_bf16 v[122:125], v[146:149], v[182:185], v[122:125]
	v_mfma_f32_16x16x32_bf16 v[114:117], v[154:157], v[182:185], v[114:117]
	v_mfma_f32_16x16x32_bf16 v[106:109], v[146:149], v[208:211], v[106:109]
	v_mfma_f32_16x16x32_bf16 v[98:101], v[154:157], v[208:211], v[98:101]
	v_mfma_f32_16x16x32_bf16 v[90:93], v[146:149], v[216:219], v[90:93]
	v_mfma_f32_16x16x32_bf16 v[82:85], v[154:157], v[216:219], v[82:85]
	v_mfma_f32_16x16x32_bf16 v[74:77], v[146:149], v[224:227], v[74:77]
	v_mfma_f32_16x16x32_bf16 v[66:69], v[154:157], v[224:227], v[66:69]
	v_mfma_f32_16x16x32_bf16 v[126:129], v[162:165], v[178:181], v[126:129]
	v_mfma_f32_16x16x32_bf16 v[118:121], v[170:173], v[178:181], v[118:121]
	v_mfma_f32_16x16x32_bf16 v[110:113], v[162:165], v[186:189], v[110:113]
	v_mfma_f32_16x16x32_bf16 v[102:105], v[170:173], v[186:189], v[102:105]
	v_mfma_f32_16x16x32_bf16 v[94:97], v[162:165], v[212:215], v[94:97]
	v_mfma_f32_16x16x32_bf16 v[86:89], v[170:173], v[212:215], v[86:89]
	v_mfma_f32_16x16x32_bf16 v[78:81], v[162:165], v[220:223], v[78:81]
	v_mfma_f32_16x16x32_bf16 v[70:73], v[170:173], v[220:223], v[70:73]
	v_mfma_f32_16x16x32_bf16 v[126:129], v[166:169], v[182:185], v[126:129]
	v_mfma_f32_16x16x32_bf16 v[118:121], v[174:177], v[182:185], v[118:121]
	v_mfma_f32_16x16x32_bf16 v[110:113], v[166:169], v[208:211], v[110:113]
	v_mfma_f32_16x16x32_bf16 v[102:105], v[174:177], v[208:211], v[102:105]
	v_mfma_f32_16x16x32_bf16 v[94:97], v[166:169], v[216:219], v[94:97]
	v_mfma_f32_16x16x32_bf16 v[86:89], v[174:177], v[216:219], v[86:89]
	v_mfma_f32_16x16x32_bf16 v[78:81], v[166:169], v[224:227], v[78:81]
	v_mfma_f32_16x16x32_bf16 v[70:73], v[174:177], v[224:227], v[70:73]
	s_barrier
	s_add_i32 s9, s9, s12
	s_mov_b32 m0, s9
	s_add_u32 s20, s38, 0x80
	s_addc_u32 s21, s39, 0
	ds_read_b128 v[178:181], v161 offset:49152
	ds_read_b128 v[182:185], v161 offset:50176
	ds_read_b128 v[186:189], v161 offset:51200
	ds_read_b128 v[208:211], v161 offset:52224
	global_load_lds_dwordx4 v0, s[20:21]
	s_add_i32 m0, s9, 0x2000
	s_add_i32 s9, s74, s12
	global_load_lds_dwordx4 v130, s[20:21]
	s_add_u32 s20, s20, 0x40000
	s_addc_u32 s21, s21, 0
	s_mov_b32 m0, s9
	ds_read_b128 v[212:215], v161 offset:53248
	global_load_lds_dwordx4 v0, s[20:21]
	s_add_i32 m0, s9, 0x2000
	ds_read_b128 v[216:219], v161 offset:54272
	global_load_lds_dwordx4 v130, s[20:21]
	s_add_u32 s20, s84, 0x80
	s_addc_u32 s21, s85, 0
	s_mov_b32 m0, s78
	ds_read_b128 v[220:223], v161 offset:55296
	global_load_lds_dwordx4 v134, s[20:21]
	s_mov_b32 m0, s80
	ds_read_b128 v[224:227], v161 offset:56320
	global_load_lds_dwordx4 v132, s[20:21]
	s_waitcnt vmcnt(8)
	s_waitcnt lgkmcnt(0)
	s_barrier
	v_mfma_f32_16x16x32_bf16 v[58:61], v[142:145], v[178:181], v[58:61]
	v_mfma_f32_16x16x32_bf16 v[50:53], v[150:153], v[178:181], v[50:53]
	v_mfma_f32_16x16x32_bf16 v[42:45], v[142:145], v[186:189], v[42:45]
	v_mfma_f32_16x16x32_bf16 v[34:37], v[150:153], v[186:189], v[34:37]
	v_mfma_f32_16x16x32_bf16 v[26:29], v[142:145], v[212:215], v[26:29]
	v_mfma_f32_16x16x32_bf16 v[18:21], v[150:153], v[212:215], v[18:21]
	v_mfma_f32_16x16x32_bf16 v[10:13], v[142:145], v[220:223], v[10:13]
	v_mfma_f32_16x16x32_bf16 v[2:5], v[150:153], v[220:223], v[2:5]
	v_mfma_f32_16x16x32_bf16 v[58:61], v[146:149], v[182:185], v[58:61]
	v_mfma_f32_16x16x32_bf16 v[50:53], v[154:157], v[182:185], v[50:53]
	v_mfma_f32_16x16x32_bf16 v[42:45], v[146:149], v[208:211], v[42:45]
	v_mfma_f32_16x16x32_bf16 v[34:37], v[154:157], v[208:211], v[34:37]
	v_mfma_f32_16x16x32_bf16 v[26:29], v[146:149], v[216:219], v[26:29]
	v_mfma_f32_16x16x32_bf16 v[18:21], v[154:157], v[216:219], v[18:21]
	v_mfma_f32_16x16x32_bf16 v[10:13], v[146:149], v[224:227], v[10:13]
	v_mfma_f32_16x16x32_bf16 v[2:5], v[154:157], v[224:227], v[2:5]
	v_mfma_f32_16x16x32_bf16 v[62:65], v[162:165], v[178:181], v[62:65]
	v_mfma_f32_16x16x32_bf16 v[54:57], v[170:173], v[178:181], v[54:57]
	v_mfma_f32_16x16x32_bf16 v[46:49], v[162:165], v[186:189], v[46:49]
	v_mfma_f32_16x16x32_bf16 v[38:41], v[170:173], v[186:189], v[38:41]
	v_mfma_f32_16x16x32_bf16 v[30:33], v[162:165], v[212:215], v[30:33]
	v_mfma_f32_16x16x32_bf16 v[22:25], v[170:173], v[212:215], v[22:25]
	v_mfma_f32_16x16x32_bf16 v[14:17], v[162:165], v[220:223], v[14:17]
	v_mfma_f32_16x16x32_bf16 v[6:9], v[170:173], v[220:223], v[6:9]
	v_mfma_f32_16x16x32_bf16 v[62:65], v[166:169], v[182:185], v[62:65]
	v_mfma_f32_16x16x32_bf16 v[54:57], v[174:177], v[182:185], v[54:57]
	v_mfma_f32_16x16x32_bf16 v[46:49], v[166:169], v[208:211], v[46:49]
	v_mfma_f32_16x16x32_bf16 v[38:41], v[174:177], v[208:211], v[38:41]
	v_mfma_f32_16x16x32_bf16 v[30:33], v[166:169], v[216:219], v[30:33]
	v_mfma_f32_16x16x32_bf16 v[22:25], v[174:177], v[216:219], v[22:25]
	v_mfma_f32_16x16x32_bf16 v[14:17], v[166:169], v[224:227], v[14:17]
	v_mfma_f32_16x16x32_bf16 v[6:9], v[174:177], v[224:227], v[6:9]
	s_barrier
	s_add_u32 s0, s0, 0x100
	s_addc_u32 s1, s1, 0
	s_add_u32 vcc_hi, vcc_hi, 0x100
	s_addc_u32 s8, s8, 0
	s_cmp_ge_i32 s96, s57
	s_mov_b32 s9, s96
	s_cbranch_scc0 .LBB0_222
	s_setprio 0
	v_readlane_b32 s96, v250, 43
	s_mov_b64 s[74:75], s[22:23]

; #define PG8_STAGE(bufoff, gbase, voff) do { _Pragma("unroll") for (int _i = 0; _i < 2; ++_i) \
;         __builtin_amdgcn_global_load_lds((const unsigned*)((const char*)(gbase) + (voff)[_i]), (LAS unsigned*)(lds + (bufoff) + ldsw + _i * 8192), 16, 0, 0); } while (0)
; #define PG8_LDA(dst, b, h) do { _Pragma("unroll") for (int m = 0; m < 4; ++m) _Pragma("unroll") for (int k = 0; k < 2; ++k) dst[m][k] = *(const LAS bf16x8*)(lds + PG8_SA(b, h) + aoff + m * 2048 + k * 1024); } while (0)
; #define PG8_LDB(dst, b, h) do { _Pragma("unroll") for (int n = 0; n < 2; ++n) _Pragma("unroll") for (int k = 0; k < 2; ++k) dst[n][k] = *(const LAS bf16x8*)(lds + PG8_SB(b, h) + boff + n * 2048 + k * 1024); } while (0)
; #define PG8_MMA(ai, bj, At, Bt) do { __builtin_amdgcn_s_setprio(1); _Pragma("unroll") for (int m = 0; m < 4; ++m) _Pragma("unroll") for (int n = 0; n < 2; ++n) _Pragma("unroll") for (int k = 0; k < 2; ++k) \
;         acc[ai][bj][m][n] = __builtin_amdgcn_mfma_f32_16x16x32_bf16(Bt[n][k], At[m][k], acc[ai][bj][m][n], 0, 0, 0); __builtin_amdgcn_s_setprio(0); } while (0)
; #define PG8_WAIT_V(n) asm volatile("s_waitcnt vmcnt(" #n ")" ::: "memory")
; #define PG8_BAR __builtin_amdgcn_s_barrier()
; template <class Epi, class Sched>
; __device__ __forceinline__ void gemm_phase(LAS unsigned char* lds, const Gemm g, const Sched& S, const Epi& E) {
;     ...
;         for (int t = 0; t < nt; t += 2) {
;             const bool last = (t == nt - 2);
;             const char* a1 = cA + (size_t)(t + 1) * kstep;
;             const char* a2 = last ? nA : cA + (size_t)(t + 2) * kstep; const char* b2 = last ? nB : cB + (size_t)(t + 2) * kstep;
;             const char* a3 = a2 + kstep; const char* b3 = b2 + kstep;
;             if constexpr (Epi::MIDK) { if (t == (nt >> 1)) { int fr_ = fr, fq_ = fq; asm volatile("" : "+v"(fr_), "+v"(fq_)); E.mid(acc, cur, wr, wc, fr_, fq_); } }
;             PG8_LDB(B0, 0, 0); PG8_LDB(B1, 0, 1); PG8_SCHED; PG8_LDA(At, 0, 0); PG8_STAGE(PG8_SA(1, 1), a1 + hsA, voffA);
;             PG8_WAIT_V(8); PG8_WAIT_L(0); PG8_BAR; PG8_MMA(0, 0, At, B0); PG8_MMA(0, 1, At, B1); PG8_BAR; PG8_SCHED;
;             PG8_LDA(At, 0, 1); PG8_STAGE(PG8_SB(0, 0), b2, voffB); PG8_STAGE(PG8_SB(0, 1), b2 + hsB, voffB); PG8_STAGE(PG8_SA(0, 0), a2, voffA);
;             PG8_WAIT_V(8); PG8_WAIT_L(0); PG8_BAR; PG8_MMA(1, 0, At, B0); PG8_MMA(1, 1, At, B1); PG8_BAR; PG8_SCHED;
.Lnp_298:
.LBB0_298:
	s_add_i32 s96, s38, 2
	s_add_u32 s20, s8, 0x100
	s_addc_u32 s21, s9, 0
	s_add_i32 s74, 0, 0x10000
	s_cmp_eq_u32 s26, s38
	s_cselect_b32 s41, s43, s21
	s_cselect_b32 s40, s73, s20
	s_cselect_b32 s39, s82, s85
	s_cselect_b32 s38, s83, s84
	s_add_i32 s75, 0, 0x14000
	v_add_u32_e32 v152, s74, v206
	v_add_u32_e32 v168, s75, v206
	ds_read_b128 v[140:143], v152
	ds_read_b128 v[144:147], v152 offset:1024
	ds_read_b128 v[148:151], v152 offset:2048
	ds_read_b128 v[152:155], v152 offset:3072
	ds_read_b128 v[156:159], v168
	ds_read_b128 v[160:163], v168 offset:1024
	ds_read_b128 v[164:167], v168 offset:2048
	ds_read_b128 v[168:171], v168 offset:3072
	v_lshl_add_u64 v[208:209], s[8:9], 0, v[136:137]
	s_add_i32 m0, s30, 0xc000
	ds_read_b128 v[172:175], v210
	ds_read_b128 v[176:179], v210 offset:1024
	ds_read_b128 v[180:183], v210 offset:2048
	ds_read_b128 v[184:187], v210 offset:3072
	ds_read_b128 v[188:191], v210 offset:4096
	ds_read_b128 v[212:215], v210 offset:5120
	ds_read_b128 v[216:219], v210 offset:6144
	global_load_lds_dwordx4 v[208:209], off
	v_lshl_add_u64 v[208:209], s[8:9], 0, v[138:139]
	s_add_i32 m0, s30, 0xe000
	ds_read_b128 v[220:223], v210 offset:7168
	global_load_lds_dwordx4 v[208:209], off
	s_waitcnt vmcnt(8)
	s_waitcnt lgkmcnt(0)
	s_barrier
	v_mfma_f32_16x16x32_bf16 v[126:129], v[140:143], v[172:175], v[126:129]
	v_mfma_f32_16x16x32_bf16 v[122:125], v[148:151], v[172:175], v[122:125]
	v_mfma_f32_16x16x32_bf16 v[118:121], v[140:143], v[180:183], v[118:121]
	v_mfma_f32_16x16x32_bf16 v[114:117], v[148:151], v[180:183], v[114:117]
	v_mfma_f32_16x16x32_bf16 v[106:109], v[140:143], v[188:191], v[106:109]
	v_mfma_f32_16x16x32_bf16 v[98:101], v[148:151], v[188:191], v[98:101]
	v_mfma_f32_16x16x32_bf16 v[90:93], v[140:143], v[216:219], v[90:93]
	v_mfma_f32_16x16x32_bf16 v[82:85], v[148:151], v[216:219], v[82:85]
	v_mfma_f32_16x16x32_bf16 v[126:129], v[144:147], v[176:179], v[126:129]
	v_mfma_f32_16x16x32_bf16 v[122:125], v[152:155], v[176:179], v[122:125]
	v_mfma_f32_16x16x32_bf16 v[118:121], v[144:147], v[184:187], v[118:121]
	v_mfma_f32_16x16x32_bf16 v[114:117], v[152:155], v[184:187], v[114:117]
	v_mfma_f32_16x16x32_bf16 v[106:109], v[144:147], v[212:215], v[106:109]
	v_mfma_f32_16x16x32_bf16 v[98:101], v[152:155], v[212:215], v[98:101]
	v_mfma_f32_16x16x32_bf16 v[90:93], v[144:147], v[220:223], v[90:93]
	v_mfma_f32_16x16x32_bf16 v[82:85], v[152:155], v[220:223], v[82:85]
	v_mfma_f32_16x16x32_bf16 v[110:113], v[156:159], v[172:175], v[110:113]
	v_mfma_f32_16x16x32_bf16 v[102:105], v[164:167], v[172:175], v[102:105]
	v_mfma_f32_16x16x32_bf16 v[94:97], v[156:159], v[180:183], v[94:97]
	v_mfma_f32_16x16x32_bf16 v[86:89], v[164:167], v[180:183], v[86:89]
	v_mfma_f32_16x16x32_bf16 v[78:81], v[156:159], v[188:191], v[78:81]
	v_mfma_f32_16x16x32_bf16 v[74:77], v[164:167], v[188:191], v[74:77]
	v_mfma_f32_16x16x32_bf16 v[70:73], v[156:159], v[216:219], v[70:73]
	v_mfma_f32_16x16x32_bf16 v[66:69], v[164:167], v[216:219], v[66:69]
	v_mfma_f32_16x16x32_bf16 v[110:113], v[160:163], v[176:179], v[110:113]
	v_mfma_f32_16x16x32_bf16 v[102:105], v[168:171], v[176:179], v[102:105]
	v_mfma_f32_16x16x32_bf16 v[94:97], v[160:163], v[184:187], v[94:97]
	v_mfma_f32_16x16x32_bf16 v[86:89], v[168:171], v[184:187], v[86:89]
	v_mfma_f32_16x16x32_bf16 v[78:81], v[160:163], v[212:215], v[78:81]
	v_mfma_f32_16x16x32_bf16 v[74:77], v[168:171], v[212:215], v[74:77]
	v_mfma_f32_16x16x32_bf16 v[70:73], v[160:163], v[220:223], v[70:73]
	v_mfma_f32_16x16x32_bf16 v[66:69], v[168:171], v[220:223], v[66:69]
	s_barrier
	s_add_i32 s8, s74, s24
	v_lshl_add_u64 v[208:209], s[38:39], 0, v[0:1]
	s_mov_b32 m0, s8
	ds_read_b128 v[172:175], v210 offset:16384
	ds_read_b128 v[176:179], v210 offset:17408
	ds_read_b128 v[180:183], v210 offset:18432
	ds_read_b128 v[184:187], v210 offset:19456
	ds_read_b128 v[188:191], v210 offset:20480
	global_load_lds_dwordx4 v[208:209], off
	s_add_i32 m0, s8, 0x2000
	s_add_u32 s8, s38, 0xb0000
	v_lshl_add_u64 v[224:225], s[38:39], 0, v[130:131]
	s_addc_u32 s9, s39, 0
	s_add_i32 s74, s75, s24
	global_load_lds_dwordx4 v[224:225], off
	v_lshl_add_u64 v[226:227], s[8:9], 0, v[0:1]
	s_mov_b32 m0, s74
	v_lshl_add_u64 v[228:229], s[40:41], 0, v[132:133]
	global_load_lds_dwordx4 v[226:227], off
	v_lshl_add_u64 v[226:227], s[8:9], 0, v[130:131]
	s_add_i32 m0, s74, 0x2000
	ds_read_b128 v[212:215], v210 offset:21504
	global_load_lds_dwordx4 v[226:227], off
	v_lshl_add_u64 v[226:227], s[40:41], 0, v[134:135]
	s_mov_b32 m0, s30
	ds_read_b128 v[216:219], v210 offset:22528
	global_load_lds_dwordx4 v[226:227], off
	s_mov_b32 m0, s52
	ds_read_b128 v[220:223], v210 offset:23552
	global_load_lds_dwordx4 v[228:229], off
	s_waitcnt vmcnt(8)
	s_waitcnt lgkmcnt(0)
	s_barrier
; #define PG8_STAGE(bufoff, gbase, voff) do { _Pragma("unroll") for (int _i = 0; _i < 2; ++_i) \
;         __builtin_amdgcn_global_load_lds((const unsigned*)((const char*)(gbase) + (voff)[_i]), (LAS unsigned*)(lds + (bufoff) + ldsw + _i * 8192), 16, 0, 0); } while (0)
; #define PG8_LDA(dst, b, h) do { _Pragma("unroll") for (int m = 0; m < 4; ++m) _Pragma("unroll") for (int k = 0; k < 2; ++k) dst[m][k] = *(const LAS bf16x8*)(lds + PG8_SA(b, h) + aoff + m * 2048 + k * 1024); } while (0)
; #define PG8_LDB(dst, b, h) do { _Pragma("unroll") for (int n = 0; n < 2; ++n) _Pragma("unroll") for (int k = 0; k < 2; ++k) dst[n][k] = *(const LAS bf16x8*)(lds + PG8_SB(b, h) + boff + n * 2048 + k * 1024); } while (0)
; #define PG8_MMA(ai, bj, At, Bt) do { __builtin_amdgcn_s_setprio(1); _Pragma("unroll") for (int m = 0; m < 4; ++m) _Pragma("unroll") for (int n = 0; n < 2; ++n) _Pragma("unroll") for (int k = 0; k < 2; ++k) \
;         acc[ai][bj][m][n] = __builtin_amdgcn_mfma_f32_16x16x32_bf16(Bt[n][k], At[m][k], acc[ai][bj][m][n], 0, 0, 0); __builtin_amdgcn_s_setprio(0); } while (0)
; #define PG8_WAIT_V(n) asm volatile("s_waitcnt vmcnt(" #n ")" ::: "memory")
; #define PG8_WAIT_L(n) asm volatile("s_waitcnt lgkmcnt(" #n ")" ::: "memory")
; #define PG8_BAR __builtin_amdgcn_s_barrier()
; #define PG8_SCHED __builtin_amdgcn_sched_barrier(0)
; template <class Epi, class Sched>
; __device__ __forceinline__ void gemm_phase(LAS unsigned char* lds, const Gemm g, const Sched& S, const Epi& E) {
;     ...
;             PG8_LDA(At, 0, 1); PG8_STAGE(PG8_SB(0, 0), b2, voffB); PG8_STAGE(PG8_SB(0, 1), b2 + hsB, voffB); PG8_STAGE(PG8_SA(0, 0), a2, voffA);
;             PG8_WAIT_V(8); PG8_WAIT_L(0); PG8_BAR; PG8_MMA(1, 0, At, B0); PG8_MMA(1, 1, At, B1); PG8_BAR; PG8_SCHED;
;             PG8_LDB(B0, 1, 0); PG8_LDB(B1, 1, 1); PG8_SCHED; PG8_LDA(At, 1, 0); PG8_STAGE(PG8_SA(0, 1), a2 + hsA, voffA);
;             PG8_WAIT_V(8); PG8_WAIT_L(0); PG8_BAR; PG8_MMA(0, 0, At, B0); PG8_MMA(0, 1, At, B1); PG8_BAR; PG8_SCHED;
	v_mfma_f32_16x16x32_bf16 v[62:65], v[140:143], v[172:175], v[62:65]
	v_mfma_f32_16x16x32_bf16 v[58:61], v[148:151], v[172:175], v[58:61]
	v_mfma_f32_16x16x32_bf16 v[54:57], v[140:143], v[180:183], v[54:57]
	v_mfma_f32_16x16x32_bf16 v[50:53], v[148:151], v[180:183], v[50:53]
	v_mfma_f32_16x16x32_bf16 v[42:45], v[140:143], v[188:191], v[42:45]
	v_mfma_f32_16x16x32_bf16 v[34:37], v[148:151], v[188:191], v[34:37]
	v_mfma_f32_16x16x32_bf16 v[26:29], v[140:143], v[216:219], v[26:29]
	v_mfma_f32_16x16x32_bf16 v[18:21], v[148:151], v[216:219], v[18:21]
	v_mfma_f32_16x16x32_bf16 v[62:65], v[144:147], v[176:179], v[62:65]
	v_mfma_f32_16x16x32_bf16 v[58:61], v[152:155], v[176:179], v[58:61]
	v_mfma_f32_16x16x32_bf16 v[54:57], v[144:147], v[184:187], v[54:57]
	v_mfma_f32_16x16x32_bf16 v[50:53], v[152:155], v[184:187], v[50:53]
	v_mfma_f32_16x16x32_bf16 v[42:45], v[144:147], v[212:215], v[42:45]
	v_mfma_f32_16x16x32_bf16 v[34:37], v[152:155], v[212:215], v[34:37]
	v_mfma_f32_16x16x32_bf16 v[26:29], v[144:147], v[220:223], v[26:29]
	v_mfma_f32_16x16x32_bf16 v[18:21], v[152:155], v[220:223], v[18:21]
	v_mfma_f32_16x16x32_bf16 v[46:49], v[156:159], v[172:175], v[46:49]
	v_mfma_f32_16x16x32_bf16 v[38:41], v[164:167], v[172:175], v[38:41]
	v_mfma_f32_16x16x32_bf16 v[30:33], v[156:159], v[180:183], v[30:33]
	v_mfma_f32_16x16x32_bf16 v[22:25], v[164:167], v[180:183], v[22:25]
	v_mfma_f32_16x16x32_bf16 v[14:17], v[156:159], v[188:191], v[14:17]
	v_mfma_f32_16x16x32_bf16 v[10:13], v[164:167], v[188:191], v[10:13]
	v_mfma_f32_16x16x32_bf16 v[6:9], v[156:159], v[216:219], v[6:9]
	v_mfma_f32_16x16x32_bf16 v[2:5], v[164:167], v[216:219], v[2:5]
	v_mfma_f32_16x16x32_bf16 v[46:49], v[160:163], v[176:179], v[46:49]
	v_mfma_f32_16x16x32_bf16 v[38:41], v[168:171], v[176:179], v[38:41]
	v_mfma_f32_16x16x32_bf16 v[30:33], v[160:163], v[184:187], v[30:33]
	v_mfma_f32_16x16x32_bf16 v[22:25], v[168:171], v[184:187], v[22:25]
	v_mfma_f32_16x16x32_bf16 v[14:17], v[160:163], v[212:215], v[14:17]
	v_mfma_f32_16x16x32_bf16 v[10:13], v[168:171], v[212:215], v[10:13]
	v_mfma_f32_16x16x32_bf16 v[6:9], v[160:163], v[220:223], v[6:9]
	v_mfma_f32_16x16x32_bf16 v[2:5], v[168:171], v[220:223], v[2:5]
	s_barrier
	s_add_i32 s74, 0, 0x18000
	s_add_i32 s75, 0, 0x1c000
	v_add_u32_e32 v152, s74, v206
	v_add_u32_e32 v168, s75, v206
	ds_read_b128 v[140:143], v152
	ds_read_b128 v[144:147], v152 offset:1024
	ds_read_b128 v[148:151], v152 offset:2048
	ds_read_b128 v[152:155], v152 offset:3072
	ds_read_b128 v[156:159], v168
	ds_read_b128 v[160:163], v168 offset:1024
	ds_read_b128 v[164:167], v168 offset:2048
	ds_read_b128 v[168:171], v168 offset:3072
	s_add_u32 s8, s40, 0xb0000
	s_addc_u32 s9, s41, 0
	s_mov_b32 m0, s64
	v_lshl_add_u64 v[230:231], s[8:9], 0, v[134:135]
	ds_read_b128 v[172:175], v210 offset:32768
	ds_read_b128 v[176:179], v210 offset:33792
	ds_read_b128 v[180:183], v210 offset:34816
	ds_read_b128 v[184:187], v210 offset:35840
	ds_read_b128 v[188:191], v210 offset:36864
	ds_read_b128 v[212:215], v210 offset:37888
	ds_read_b128 v[216:219], v210 offset:38912
	global_load_lds_dwordx4 v[230:231], off
	v_lshl_add_u64 v[230:231], s[8:9], 0, v[132:133]
	s_mov_b32 m0, s78
	ds_read_b128 v[220:223], v210 offset:39936
	global_load_lds_dwordx4 v[230:231], off
	s_waitcnt vmcnt(8)
	s_waitcnt lgkmcnt(0)
	s_barrier
	v_mfma_f32_16x16x32_bf16 v[126:129], v[140:143], v[172:175], v[126:129]
	v_mfma_f32_16x16x32_bf16 v[122:125], v[148:151], v[172:175], v[122:125]
	v_mfma_f32_16x16x32_bf16 v[118:121], v[140:143], v[180:183], v[118:121]
	v_mfma_f32_16x16x32_bf16 v[114:117], v[148:151], v[180:183], v[114:117]
	v_mfma_f32_16x16x32_bf16 v[106:109], v[140:143], v[188:191], v[106:109]
	v_mfma_f32_16x16x32_bf16 v[98:101], v[148:151], v[188:191], v[98:101]
	v_mfma_f32_16x16x32_bf16 v[90:93], v[140:143], v[216:219], v[90:93]
	v_mfma_f32_16x16x32_bf16 v[82:85], v[148:151], v[216:219], v[82:85]
	v_mfma_f32_16x16x32_bf16 v[126:129], v[144:147], v[176:179], v[126:129]
	v_mfma_f32_16x16x32_bf16 v[122:125], v[152:155], v[176:179], v[122:125]
	v_mfma_f32_16x16x32_bf16 v[118:121], v[144:147], v[184:187], v[118:121]
	v_mfma_f32_16x16x32_bf16 v[114:117], v[152:155], v[184:187], v[114:117]
	v_mfma_f32_16x16x32_bf16 v[106:109], v[144:147], v[212:215], v[106:109]
	v_mfma_f32_16x16x32_bf16 v[98:101], v[152:155], v[212:215], v[98:101]
	v_mfma_f32_16x16x32_bf16 v[90:93], v[144:147], v[220:223], v[90:93]
	v_mfma_f32_16x16x32_bf16 v[82:85], v[152:155], v[220:223], v[82:85]
	v_mfma_f32_16x16x32_bf16 v[110:113], v[156:159], v[172:175], v[110:113]
	v_mfma_f32_16x16x32_bf16 v[102:105], v[164:167], v[172:175], v[102:105]
	v_mfma_f32_16x16x32_bf16 v[94:97], v[156:159], v[180:183], v[94:97]
	v_mfma_f32_16x16x32_bf16 v[86:89], v[164:167], v[180:183], v[86:89]
	v_mfma_f32_16x16x32_bf16 v[78:81], v[156:159], v[188:191], v[78:81]
	v_mfma_f32_16x16x32_bf16 v[74:77], v[164:167], v[188:191], v[74:77]
	v_mfma_f32_16x16x32_bf16 v[70:73], v[156:159], v[216:219], v[70:73]
	v_mfma_f32_16x16x32_bf16 v[66:69], v[164:167], v[216:219], v[66:69]
	v_mfma_f32_16x16x32_bf16 v[110:113], v[160:163], v[176:179], v[110:113]
	v_mfma_f32_16x16x32_bf16 v[102:105], v[168:171], v[176:179], v[102:105]
	v_mfma_f32_16x16x32_bf16 v[94:97], v[160:163], v[184:187], v[94:97]
	v_mfma_f32_16x16x32_bf16 v[86:89], v[168:171], v[184:187], v[86:89]
	v_mfma_f32_16x16x32_bf16 v[78:81], v[160:163], v[212:215], v[78:81]
	v_mfma_f32_16x16x32_bf16 v[74:77], v[168:171], v[212:215], v[74:77]
	v_mfma_f32_16x16x32_bf16 v[70:73], v[160:163], v[220:223], v[70:73]
	v_mfma_f32_16x16x32_bf16 v[66:69], v[168:171], v[220:223], v[66:69]
	s_barrier
; #define PG8_STAGE(bufoff, gbase, voff) do { _Pragma("unroll") for (int _i = 0; _i < 2; ++_i) \
;         __builtin_amdgcn_global_load_lds((const unsigned*)((const char*)(gbase) + (voff)[_i]), (LAS unsigned*)(lds + (bufoff) + ldsw + _i * 8192), 16, 0, 0); } while (0)
; #define PG8_LDA(dst, b, h) do { _Pragma("unroll") for (int m = 0; m < 4; ++m) _Pragma("unroll") for (int k = 0; k < 2; ++k) dst[m][k] = *(const LAS bf16x8*)(lds + PG8_SA(b, h) + aoff + m * 2048 + k * 1024); } while (0)
; #define PG8_MMA(ai, bj, At, Bt) do { __builtin_amdgcn_s_setprio(1); _Pragma("unroll") for (int m = 0; m < 4; ++m) _Pragma("unroll") for (int n = 0; n < 2; ++n) _Pragma("unroll") for (int k = 0; k < 2; ++k) \
;         acc[ai][bj][m][n] = __builtin_amdgcn_mfma_f32_16x16x32_bf16(Bt[n][k], At[m][k], acc[ai][bj][m][n], 0, 0, 0); __builtin_amdgcn_s_setprio(0); } while (0)
; #define PG8_WAIT_V(n) asm volatile("s_waitcnt vmcnt(" #n ")" ::: "memory")
; #define PG8_WAIT_L(n) asm volatile("s_waitcnt lgkmcnt(" #n ")" ::: "memory")
; #define PG8_BAR __builtin_amdgcn_s_barrier()
; #define PG8_SCHED __builtin_amdgcn_sched_barrier(0)
; template <class Epi, class Sched>
; __device__ __forceinline__ void gemm_phase(LAS unsigned char* lds, const Gemm g, const Sched& S, const Epi& E) {
;     ...
;             PG8_LDA(At, 1, 1); PG8_STAGE(PG8_SB(1, 0), b3, voffB); PG8_STAGE(PG8_SB(1, 1), b3 + hsB, voffB); PG8_STAGE(PG8_SA(1, 0), a3, voffA);
;             PG8_WAIT_V(8); PG8_WAIT_L(0); PG8_BAR; PG8_MMA(1, 0, At, B0); PG8_MMA(1, 1, At, B1); PG8_BAR; PG8_SCHED;
;         }
	s_add_i32 s8, s74, s24
	v_lshl_add_u64 v[208:209], v[208:209], 0, s[18:19]
	s_mov_b32 m0, s8
	ds_read_b128 v[172:175], v210 offset:49152
	ds_read_b128 v[176:179], v210 offset:50176
	ds_read_b128 v[180:183], v210 offset:51200
	ds_read_b128 v[184:187], v210 offset:52224
	global_load_lds_dwordx4 v[208:209], off
	s_add_i32 m0, s8, 0x2000
	s_add_u32 s8, s38, 0xb0080
	v_lshl_add_u64 v[208:209], v[224:225], 0, s[18:19]
	s_addc_u32 s9, s39, 0
	s_add_i32 s38, s75, s24
	global_load_lds_dwordx4 v[208:209], off
	v_lshl_add_u64 v[208:209], s[8:9], 0, v[0:1]
	s_mov_b32 m0, s38
	ds_read_b128 v[188:191], v210 offset:53248
	global_load_lds_dwordx4 v[208:209], off
	v_lshl_add_u64 v[208:209], s[8:9], 0, v[130:131]
	s_add_i32 m0, s38, 0x2000
	ds_read_b128 v[212:215], v210 offset:54272
	global_load_lds_dwordx4 v[208:209], off
	v_lshl_add_u64 v[208:209], v[226:227], 0, s[18:19]
	s_mov_b32 m0, s16
	ds_read_b128 v[216:219], v210 offset:55296
	global_load_lds_dwordx4 v[208:209], off
	v_lshl_add_u64 v[208:209], v[228:229], 0, s[18:19]
	s_mov_b32 m0, s7
	ds_read_b128 v[220:223], v210 offset:56320
	global_load_lds_dwordx4 v[208:209], off
	s_waitcnt vmcnt(8)
	s_waitcnt lgkmcnt(0)
	s_barrier
	v_mfma_f32_16x16x32_bf16 v[62:65], v[140:143], v[172:175], v[62:65]
	v_mfma_f32_16x16x32_bf16 v[58:61], v[148:151], v[172:175], v[58:61]
	v_mfma_f32_16x16x32_bf16 v[54:57], v[140:143], v[180:183], v[54:57]
	v_mfma_f32_16x16x32_bf16 v[50:53], v[148:151], v[180:183], v[50:53]
	v_mfma_f32_16x16x32_bf16 v[42:45], v[140:143], v[188:191], v[42:45]
	v_mfma_f32_16x16x32_bf16 v[34:37], v[148:151], v[188:191], v[34:37]
	v_mfma_f32_16x16x32_bf16 v[26:29], v[140:143], v[216:219], v[26:29]
	v_mfma_f32_16x16x32_bf16 v[18:21], v[148:151], v[216:219], v[18:21]
	v_mfma_f32_16x16x32_bf16 v[62:65], v[144:147], v[176:179], v[62:65]
	v_mfma_f32_16x16x32_bf16 v[58:61], v[152:155], v[176:179], v[58:61]
	v_mfma_f32_16x16x32_bf16 v[54:57], v[144:147], v[184:187], v[54:57]
	v_mfma_f32_16x16x32_bf16 v[50:53], v[152:155], v[184:187], v[50:53]
	v_mfma_f32_16x16x32_bf16 v[42:45], v[144:147], v[212:215], v[42:45]
	v_mfma_f32_16x16x32_bf16 v[34:37], v[152:155], v[212:215], v[34:37]
	v_mfma_f32_16x16x32_bf16 v[26:29], v[144:147], v[220:223], v[26:29]
	v_mfma_f32_16x16x32_bf16 v[18:21], v[152:155], v[220:223], v[18:21]
	v_mfma_f32_16x16x32_bf16 v[46:49], v[156:159], v[172:175], v[46:49]
	v_mfma_f32_16x16x32_bf16 v[38:41], v[164:167], v[172:175], v[38:41]
	v_mfma_f32_16x16x32_bf16 v[30:33], v[156:159], v[180:183], v[30:33]
	v_mfma_f32_16x16x32_bf16 v[22:25], v[164:167], v[180:183], v[22:25]
	v_mfma_f32_16x16x32_bf16 v[14:17], v[156:159], v[188:191], v[14:17]
	v_mfma_f32_16x16x32_bf16 v[10:13], v[164:167], v[188:191], v[10:13]
	v_mfma_f32_16x16x32_bf16 v[6:9], v[156:159], v[216:219], v[6:9]
	v_mfma_f32_16x16x32_bf16 v[2:5], v[164:167], v[216:219], v[2:5]
	v_mfma_f32_16x16x32_bf16 v[46:49], v[160:163], v[176:179], v[46:49]
	v_mfma_f32_16x16x32_bf16 v[38:41], v[168:171], v[176:179], v[38:41]
	v_mfma_f32_16x16x32_bf16 v[30:33], v[160:163], v[184:187], v[30:33]
	v_mfma_f32_16x16x32_bf16 v[22:25], v[168:171], v[184:187], v[22:25]
	v_mfma_f32_16x16x32_bf16 v[14:17], v[160:163], v[212:215], v[14:17]
	v_mfma_f32_16x16x32_bf16 v[10:13], v[168:171], v[212:215], v[10:13]
	v_mfma_f32_16x16x32_bf16 v[6:9], v[160:163], v[220:223], v[6:9]
	v_mfma_f32_16x16x32_bf16 v[2:5], v[168:171], v[220:223], v[2:5]
	s_barrier
	s_add_u32 s84, s84, 0x100
	s_addc_u32 s85, s85, 0
	s_cmp_ge_i32 s96, s12
	s_mov_b64 s[8:9], s[20:21]
	s_mov_b32 s38, s96
	s_cbranch_scc0 .LBB0_298
;     __device__ __forceinline__ void operator()(const Acc& acc, const Unit& u, int wr, int wc, int fr, int fq) const {
;     ...
;         for (int ai = 0; ai < 2; ++ai) { u32x4 bv[4][2];
; #pragma unroll
;             for (int m = 0; m < 4; ++m)
; #pragma unroll
;                 for (int bj = 0; bj < 2; ++bj) bv[m][bj] = *(const u32x4*)(xb + (size_t)(row0 + ai * 128 + m * 16) * DM + c8 + bj * 128);
; #pragma unroll
;             for (int m = 0; m < 4; ++m) { const size_t row = (size_t)(row0 + ai * 128 + m * 16); float s = 0.f;
; #pragma unroll
;                 for (int bj = 0; bj < 2; ++bj) { const size_t off = row * DM + c8 + bj * 128; f32x4 b0, b1; unpack8(bv[m][bj], b0, b1);
;                     const f32x4 o0 = b0 + acc[ai][bj][m][0] * scale, o1 = b1 + acc[ai][bj][m][1] * scale;
	s_setprio 0
	v_pk_mul_f32 v[182:183], v[128:129], 0.5 op_sel_hi:[1,0]
	v_pk_mul_f32 v[184:185], v[126:127], 0.5 op_sel_hi:[1,0]
	v_pk_mul_f32 v[186:187], v[124:125], 0.5 op_sel_hi:[1,0]
	v_pk_mul_f32 v[188:189], v[122:123], 0.5 op_sel_hi:[1,0]
	v_pk_mul_f32 v[180:181], v[112:113], 0.5 op_sel_hi:[1,0]
	v_pk_mul_f32 v[178:179], v[110:111], 0.5 op_sel_hi:[1,0]
	v_pk_mul_f32 v[176:177], v[104:105], 0.5 op_sel_hi:[1,0]
	v_pk_mul_f32 v[174:175], v[102:103], 0.5 op_sel_hi:[1,0]
	v_pk_mul_f32 v[170:171], v[120:121], 0.5 op_sel_hi:[1,0]
	v_pk_mul_f32 v[168:169], v[118:119], 0.5 op_sel_hi:[1,0]
	v_pk_mul_f32 v[166:167], v[116:117], 0.5 op_sel_hi:[1,0]
	v_pk_mul_f32 v[164:165], v[114:115], 0.5 op_sel_hi:[1,0]
	v_pk_mul_f32 v[162:163], v[96:97], 0.5 op_sel_hi:[1,0]
	v_pk_mul_f32 v[160:161], v[94:95], 0.5 op_sel_hi:[1,0]
	v_pk_mul_f32 v[158:159], v[88:89], 0.5 op_sel_hi:[1,0]
	v_pk_mul_f32 v[156:157], v[86:87], 0.5 op_sel_hi:[1,0]
	v_pk_mul_f32 v[150:151], v[108:109], 0.5 op_sel_hi:[1,0]
	v_pk_mul_f32 v[148:149], v[106:107], 0.5 op_sel_hi:[1,0]
	v_pk_mul_f32 v[146:147], v[100:101], 0.5 op_sel_hi:[1,0]
	v_pk_mul_f32 v[144:145], v[98:99], 0.5 op_sel_hi:[1,0]
	v_pk_mul_f32 v[142:143], v[80:81], 0.5 op_sel_hi:[1,0]
	v_pk_mul_f32 v[140:141], v[78:79], 0.5 op_sel_hi:[1,0]
	v_pk_mul_f32 v[128:129], v[76:77], 0.5 op_sel_hi:[1,0]
	v_pk_mul_f32 v[126:127], v[74:75], 0.5 op_sel_hi:[1,0]
	v_pk_mul_f32 v[124:125], v[92:93], 0.5 op_sel_hi:[1,0]
	v_pk_mul_f32 v[122:123], v[90:91], 0.5 op_sel_hi:[1,0]
	v_pk_mul_f32 v[120:121], v[84:85], 0.5 op_sel_hi:[1,0]
	v_pk_mul_f32 v[118:119], v[82:83], 0.5 op_sel_hi:[1,0]
	v_pk_mul_f32 v[116:117], v[72:73], 0.5 op_sel_hi:[1,0]
	v_pk_mul_f32 v[114:115], v[70:71], 0.5 op_sel_hi:[1,0]
	v_pk_mul_f32 v[112:113], v[68:69], 0.5 op_sel_hi:[1,0]
	v_pk_mul_f32 v[110:111], v[66:67], 0.5 op_sel_hi:[1,0]
	v_pk_mul_f32 v[102:103], v[64:65], 0.5 op_sel_hi:[1,0]
	v_pk_mul_f32 v[104:105], v[62:63], 0.5 op_sel_hi:[1,0]
	v_pk_mul_f32 v[106:107], v[60:61], 0.5 op_sel_hi:[1,0]
	v_pk_mul_f32 v[108:109], v[58:59], 0.5 op_sel_hi:[1,0]
	v_pk_mul_f32 v[100:101], v[48:49], 0.5 op_sel_hi:[1,0]
	v_pk_mul_f32 v[98:99], v[46:47], 0.5 op_sel_hi:[1,0]
	v_pk_mul_f32 v[96:97], v[40:41], 0.5 op_sel_hi:[1,0]
	v_pk_mul_f32 v[94:95], v[38:39], 0.5 op_sel_hi:[1,0]
	v_pk_mul_f32 v[92:93], v[56:57], 0.5 op_sel_hi:[1,0]
	v_pk_mul_f32 v[90:91], v[54:55], 0.5 op_sel_hi:[1,0]
	v_pk_mul_f32 v[88:89], v[52:53], 0.5 op_sel_hi:[1,0]
	v_pk_mul_f32 v[86:87], v[50:51], 0.5 op_sel_hi:[1,0]
	v_pk_mul_f32 v[82:83], v[32:33], 0.5 op_sel_hi:[1,0]
	v_pk_mul_f32 v[80:81], v[30:31], 0.5 op_sel_hi:[1,0]
	v_pk_mul_f32 v[78:79], v[24:25], 0.5 op_sel_hi:[1,0]
	v_pk_mul_f32 v[76:77], v[22:23], 0.5 op_sel_hi:[1,0]
	v_pk_mul_f32 v[72:73], v[44:45], 0.5 op_sel_hi:[1,0]
	v_pk_mul_f32 v[70:71], v[42:43], 0.5 op_sel_hi:[1,0]
	v_pk_mul_f32 v[68:69], v[36:37], 0.5 op_sel_hi:[1,0]
	v_pk_mul_f32 v[66:67], v[34:35], 0.5 op_sel_hi:[1,0]
	v_pk_mul_f32 v[64:65], v[16:17], 0.5 op_sel_hi:[1,0]
	v_pk_mul_f32 v[62:63], v[14:15], 0.5 op_sel_hi:[1,0]
	v_pk_mul_f32 v[60:61], v[12:13], 0.5 op_sel_hi:[1,0]
	v_pk_mul_f32 v[58:59], v[10:11], 0.5 op_sel_hi:[1,0]
	v_pk_mul_f32 v[56:57], v[28:29], 0.5 op_sel_hi:[1,0]
	v_pk_mul_f32 v[54:55], v[26:27], 0.5 op_sel_hi:[1,0]
	v_pk_mul_f32 v[52:53], v[20:21], 0.5 op_sel_hi:[1,0]
	v_pk_mul_f32 v[50:51], v[18:19], 0.5 op_sel_hi:[1,0]
	v_pk_mul_f32 v[48:49], v[8:9], 0.5 op_sel_hi:[1,0]
	v_pk_mul_f32 v[46:47], v[6:7], 0.5 op_sel_hi:[1,0]
	v_pk_mul_f32 v[44:45], v[4:5], 0.5 op_sel_hi:[1,0]
	v_pk_mul_f32 v[42:43], v[2:3], 0.5 op_sel_hi:[1,0]
	v_readlane_b32 s96, v250, 43
	s_mov_b32 s73, s22
	s_mov_b32 s74, s23
	s_mov_b32 s75, vcc_lo

; #define PG8_STAGE(bufoff, gbase, voff) do { _Pragma("unroll") for (int _i = 0; _i < 2; ++_i) \
;         __builtin_amdgcn_global_load_lds((const unsigned*)((const char*)(gbase) + (voff)[_i]), (LAS unsigned*)(lds + (bufoff) + ldsw + _i * 8192), 16, 0, 0); } while (0)
; #define PG8_LDA(dst, b, h) do { _Pragma("unroll") for (int m = 0; m < 4; ++m) _Pragma("unroll") for (int k = 0; k < 2; ++k) dst[m][k] = *(const LAS bf16x8*)(lds + PG8_SA(b, h) + aoff + m * 2048 + k * 1024); } while (0)
; #define PG8_LDB(dst, b, h) do { _Pragma("unroll") for (int n = 0; n < 2; ++n) _Pragma("unroll") for (int k = 0; k < 2; ++k) dst[n][k] = *(const LAS bf16x8*)(lds + PG8_SB(b, h) + boff + n * 2048 + k * 1024); } while (0)
; #define PG8_MMA(ai, bj, At, Bt) do { __builtin_amdgcn_s_setprio(1); _Pragma("unroll") for (int m = 0; m < 4; ++m) _Pragma("unroll") for (int n = 0; n < 2; ++n) _Pragma("unroll") for (int k = 0; k < 2; ++k) \
;         acc[ai][bj][m][n] = __builtin_amdgcn_mfma_f32_16x16x32_bf16(Bt[n][k], At[m][k], acc[ai][bj][m][n], 0, 0, 0); __builtin_amdgcn_s_setprio(0); } while (0)
; #define PG8_WAIT_V(n) asm volatile("s_waitcnt vmcnt(" #n ")" ::: "memory")
; #define PG8_BAR __builtin_amdgcn_s_barrier()
; template <class Epi, class Sched>
; __device__ __forceinline__ void gemm_phase(LAS unsigned char* lds, const Gemm g, const Sched& S, const Epi& E) {
;     ...
;         for (int t = 0; t < nt; t += 2) {
;             const bool last = (t == nt - 2);
;             const char* a1 = cA + (size_t)(t + 1) * kstep;
;             const char* a2 = last ? nA : cA + (size_t)(t + 2) * kstep; const char* b2 = last ? nB : cB + (size_t)(t + 2) * kstep;
;             const char* a3 = a2 + kstep; const char* b3 = b2 + kstep;
;             if constexpr (Epi::MIDK) { if (t == (nt >> 1)) { int fr_ = fr, fq_ = fq; asm volatile("" : "+v"(fr_), "+v"(fq_)); E.mid(acc, cur, wr, wc, fr_, fq_); } }
;             PG8_LDB(B0, 0, 0); PG8_LDB(B1, 0, 1); PG8_SCHED; PG8_LDA(At, 0, 0); PG8_STAGE(PG8_SA(1, 1), a1 + hsA, voffA);
;             PG8_WAIT_V(8); PG8_WAIT_L(0); PG8_BAR; PG8_MMA(0, 0, At, B0); PG8_MMA(0, 1, At, B1); PG8_BAR; PG8_SCHED;
;             PG8_LDA(At, 0, 1); PG8_STAGE(PG8_SB(0, 0), b2, voffB); PG8_STAGE(PG8_SB(0, 1), b2 + hsB, voffB); PG8_STAGE(PG8_SA(0, 0), a2, voffA);
;             PG8_WAIT_V(8); PG8_WAIT_L(0); PG8_BAR; PG8_MMA(1, 0, At, B0); PG8_MMA(1, 1, At, B1); PG8_BAR; PG8_SCHED;
.Lnp_485:
.LBB0_485:
	s_add_i32 s85, s40, 2
	s_add_u32 s41, s38, 0xfffc0080
	s_addc_u32 s42, s39, -1
	s_add_i32 s74, 0, 0x10000
	s_cmp_eq_u32 s26, s40
	s_cselect_b32 s43, s47, s42
	s_cselect_b32 s42, s49, s41
	s_cselect_b32 s41, s73, s84
	s_cselect_b32 s40, s82, s83
	s_add_i32 s75, 0, 0x14000
	v_add_u32_e32 v154, s74, v165
	v_add_u32_e32 v162, s75, v165
	ds_read_b128 v[142:145], v154
	ds_read_b128 v[146:149], v154 offset:1024
	ds_read_b128 v[150:153], v154 offset:2048
	ds_read_b128 v[154:157], v154 offset:3072
	ds_read_b128 v[158:161], v162
	ds_read_b128 v[168:171], v162 offset:1024
	ds_read_b128 v[172:175], v162 offset:2048
	ds_read_b128 v[176:179], v162 offset:3072
	v_lshl_add_u64 v[228:229], s[38:39], 0, v[138:139]
	s_add_i32 m0, s16, 0xc000
	ds_read_b128 v[180:183], v166
	ds_read_b128 v[184:187], v166 offset:1024
	ds_read_b128 v[188:191], v166 offset:2048
	ds_read_b128 v[208:211], v166 offset:3072
	ds_read_b128 v[212:215], v166 offset:4096
	ds_read_b128 v[216:219], v166 offset:5120
	ds_read_b128 v[220:223], v166 offset:6144
	global_load_lds_dwordx4 v[228:229], off
	v_lshl_add_u64 v[228:229], s[38:39], 0, v[140:141]
	s_add_i32 m0, s16, 0xe000
	ds_read_b128 v[224:227], v166 offset:7168
	global_load_lds_dwordx4 v[228:229], off
	s_waitcnt vmcnt(8)
	s_waitcnt lgkmcnt(0)
	s_barrier
	v_mfma_f32_16x16x32_bf16 v[122:125], v[142:145], v[180:183], v[122:125]
	v_mfma_f32_16x16x32_bf16 v[114:117], v[150:153], v[180:183], v[114:117]
	v_mfma_f32_16x16x32_bf16 v[110:113], v[142:145], v[188:191], v[110:113]
	v_mfma_f32_16x16x32_bf16 v[98:101], v[150:153], v[188:191], v[98:101]
	v_mfma_f32_16x16x32_bf16 v[94:97], v[142:145], v[212:215], v[94:97]
	v_mfma_f32_16x16x32_bf16 v[82:85], v[150:153], v[212:215], v[82:85]
	v_mfma_f32_16x16x32_bf16 v[78:81], v[142:145], v[220:223], v[78:81]
	v_mfma_f32_16x16x32_bf16 v[66:69], v[150:153], v[220:223], v[66:69]
	v_mfma_f32_16x16x32_bf16 v[122:125], v[146:149], v[184:187], v[122:125]
	v_mfma_f32_16x16x32_bf16 v[114:117], v[154:157], v[184:187], v[114:117]
	v_mfma_f32_16x16x32_bf16 v[110:113], v[146:149], v[208:211], v[110:113]
	v_mfma_f32_16x16x32_bf16 v[98:101], v[154:157], v[208:211], v[98:101]
	v_mfma_f32_16x16x32_bf16 v[94:97], v[146:149], v[216:219], v[94:97]
	v_mfma_f32_16x16x32_bf16 v[82:85], v[154:157], v[216:219], v[82:85]
	v_mfma_f32_16x16x32_bf16 v[78:81], v[146:149], v[224:227], v[78:81]
	v_mfma_f32_16x16x32_bf16 v[66:69], v[154:157], v[224:227], v[66:69]
	v_mfma_f32_16x16x32_bf16 v[126:129], v[158:161], v[180:183], v[126:129]
	v_mfma_f32_16x16x32_bf16 v[118:121], v[172:175], v[180:183], v[118:121]
	v_mfma_f32_16x16x32_bf16 v[106:109], v[158:161], v[188:191], v[106:109]
	v_mfma_f32_16x16x32_bf16 v[102:105], v[172:175], v[188:191], v[102:105]
	v_mfma_f32_16x16x32_bf16 v[90:93], v[158:161], v[212:215], v[90:93]
	v_mfma_f32_16x16x32_bf16 v[86:89], v[172:175], v[212:215], v[86:89]
	v_mfma_f32_16x16x32_bf16 v[74:77], v[158:161], v[220:223], v[74:77]
	v_mfma_f32_16x16x32_bf16 v[70:73], v[172:175], v[220:223], v[70:73]
	v_mfma_f32_16x16x32_bf16 v[126:129], v[168:171], v[184:187], v[126:129]
	v_mfma_f32_16x16x32_bf16 v[118:121], v[176:179], v[184:187], v[118:121]
	v_mfma_f32_16x16x32_bf16 v[106:109], v[168:171], v[208:211], v[106:109]
	v_mfma_f32_16x16x32_bf16 v[102:105], v[176:179], v[208:211], v[102:105]
	v_mfma_f32_16x16x32_bf16 v[90:93], v[168:171], v[216:219], v[90:93]
	v_mfma_f32_16x16x32_bf16 v[86:89], v[176:179], v[216:219], v[86:89]
	v_mfma_f32_16x16x32_bf16 v[74:77], v[168:171], v[224:227], v[74:77]
	v_mfma_f32_16x16x32_bf16 v[70:73], v[176:179], v[224:227], v[70:73]
	s_barrier
	s_add_i32 s74, s74, s12
	v_lshl_add_u64 v[228:229], s[40:41], 0, v[0:1]
	s_mov_b32 m0, s74
	ds_read_b128 v[180:183], v166 offset:16384
	ds_read_b128 v[184:187], v166 offset:17408
	ds_read_b128 v[188:191], v166 offset:18432
	ds_read_b128 v[208:211], v166 offset:19456
	ds_read_b128 v[212:215], v166 offset:20480
	global_load_lds_dwordx4 v[228:229], off
	s_add_i32 m0, s74, 0x2000
	s_add_u32 vcc_lo, s40, 0x40000
	v_lshl_add_u64 v[230:231], s[40:41], 0, v[130:131]
	s_addc_u32 vcc_hi, s41, 0
	s_add_i32 s74, s75, s12
	global_load_lds_dwordx4 v[230:231], off
	v_lshl_add_u64 v[232:233], vcc, 0, v[0:1]
	s_mov_b32 m0, s74
	v_lshl_add_u64 v[238:239], s[42:43], 0, v[132:133]
	global_load_lds_dwordx4 v[232:233], off
	v_lshl_add_u64 v[232:233], vcc, 0, v[130:131]
	s_add_i32 m0, s74, 0x2000
	ds_read_b128 v[216:219], v166 offset:21504
	global_load_lds_dwordx4 v[232:233], off
	v_lshl_add_u64 v[232:233], s[42:43], 0, v[134:135]
	s_mov_b32 m0, s16
	ds_read_b128 v[220:223], v166 offset:22528
	global_load_lds_dwordx4 v[232:233], off
	s_mov_b32 m0, s52
	ds_read_b128 v[224:227], v166 offset:23552
	global_load_lds_dwordx4 v[238:239], off
	s_waitcnt vmcnt(8)
	s_waitcnt lgkmcnt(0)
	s_barrier
; #define PG8_STAGE(bufoff, gbase, voff) do { _Pragma("unroll") for (int _i = 0; _i < 2; ++_i) \
;         __builtin_amdgcn_global_load_lds((const unsigned*)((const char*)(gbase) + (voff)[_i]), (LAS unsigned*)(lds + (bufoff) + ldsw + _i * 8192), 16, 0, 0); } while (0)
; #define PG8_LDA(dst, b, h) do { _Pragma("unroll") for (int m = 0; m < 4; ++m) _Pragma("unroll") for (int k = 0; k < 2; ++k) dst[m][k] = *(const LAS bf16x8*)(lds + PG8_SA(b, h) + aoff + m * 2048 + k * 1024); } while (0)
; #define PG8_LDB(dst, b, h) do { _Pragma("unroll") for (int n = 0; n < 2; ++n) _Pragma("unroll") for (int k = 0; k < 2; ++k) dst[n][k] = *(const LAS bf16x8*)(lds + PG8_SB(b, h) + boff + n * 2048 + k * 1024); } while (0)
; #define PG8_MMA(ai, bj, At, Bt) do { __builtin_amdgcn_s_setprio(1); _Pragma("unroll") for (int m = 0; m < 4; ++m) _Pragma("unroll") for (int n = 0; n < 2; ++n) _Pragma("unroll") for (int k = 0; k < 2; ++k) \
;         acc[ai][bj][m][n] = __builtin_amdgcn_mfma_f32_16x16x32_bf16(Bt[n][k], At[m][k], acc[ai][bj][m][n], 0, 0, 0); __builtin_amdgcn_s_setprio(0); } while (0)
; #define PG8_WAIT_V(n) asm volatile("s_waitcnt vmcnt(" #n ")" ::: "memory")
; #define PG8_WAIT_L(n) asm volatile("s_waitcnt lgkmcnt(" #n ")" ::: "memory")
; #define PG8_BAR __builtin_amdgcn_s_barrier()
; #define PG8_SCHED __builtin_amdgcn_sched_barrier(0)
; template <class Epi, class Sched>
; __device__ __forceinline__ void gemm_phase(LAS unsigned char* lds, const Gemm g, const Sched& S, const Epi& E) {
;     ...
;             PG8_LDA(At, 0, 1); PG8_STAGE(PG8_SB(0, 0), b2, voffB); PG8_STAGE(PG8_SB(0, 1), b2 + hsB, voffB); PG8_STAGE(PG8_SA(0, 0), a2, voffA);
;             PG8_WAIT_V(8); PG8_WAIT_L(0); PG8_BAR; PG8_MMA(1, 0, At, B0); PG8_MMA(1, 1, At, B1); PG8_BAR; PG8_SCHED;
;             PG8_LDB(B0, 1, 0); PG8_LDB(B1, 1, 1); PG8_SCHED; PG8_LDA(At, 1, 0); PG8_STAGE(PG8_SA(0, 1), a2 + hsA, voffA);
;             PG8_WAIT_V(8); PG8_WAIT_L(0); PG8_BAR; PG8_MMA(0, 0, At, B0); PG8_MMA(0, 1, At, B1); PG8_BAR; PG8_SCHED;
	v_mfma_f32_16x16x32_bf16 v[62:65], v[142:145], v[180:183], v[62:65]
	v_mfma_f32_16x16x32_bf16 v[50:53], v[150:153], v[180:183], v[50:53]
	v_mfma_f32_16x16x32_bf16 v[46:49], v[142:145], v[188:191], v[46:49]
	v_mfma_f32_16x16x32_bf16 v[34:37], v[150:153], v[188:191], v[34:37]
	v_mfma_f32_16x16x32_bf16 v[30:33], v[142:145], v[212:215], v[30:33]
	v_mfma_f32_16x16x32_bf16 v[18:21], v[150:153], v[212:215], v[18:21]
	v_mfma_f32_16x16x32_bf16 v[10:13], v[142:145], v[220:223], v[10:13]
	v_mfma_f32_16x16x32_bf16 v[2:5], v[150:153], v[220:223], v[2:5]
	v_mfma_f32_16x16x32_bf16 v[62:65], v[146:149], v[184:187], v[62:65]
	v_mfma_f32_16x16x32_bf16 v[50:53], v[154:157], v[184:187], v[50:53]
	v_mfma_f32_16x16x32_bf16 v[46:49], v[146:149], v[208:211], v[46:49]
	v_mfma_f32_16x16x32_bf16 v[34:37], v[154:157], v[208:211], v[34:37]
	v_mfma_f32_16x16x32_bf16 v[30:33], v[146:149], v[216:219], v[30:33]
	v_mfma_f32_16x16x32_bf16 v[18:21], v[154:157], v[216:219], v[18:21]
	v_mfma_f32_16x16x32_bf16 v[10:13], v[146:149], v[224:227], v[10:13]
	v_mfma_f32_16x16x32_bf16 v[2:5], v[154:157], v[224:227], v[2:5]
	v_mfma_f32_16x16x32_bf16 v[58:61], v[158:161], v[180:183], v[58:61]
	v_mfma_f32_16x16x32_bf16 v[54:57], v[172:175], v[180:183], v[54:57]
	v_mfma_f32_16x16x32_bf16 v[42:45], v[158:161], v[188:191], v[42:45]
	v_mfma_f32_16x16x32_bf16 v[38:41], v[172:175], v[188:191], v[38:41]
	v_mfma_f32_16x16x32_bf16 v[26:29], v[158:161], v[212:215], v[26:29]
	v_mfma_f32_16x16x32_bf16 v[22:25], v[172:175], v[212:215], v[22:25]
	v_mfma_f32_16x16x32_bf16 v[14:17], v[158:161], v[220:223], v[14:17]
	v_mfma_f32_16x16x32_bf16 v[6:9], v[172:175], v[220:223], v[6:9]
	v_mfma_f32_16x16x32_bf16 v[58:61], v[168:171], v[184:187], v[58:61]
	v_mfma_f32_16x16x32_bf16 v[54:57], v[176:179], v[184:187], v[54:57]
	v_mfma_f32_16x16x32_bf16 v[42:45], v[168:171], v[208:211], v[42:45]
	v_mfma_f32_16x16x32_bf16 v[38:41], v[176:179], v[208:211], v[38:41]
	v_mfma_f32_16x16x32_bf16 v[26:29], v[168:171], v[216:219], v[26:29]
	v_mfma_f32_16x16x32_bf16 v[22:25], v[176:179], v[216:219], v[22:25]
	v_mfma_f32_16x16x32_bf16 v[14:17], v[168:171], v[224:227], v[14:17]
	v_mfma_f32_16x16x32_bf16 v[6:9], v[176:179], v[224:227], v[6:9]
	s_barrier
	s_add_i32 s74, 0, 0x18000
	s_add_i32 s75, 0, 0x1c000
	v_add_u32_e32 v154, s74, v165
	v_add_u32_e32 v162, s75, v165
	ds_read_b128 v[142:145], v154
	ds_read_b128 v[146:149], v154 offset:1024
	ds_read_b128 v[150:153], v154 offset:2048
	ds_read_b128 v[154:157], v154 offset:3072
	ds_read_b128 v[158:161], v162
	ds_read_b128 v[168:171], v162 offset:1024
	ds_read_b128 v[172:175], v162 offset:2048
	ds_read_b128 v[176:179], v162 offset:3072
	s_add_u32 s42, s42, 0x40000
	s_addc_u32 s43, s43, 0
	s_mov_b32 m0, s64
	v_lshl_add_u64 v[240:241], s[42:43], 0, v[134:135]
	ds_read_b128 v[180:183], v166 offset:32768
	ds_read_b128 v[184:187], v166 offset:33792
	ds_read_b128 v[188:191], v166 offset:34816
	ds_read_b128 v[208:211], v166 offset:35840
	ds_read_b128 v[212:215], v166 offset:36864
	ds_read_b128 v[216:219], v166 offset:37888
	ds_read_b128 v[220:223], v166 offset:38912
	global_load_lds_dwordx4 v[240:241], off
	v_lshl_add_u64 v[240:241], s[42:43], 0, v[132:133]
	s_mov_b32 m0, s78
	ds_read_b128 v[224:227], v166 offset:39936
	global_load_lds_dwordx4 v[240:241], off
	s_waitcnt vmcnt(8)
	s_waitcnt lgkmcnt(0)
	s_barrier
	v_mfma_f32_16x16x32_bf16 v[122:125], v[142:145], v[180:183], v[122:125]
	v_mfma_f32_16x16x32_bf16 v[114:117], v[150:153], v[180:183], v[114:117]
	v_mfma_f32_16x16x32_bf16 v[110:113], v[142:145], v[188:191], v[110:113]
	v_mfma_f32_16x16x32_bf16 v[98:101], v[150:153], v[188:191], v[98:101]
	v_mfma_f32_16x16x32_bf16 v[94:97], v[142:145], v[212:215], v[94:97]
	v_mfma_f32_16x16x32_bf16 v[82:85], v[150:153], v[212:215], v[82:85]
	v_mfma_f32_16x16x32_bf16 v[78:81], v[142:145], v[220:223], v[78:81]
	v_mfma_f32_16x16x32_bf16 v[66:69], v[150:153], v[220:223], v[66:69]
	v_mfma_f32_16x16x32_bf16 v[122:125], v[146:149], v[184:187], v[122:125]
	v_mfma_f32_16x16x32_bf16 v[114:117], v[154:157], v[184:187], v[114:117]
	v_mfma_f32_16x16x32_bf16 v[110:113], v[146:149], v[208:211], v[110:113]
	v_mfma_f32_16x16x32_bf16 v[98:101], v[154:157], v[208:211], v[98:101]
	v_mfma_f32_16x16x32_bf16 v[94:97], v[146:149], v[216:219], v[94:97]
	v_mfma_f32_16x16x32_bf16 v[82:85], v[154:157], v[216:219], v[82:85]
	v_mfma_f32_16x16x32_bf16 v[78:81], v[146:149], v[224:227], v[78:81]
	v_mfma_f32_16x16x32_bf16 v[66:69], v[154:157], v[224:227], v[66:69]
	v_mfma_f32_16x16x32_bf16 v[126:129], v[158:161], v[180:183], v[126:129]
	v_mfma_f32_16x16x32_bf16 v[118:121], v[172:175], v[180:183], v[118:121]
	v_mfma_f32_16x16x32_bf16 v[106:109], v[158:161], v[188:191], v[106:109]
	v_mfma_f32_16x16x32_bf16 v[102:105], v[172:175], v[188:191], v[102:105]
	v_mfma_f32_16x16x32_bf16 v[90:93], v[158:161], v[212:215], v[90:93]
	v_mfma_f32_16x16x32_bf16 v[86:89], v[172:175], v[212:215], v[86:89]
	v_mfma_f32_16x16x32_bf16 v[74:77], v[158:161], v[220:223], v[74:77]
	v_mfma_f32_16x16x32_bf16 v[70:73], v[172:175], v[220:223], v[70:73]
	v_mfma_f32_16x16x32_bf16 v[126:129], v[168:171], v[184:187], v[126:129]
	v_mfma_f32_16x16x32_bf16 v[118:121], v[176:179], v[184:187], v[118:121]
	v_mfma_f32_16x16x32_bf16 v[106:109], v[168:171], v[208:211], v[106:109]
	v_mfma_f32_16x16x32_bf16 v[102:105], v[176:179], v[208:211], v[102:105]
	v_mfma_f32_16x16x32_bf16 v[90:93], v[168:171], v[216:219], v[90:93]
	v_mfma_f32_16x16x32_bf16 v[86:89], v[176:179], v[216:219], v[86:89]
	v_mfma_f32_16x16x32_bf16 v[74:77], v[168:171], v[224:227], v[74:77]
	v_mfma_f32_16x16x32_bf16 v[70:73], v[176:179], v[224:227], v[70:73]
	s_barrier
; #define PG8_STAGE(bufoff, gbase, voff) do { _Pragma("unroll") for (int _i = 0; _i < 2; ++_i) \
;         __builtin_amdgcn_global_load_lds((const unsigned*)((const char*)(gbase) + (voff)[_i]), (LAS unsigned*)(lds + (bufoff) + ldsw + _i * 8192), 16, 0, 0); } while (0)
; #define PG8_LDA(dst, b, h) do { _Pragma("unroll") for (int m = 0; m < 4; ++m) _Pragma("unroll") for (int k = 0; k < 2; ++k) dst[m][k] = *(const LAS bf16x8*)(lds + PG8_SA(b, h) + aoff + m * 2048 + k * 1024); } while (0)
; #define PG8_MMA(ai, bj, At, Bt) do { __builtin_amdgcn_s_setprio(1); _Pragma("unroll") for (int m = 0; m < 4; ++m) _Pragma("unroll") for (int n = 0; n < 2; ++n) _Pragma("unroll") for (int k = 0; k < 2; ++k) \
;         acc[ai][bj][m][n] = __builtin_amdgcn_mfma_f32_16x16x32_bf16(Bt[n][k], At[m][k], acc[ai][bj][m][n], 0, 0, 0); __builtin_amdgcn_s_setprio(0); } while (0)
; #define PG8_WAIT_V(n) asm volatile("s_waitcnt vmcnt(" #n ")" ::: "memory")
; #define PG8_WAIT_L(n) asm volatile("s_waitcnt lgkmcnt(" #n ")" ::: "memory")
; #define PG8_BAR __builtin_amdgcn_s_barrier()
; #define PG8_SCHED __builtin_amdgcn_sched_barrier(0)
; template <class Epi, class Sched>
; __device__ __forceinline__ void gemm_phase(LAS unsigned char* lds, const Gemm g, const Sched& S, const Epi& E) {
;     ...
;             PG8_LDA(At, 1, 1); PG8_STAGE(PG8_SB(1, 0), b3, voffB); PG8_STAGE(PG8_SB(1, 1), b3 + hsB, voffB); PG8_STAGE(PG8_SA(1, 0), a3, voffA);
;             PG8_WAIT_V(8); PG8_WAIT_L(0); PG8_BAR; PG8_MMA(1, 0, At, B0); PG8_MMA(1, 1, At, B1); PG8_BAR; PG8_SCHED;
;         }
	s_add_i32 s42, s74, s12
	v_lshl_add_u64 v[228:229], v[228:229], 0, s[18:19]
	s_mov_b32 m0, s42
	ds_read_b128 v[180:183], v166 offset:49152
	ds_read_b128 v[184:187], v166 offset:50176
	ds_read_b128 v[188:191], v166 offset:51200
	ds_read_b128 v[208:211], v166 offset:52224
	global_load_lds_dwordx4 v[228:229], off
	s_add_i32 m0, s42, 0x2000
	s_add_u32 s40, s40, 0x40080
	v_lshl_add_u64 v[228:229], v[230:231], 0, s[18:19]
	s_addc_u32 s41, s41, 0
	s_add_i32 s42, s75, s12
	global_load_lds_dwordx4 v[228:229], off
	v_lshl_add_u64 v[228:229], s[40:41], 0, v[0:1]
	s_mov_b32 m0, s42
	ds_read_b128 v[212:215], v166 offset:53248
	global_load_lds_dwordx4 v[228:229], off
	v_lshl_add_u64 v[228:229], s[40:41], 0, v[130:131]
	s_add_i32 m0, s42, 0x2000
	ds_read_b128 v[216:219], v166 offset:54272
	global_load_lds_dwordx4 v[228:229], off
	v_lshl_add_u64 v[228:229], v[232:233], 0, s[18:19]
	s_mov_b32 m0, s1
	ds_read_b128 v[220:223], v166 offset:55296
	global_load_lds_dwordx4 v[228:229], off
	v_lshl_add_u64 v[228:229], v[238:239], 0, s[18:19]
	s_mov_b32 m0, s7
	ds_read_b128 v[224:227], v166 offset:56320
	global_load_lds_dwordx4 v[228:229], off
	s_waitcnt vmcnt(8)
	s_waitcnt lgkmcnt(0)
	s_barrier
	v_mfma_f32_16x16x32_bf16 v[62:65], v[142:145], v[180:183], v[62:65]
	v_mfma_f32_16x16x32_bf16 v[50:53], v[150:153], v[180:183], v[50:53]
	v_mfma_f32_16x16x32_bf16 v[46:49], v[142:145], v[188:191], v[46:49]
	v_mfma_f32_16x16x32_bf16 v[34:37], v[150:153], v[188:191], v[34:37]
	v_mfma_f32_16x16x32_bf16 v[30:33], v[142:145], v[212:215], v[30:33]
	v_mfma_f32_16x16x32_bf16 v[18:21], v[150:153], v[212:215], v[18:21]
	v_mfma_f32_16x16x32_bf16 v[10:13], v[142:145], v[220:223], v[10:13]
	v_mfma_f32_16x16x32_bf16 v[2:5], v[150:153], v[220:223], v[2:5]
	v_mfma_f32_16x16x32_bf16 v[62:65], v[146:149], v[184:187], v[62:65]
	v_mfma_f32_16x16x32_bf16 v[50:53], v[154:157], v[184:187], v[50:53]
	v_mfma_f32_16x16x32_bf16 v[46:49], v[146:149], v[208:211], v[46:49]
	v_mfma_f32_16x16x32_bf16 v[34:37], v[154:157], v[208:211], v[34:37]
	v_mfma_f32_16x16x32_bf16 v[30:33], v[146:149], v[216:219], v[30:33]
	v_mfma_f32_16x16x32_bf16 v[18:21], v[154:157], v[216:219], v[18:21]
	v_mfma_f32_16x16x32_bf16 v[10:13], v[146:149], v[224:227], v[10:13]
	v_mfma_f32_16x16x32_bf16 v[2:5], v[154:157], v[224:227], v[2:5]
	v_mfma_f32_16x16x32_bf16 v[58:61], v[158:161], v[180:183], v[58:61]
	v_mfma_f32_16x16x32_bf16 v[54:57], v[172:175], v[180:183], v[54:57]
	v_mfma_f32_16x16x32_bf16 v[42:45], v[158:161], v[188:191], v[42:45]
	v_mfma_f32_16x16x32_bf16 v[38:41], v[172:175], v[188:191], v[38:41]
	v_mfma_f32_16x16x32_bf16 v[26:29], v[158:161], v[212:215], v[26:29]
	v_mfma_f32_16x16x32_bf16 v[22:25], v[172:175], v[212:215], v[22:25]
	v_mfma_f32_16x16x32_bf16 v[14:17], v[158:161], v[220:223], v[14:17]
	v_mfma_f32_16x16x32_bf16 v[6:9], v[172:175], v[220:223], v[6:9]
	v_mfma_f32_16x16x32_bf16 v[58:61], v[168:171], v[184:187], v[58:61]
	v_mfma_f32_16x16x32_bf16 v[54:57], v[176:179], v[184:187], v[54:57]
	v_mfma_f32_16x16x32_bf16 v[42:45], v[168:171], v[208:211], v[42:45]
	v_mfma_f32_16x16x32_bf16 v[38:41], v[176:179], v[208:211], v[38:41]
	v_mfma_f32_16x16x32_bf16 v[26:29], v[168:171], v[216:219], v[26:29]
	v_mfma_f32_16x16x32_bf16 v[22:25], v[176:179], v[216:219], v[22:25]
	v_mfma_f32_16x16x32_bf16 v[14:17], v[168:171], v[224:227], v[14:17]
	v_mfma_f32_16x16x32_bf16 v[6:9], v[176:179], v[224:227], v[6:9]
	s_barrier
	s_add_u32 s38, s38, 0x100
	s_addc_u32 s39, s39, 0
	s_add_u32 s83, s83, 0x100
	s_addc_u32 s84, s84, 0
	s_cmp_ge_i32 s85, s11
	s_mov_b32 s40, s85
	s_cbranch_scc0 .LBB0_485
	s_setprio 0

; #define PG8_STAGE(bufoff, gbase, voff) do { _Pragma("unroll") for (int _i = 0; _i < 2; ++_i) \
;         __builtin_amdgcn_global_load_lds((const unsigned*)((const char*)(gbase) + (voff)[_i]), (LAS unsigned*)(lds + (bufoff) + ldsw + _i * 8192), 16, 0, 0); } while (0)
; #define PG8_LDA(dst, b, h) do { _Pragma("unroll") for (int m = 0; m < 4; ++m) _Pragma("unroll") for (int k = 0; k < 2; ++k) dst[m][k] = *(const LAS bf16x8*)(lds + PG8_SA(b, h) + aoff + m * 2048 + k * 1024); } while (0)
; #define PG8_LDB(dst, b, h) do { _Pragma("unroll") for (int n = 0; n < 2; ++n) _Pragma("unroll") for (int k = 0; k < 2; ++k) dst[n][k] = *(const LAS bf16x8*)(lds + PG8_SB(b, h) + boff + n * 2048 + k * 1024); } while (0)
; #define PG8_MMA(ai, bj, At, Bt) do { __builtin_amdgcn_s_setprio(1); _Pragma("unroll") for (int m = 0; m < 4; ++m) _Pragma("unroll") for (int n = 0; n < 2; ++n) _Pragma("unroll") for (int k = 0; k < 2; ++k) \
;         acc[ai][bj][m][n] = __builtin_amdgcn_mfma_f32_16x16x32_bf16(Bt[n][k], At[m][k], acc[ai][bj][m][n], 0, 0, 0); __builtin_amdgcn_s_setprio(0); } while (0)
; #define PG8_WAIT_V(n) asm volatile("s_waitcnt vmcnt(" #n ")" ::: "memory")
; #define PG8_BAR __builtin_amdgcn_s_barrier()
; template <class Epi, class Sched>
; __device__ __forceinline__ void gemm_phase(LAS unsigned char* lds, const Gemm g, const Sched& S, const Epi& E) {
;     ...
;         for (int t = 0; t < nt; t += 2) {
;             const bool last = (t == nt - 2);
;             const char* a1 = cA + (size_t)(t + 1) * kstep;
;             const char* a2 = last ? nA : cA + (size_t)(t + 2) * kstep; const char* b2 = last ? nB : cB + (size_t)(t + 2) * kstep;
;             const char* a3 = a2 + kstep; const char* b3 = b2 + kstep;
;             if constexpr (Epi::MIDK) { if (t == (nt >> 1)) { int fr_ = fr, fq_ = fq; asm volatile("" : "+v"(fr_), "+v"(fq_)); E.mid(acc, cur, wr, wc, fr_, fq_); } }
;             PG8_LDB(B0, 0, 0); PG8_LDB(B1, 0, 1); PG8_SCHED; PG8_LDA(At, 0, 0); PG8_STAGE(PG8_SA(1, 1), a1 + hsA, voffA);
;             PG8_WAIT_V(8); PG8_WAIT_L(0); PG8_BAR; PG8_MMA(0, 0, At, B0); PG8_MMA(0, 1, At, B1); PG8_BAR; PG8_SCHED;
;             PG8_LDA(At, 0, 1); PG8_STAGE(PG8_SB(0, 0), b2, voffB); PG8_STAGE(PG8_SB(0, 1), b2 + hsB, voffB); PG8_STAGE(PG8_SA(0, 0), a2, voffA);
;             PG8_WAIT_V(8); PG8_WAIT_L(0); PG8_BAR; PG8_MMA(1, 0, At, B0); PG8_MMA(1, 1, At, B1); PG8_BAR; PG8_SCHED;
.Lnp_536:
.LBB0_536:
	s_add_i32 s83, s46, 2
	s_add_u32 s74, s44, 0xfffc0080
	s_addc_u32 s47, s45, -1
	s_add_i32 s75, 0, 0x10000
	s_cmp_eq_u32 s51, s46
	s_cselect_b32 s47, s73, s47
	s_cselect_b32 s46, s76, s74
	v_add_u32_e32 v144, s75, v148
	s_cselect_b32 s85, s77, s82
	s_cselect_b32 s84, s78, s80
	s_add_i32 s74, 0, 0x14000
	ds_read_b128 v[140:143], v144
	ds_read_b128 v[150:153], v144 offset:1024
	ds_read_b128 v[154:157], v144 offset:2048
	ds_read_b128 v[158:161], v144 offset:3072
	v_add_u32_e32 v144, s74, v148
	ds_read_b128 v[162:165], v144
	ds_read_b128 v[166:169], v144 offset:1024
	ds_read_b128 v[170:173], v144 offset:2048
	ds_read_b128 v[174:177], v144 offset:3072
	v_lshl_add_u64 v[144:145], s[44:45], 0, v[136:137]
	s_add_i32 m0, s11, 0xc000
	ds_read_b128 v[178:181], v149
	ds_read_b128 v[182:185], v149 offset:1024
	ds_read_b128 v[186:189], v149 offset:2048
	ds_read_b128 v[208:211], v149 offset:3072
	ds_read_b128 v[212:215], v149 offset:4096
	ds_read_b128 v[216:219], v149 offset:5120
	ds_read_b128 v[220:223], v149 offset:6144
	global_load_lds_dwordx4 v[144:145], off
	v_lshl_add_u64 v[144:145], s[44:45], 0, v[138:139]
	s_add_i32 m0, s11, 0xe000
	ds_read_b128 v[224:227], v149 offset:7168
	global_load_lds_dwordx4 v[144:145], off
	s_waitcnt vmcnt(8)
	s_waitcnt lgkmcnt(0)
	s_barrier
	v_mfma_f32_16x16x32_bf16 v[122:125], v[140:143], v[178:181], v[122:125]
	v_mfma_f32_16x16x32_bf16 v[126:129], v[154:157], v[178:181], v[126:129]
	v_mfma_f32_16x16x32_bf16 v[110:113], v[140:143], v[186:189], v[110:113]
	v_mfma_f32_16x16x32_bf16 v[106:109], v[154:157], v[186:189], v[106:109]
	v_mfma_f32_16x16x32_bf16 v[94:97], v[140:143], v[212:215], v[94:97]
	v_mfma_f32_16x16x32_bf16 v[90:93], v[154:157], v[212:215], v[90:93]
	v_mfma_f32_16x16x32_bf16 v[78:81], v[140:143], v[220:223], v[78:81]
	v_mfma_f32_16x16x32_bf16 v[74:77], v[154:157], v[220:223], v[74:77]
	v_mfma_f32_16x16x32_bf16 v[122:125], v[150:153], v[182:185], v[122:125]
	v_mfma_f32_16x16x32_bf16 v[126:129], v[158:161], v[182:185], v[126:129]
	v_mfma_f32_16x16x32_bf16 v[110:113], v[150:153], v[208:211], v[110:113]
	v_mfma_f32_16x16x32_bf16 v[106:109], v[158:161], v[208:211], v[106:109]
	v_mfma_f32_16x16x32_bf16 v[94:97], v[150:153], v[216:219], v[94:97]
	v_mfma_f32_16x16x32_bf16 v[90:93], v[158:161], v[216:219], v[90:93]
	v_mfma_f32_16x16x32_bf16 v[78:81], v[150:153], v[224:227], v[78:81]
	v_mfma_f32_16x16x32_bf16 v[74:77], v[158:161], v[224:227], v[74:77]
	v_mfma_f32_16x16x32_bf16 v[118:121], v[162:165], v[178:181], v[118:121]
	v_mfma_f32_16x16x32_bf16 v[114:117], v[170:173], v[178:181], v[114:117]
	v_mfma_f32_16x16x32_bf16 v[102:105], v[162:165], v[186:189], v[102:105]
	v_mfma_f32_16x16x32_bf16 v[98:101], v[170:173], v[186:189], v[98:101]
	v_mfma_f32_16x16x32_bf16 v[86:89], v[162:165], v[212:215], v[86:89]
	v_mfma_f32_16x16x32_bf16 v[82:85], v[170:173], v[212:215], v[82:85]
	v_mfma_f32_16x16x32_bf16 v[70:73], v[162:165], v[220:223], v[70:73]
	v_mfma_f32_16x16x32_bf16 v[66:69], v[170:173], v[220:223], v[66:69]
	v_mfma_f32_16x16x32_bf16 v[118:121], v[166:169], v[182:185], v[118:121]
	v_mfma_f32_16x16x32_bf16 v[114:117], v[174:177], v[182:185], v[114:117]
	v_mfma_f32_16x16x32_bf16 v[102:105], v[166:169], v[208:211], v[102:105]
	v_mfma_f32_16x16x32_bf16 v[98:101], v[174:177], v[208:211], v[98:101]
	v_mfma_f32_16x16x32_bf16 v[86:89], v[166:169], v[216:219], v[86:89]
	v_mfma_f32_16x16x32_bf16 v[82:85], v[174:177], v[216:219], v[82:85]
	v_mfma_f32_16x16x32_bf16 v[70:73], v[166:169], v[224:227], v[70:73]
	v_mfma_f32_16x16x32_bf16 v[66:69], v[174:177], v[224:227], v[66:69]
	s_barrier
	s_add_i32 s75, s75, s7
	v_lshl_add_u64 v[144:145], s[84:85], 0, v[0:1]
	s_mov_b32 m0, s75
	ds_read_b128 v[178:181], v149 offset:16384
	ds_read_b128 v[182:185], v149 offset:17408
	ds_read_b128 v[186:189], v149 offset:18432
	ds_read_b128 v[208:211], v149 offset:19456
	ds_read_b128 v[212:215], v149 offset:20480
	global_load_lds_dwordx4 v[144:145], off
	v_lshl_add_u64 v[190:191], s[84:85], 0, v[130:131]
	s_add_i32 m0, s75, 0x2000
	s_add_i32 s74, s74, s7
	global_load_lds_dwordx4 v[190:191], off
	v_lshl_add_u64 v[228:229], v[144:145], 0, s[22:23]
	s_mov_b32 m0, s74
	v_lshl_add_u64 v[230:231], s[46:47], 0, v[132:133]
	global_load_lds_dwordx4 v[228:229], off
	v_lshl_add_u64 v[228:229], v[190:191], 0, s[22:23]
	s_add_i32 m0, s74, 0x2000
	ds_read_b128 v[216:219], v149 offset:21504
	global_load_lds_dwordx4 v[228:229], off
	v_lshl_add_u64 v[228:229], s[46:47], 0, v[134:135]
	s_mov_b32 m0, s11
	ds_read_b128 v[220:223], v149 offset:22528
	global_load_lds_dwordx4 v[228:229], off
	s_mov_b32 m0, s12
	ds_read_b128 v[224:227], v149 offset:23552
	global_load_lds_dwordx4 v[230:231], off
	s_waitcnt vmcnt(8)
	s_waitcnt lgkmcnt(0)
	s_barrier
; #define PG8_STAGE(bufoff, gbase, voff) do { _Pragma("unroll") for (int _i = 0; _i < 2; ++_i) \
;         __builtin_amdgcn_global_load_lds((const unsigned*)((const char*)(gbase) + (voff)[_i]), (LAS unsigned*)(lds + (bufoff) + ldsw + _i * 8192), 16, 0, 0); } while (0)
; #define PG8_LDA(dst, b, h) do { _Pragma("unroll") for (int m = 0; m < 4; ++m) _Pragma("unroll") for (int k = 0; k < 2; ++k) dst[m][k] = *(const LAS bf16x8*)(lds + PG8_SA(b, h) + aoff + m * 2048 + k * 1024); } while (0)
; #define PG8_LDB(dst, b, h) do { _Pragma("unroll") for (int n = 0; n < 2; ++n) _Pragma("unroll") for (int k = 0; k < 2; ++k) dst[n][k] = *(const LAS bf16x8*)(lds + PG8_SB(b, h) + boff + n * 2048 + k * 1024); } while (0)
; #define PG8_MMA(ai, bj, At, Bt) do { __builtin_amdgcn_s_setprio(1); _Pragma("unroll") for (int m = 0; m < 4; ++m) _Pragma("unroll") for (int n = 0; n < 2; ++n) _Pragma("unroll") for (int k = 0; k < 2; ++k) \
;         acc[ai][bj][m][n] = __builtin_amdgcn_mfma_f32_16x16x32_bf16(Bt[n][k], At[m][k], acc[ai][bj][m][n], 0, 0, 0); __builtin_amdgcn_s_setprio(0); } while (0)
; #define PG8_WAIT_V(n) asm volatile("s_waitcnt vmcnt(" #n ")" ::: "memory")
; #define PG8_WAIT_L(n) asm volatile("s_waitcnt lgkmcnt(" #n ")" ::: "memory")
; #define PG8_BAR __builtin_amdgcn_s_barrier()
; #define PG8_SCHED __builtin_amdgcn_sched_barrier(0)
; template <class Epi, class Sched>
; __device__ __forceinline__ void gemm_phase(LAS unsigned char* lds, const Gemm g, const Sched& S, const Epi& E) {
;     ...
;             PG8_LDA(At, 0, 1); PG8_STAGE(PG8_SB(0, 0), b2, voffB); PG8_STAGE(PG8_SB(0, 1), b2 + hsB, voffB); PG8_STAGE(PG8_SA(0, 0), a2, voffA);
;             PG8_WAIT_V(8); PG8_WAIT_L(0); PG8_BAR; PG8_MMA(1, 0, At, B0); PG8_MMA(1, 1, At, B1); PG8_BAR; PG8_SCHED;
;             PG8_LDB(B0, 1, 0); PG8_LDB(B1, 1, 1); PG8_SCHED; PG8_LDA(At, 1, 0); PG8_STAGE(PG8_SA(0, 1), a2 + hsA, voffA);
;             PG8_WAIT_V(8); PG8_WAIT_L(0); PG8_BAR; PG8_MMA(0, 0, At, B0); PG8_MMA(0, 1, At, B1); PG8_BAR; PG8_SCHED;
	v_mfma_f32_16x16x32_bf16 v[62:65], v[140:143], v[178:181], v[62:65]
	v_mfma_f32_16x16x32_bf16 v[58:61], v[154:157], v[178:181], v[58:61]
	v_mfma_f32_16x16x32_bf16 v[46:49], v[140:143], v[186:189], v[46:49]
	v_mfma_f32_16x16x32_bf16 v[42:45], v[154:157], v[186:189], v[42:45]
	v_mfma_f32_16x16x32_bf16 v[30:33], v[140:143], v[212:215], v[30:33]
	v_mfma_f32_16x16x32_bf16 v[26:29], v[154:157], v[212:215], v[26:29]
	v_mfma_f32_16x16x32_bf16 v[14:17], v[140:143], v[220:223], v[14:17]
	v_mfma_f32_16x16x32_bf16 v[10:13], v[154:157], v[220:223], v[10:13]
	v_mfma_f32_16x16x32_bf16 v[62:65], v[150:153], v[182:185], v[62:65]
	v_mfma_f32_16x16x32_bf16 v[58:61], v[158:161], v[182:185], v[58:61]
	v_mfma_f32_16x16x32_bf16 v[46:49], v[150:153], v[208:211], v[46:49]
	v_mfma_f32_16x16x32_bf16 v[42:45], v[158:161], v[208:211], v[42:45]
	v_mfma_f32_16x16x32_bf16 v[30:33], v[150:153], v[216:219], v[30:33]
	v_mfma_f32_16x16x32_bf16 v[26:29], v[158:161], v[216:219], v[26:29]
	v_mfma_f32_16x16x32_bf16 v[14:17], v[150:153], v[224:227], v[14:17]
	v_mfma_f32_16x16x32_bf16 v[10:13], v[158:161], v[224:227], v[10:13]
	v_mfma_f32_16x16x32_bf16 v[54:57], v[162:165], v[178:181], v[54:57]
	v_mfma_f32_16x16x32_bf16 v[50:53], v[170:173], v[178:181], v[50:53]
	v_mfma_f32_16x16x32_bf16 v[38:41], v[162:165], v[186:189], v[38:41]
	v_mfma_f32_16x16x32_bf16 v[34:37], v[170:173], v[186:189], v[34:37]
	v_mfma_f32_16x16x32_bf16 v[22:25], v[162:165], v[212:215], v[22:25]
	v_mfma_f32_16x16x32_bf16 v[18:21], v[170:173], v[212:215], v[18:21]
	v_mfma_f32_16x16x32_bf16 v[6:9], v[162:165], v[220:223], v[6:9]
	v_mfma_f32_16x16x32_bf16 v[2:5], v[170:173], v[220:223], v[2:5]
	v_mfma_f32_16x16x32_bf16 v[54:57], v[166:169], v[182:185], v[54:57]
	v_mfma_f32_16x16x32_bf16 v[50:53], v[174:177], v[182:185], v[50:53]
	v_mfma_f32_16x16x32_bf16 v[38:41], v[166:169], v[208:211], v[38:41]
	v_mfma_f32_16x16x32_bf16 v[34:37], v[174:177], v[208:211], v[34:37]
	v_mfma_f32_16x16x32_bf16 v[22:25], v[166:169], v[216:219], v[22:25]
	v_mfma_f32_16x16x32_bf16 v[18:21], v[174:177], v[216:219], v[18:21]
	v_mfma_f32_16x16x32_bf16 v[6:9], v[166:169], v[224:227], v[6:9]
	v_mfma_f32_16x16x32_bf16 v[2:5], v[174:177], v[224:227], v[2:5]
	s_barrier
	s_add_i32 s74, 0, 0x18000
	s_add_i32 s75, 0, 0x1c000
	v_add_u32_e32 v158, s74, v148
	v_add_u32_e32 v174, s75, v148
	ds_read_b128 v[140:143], v158
	ds_read_b128 v[150:153], v158 offset:1024
	ds_read_b128 v[154:157], v158 offset:2048
	ds_read_b128 v[158:161], v158 offset:3072
	ds_read_b128 v[162:165], v174
	ds_read_b128 v[166:169], v174 offset:1024
	ds_read_b128 v[170:173], v174 offset:2048
	ds_read_b128 v[174:177], v174 offset:3072
	s_add_u32 s46, s46, 0x40000
	s_addc_u32 s47, s47, 0
	s_mov_b32 m0, s16
	v_lshl_add_u64 v[232:233], s[46:47], 0, v[134:135]
	ds_read_b128 v[178:181], v149 offset:32768
	ds_read_b128 v[182:185], v149 offset:33792
	ds_read_b128 v[186:189], v149 offset:34816
	ds_read_b128 v[208:211], v149 offset:35840
	ds_read_b128 v[212:215], v149 offset:36864
	ds_read_b128 v[216:219], v149 offset:37888
	ds_read_b128 v[220:223], v149 offset:38912
	global_load_lds_dwordx4 v[232:233], off
	v_lshl_add_u64 v[232:233], s[46:47], 0, v[132:133]
	s_mov_b32 m0, s24
	ds_read_b128 v[224:227], v149 offset:39936
	global_load_lds_dwordx4 v[232:233], off
	s_waitcnt vmcnt(8)
	s_waitcnt lgkmcnt(0)
	s_barrier
	v_mfma_f32_16x16x32_bf16 v[122:125], v[140:143], v[178:181], v[122:125]
	v_mfma_f32_16x16x32_bf16 v[126:129], v[154:157], v[178:181], v[126:129]
	v_mfma_f32_16x16x32_bf16 v[110:113], v[140:143], v[186:189], v[110:113]
	v_mfma_f32_16x16x32_bf16 v[106:109], v[154:157], v[186:189], v[106:109]
	v_mfma_f32_16x16x32_bf16 v[94:97], v[140:143], v[212:215], v[94:97]
	v_mfma_f32_16x16x32_bf16 v[90:93], v[154:157], v[212:215], v[90:93]
	v_mfma_f32_16x16x32_bf16 v[78:81], v[140:143], v[220:223], v[78:81]
	v_mfma_f32_16x16x32_bf16 v[74:77], v[154:157], v[220:223], v[74:77]
	v_mfma_f32_16x16x32_bf16 v[122:125], v[150:153], v[182:185], v[122:125]
	v_mfma_f32_16x16x32_bf16 v[126:129], v[158:161], v[182:185], v[126:129]
	v_mfma_f32_16x16x32_bf16 v[110:113], v[150:153], v[208:211], v[110:113]
	v_mfma_f32_16x16x32_bf16 v[106:109], v[158:161], v[208:211], v[106:109]
	v_mfma_f32_16x16x32_bf16 v[94:97], v[150:153], v[216:219], v[94:97]
	v_mfma_f32_16x16x32_bf16 v[90:93], v[158:161], v[216:219], v[90:93]
	v_mfma_f32_16x16x32_bf16 v[78:81], v[150:153], v[224:227], v[78:81]
	v_mfma_f32_16x16x32_bf16 v[74:77], v[158:161], v[224:227], v[74:77]
	v_mfma_f32_16x16x32_bf16 v[118:121], v[162:165], v[178:181], v[118:121]
	v_mfma_f32_16x16x32_bf16 v[114:117], v[170:173], v[178:181], v[114:117]
	v_mfma_f32_16x16x32_bf16 v[102:105], v[162:165], v[186:189], v[102:105]
	v_mfma_f32_16x16x32_bf16 v[98:101], v[170:173], v[186:189], v[98:101]
	v_mfma_f32_16x16x32_bf16 v[86:89], v[162:165], v[212:215], v[86:89]
	v_mfma_f32_16x16x32_bf16 v[82:85], v[170:173], v[212:215], v[82:85]
	v_mfma_f32_16x16x32_bf16 v[70:73], v[162:165], v[220:223], v[70:73]
	v_mfma_f32_16x16x32_bf16 v[66:69], v[170:173], v[220:223], v[66:69]
	v_mfma_f32_16x16x32_bf16 v[118:121], v[166:169], v[182:185], v[118:121]
	v_mfma_f32_16x16x32_bf16 v[114:117], v[174:177], v[182:185], v[114:117]
	v_mfma_f32_16x16x32_bf16 v[102:105], v[166:169], v[208:211], v[102:105]
	v_mfma_f32_16x16x32_bf16 v[98:101], v[174:177], v[208:211], v[98:101]
	v_mfma_f32_16x16x32_bf16 v[86:89], v[166:169], v[216:219], v[86:89]
	v_mfma_f32_16x16x32_bf16 v[82:85], v[174:177], v[216:219], v[82:85]
	v_mfma_f32_16x16x32_bf16 v[70:73], v[166:169], v[224:227], v[70:73]
	v_mfma_f32_16x16x32_bf16 v[66:69], v[174:177], v[224:227], v[66:69]
	s_barrier
; #define PG8_STAGE(bufoff, gbase, voff) do { _Pragma("unroll") for (int _i = 0; _i < 2; ++_i) \
;         __builtin_amdgcn_global_load_lds((const unsigned*)((const char*)(gbase) + (voff)[_i]), (LAS unsigned*)(lds + (bufoff) + ldsw + _i * 8192), 16, 0, 0); } while (0)
; #define PG8_LDA(dst, b, h) do { _Pragma("unroll") for (int m = 0; m < 4; ++m) _Pragma("unroll") for (int k = 0; k < 2; ++k) dst[m][k] = *(const LAS bf16x8*)(lds + PG8_SA(b, h) + aoff + m * 2048 + k * 1024); } while (0)
; #define PG8_MMA(ai, bj, At, Bt) do { __builtin_amdgcn_s_setprio(1); _Pragma("unroll") for (int m = 0; m < 4; ++m) _Pragma("unroll") for (int n = 0; n < 2; ++n) _Pragma("unroll") for (int k = 0; k < 2; ++k) \
;         acc[ai][bj][m][n] = __builtin_amdgcn_mfma_f32_16x16x32_bf16(Bt[n][k], At[m][k], acc[ai][bj][m][n], 0, 0, 0); __builtin_amdgcn_s_setprio(0); } while (0)
; #define PG8_WAIT_V(n) asm volatile("s_waitcnt vmcnt(" #n ")" ::: "memory")
; #define PG8_WAIT_L(n) asm volatile("s_waitcnt lgkmcnt(" #n ")" ::: "memory")
; #define PG8_BAR __builtin_amdgcn_s_barrier()
; #define PG8_SCHED __builtin_amdgcn_sched_barrier(0)
; template <class Epi, class Sched>
; __device__ __forceinline__ void gemm_phase(LAS unsigned char* lds, const Gemm g, const Sched& S, const Epi& E) {
;     ...
;             PG8_LDA(At, 1, 1); PG8_STAGE(PG8_SB(1, 0), b3, voffB); PG8_STAGE(PG8_SB(1, 1), b3 + hsB, voffB); PG8_STAGE(PG8_SA(1, 0), a3, voffA);
;             PG8_WAIT_V(8); PG8_WAIT_L(0); PG8_BAR; PG8_MMA(1, 0, At, B0); PG8_MMA(1, 1, At, B1); PG8_BAR; PG8_SCHED;
;         }
	s_add_i32 s46, s74, s7
	v_lshl_add_u64 v[232:233], v[144:145], 0, s[18:19]
	s_mov_b32 m0, s46
	ds_read_b128 v[178:181], v149 offset:49152
	ds_read_b128 v[182:185], v149 offset:50176
	ds_read_b128 v[186:189], v149 offset:51200
	ds_read_b128 v[208:211], v149 offset:52224
	global_load_lds_dwordx4 v[232:233], off
	v_lshl_add_u64 v[232:233], v[190:191], 0, s[18:19]
	s_add_i32 m0, s46, 0x2000
	s_add_i32 s46, s75, s7
	global_load_lds_dwordx4 v[232:233], off
	v_lshl_add_u64 v[144:145], v[144:145], 0, vcc
	s_mov_b32 m0, s46
	ds_read_b128 v[212:215], v149 offset:53248
	global_load_lds_dwordx4 v[144:145], off
	v_lshl_add_u64 v[144:145], v[190:191], 0, vcc
	s_add_i32 m0, s46, 0x2000
	ds_read_b128 v[216:219], v149 offset:54272
	global_load_lds_dwordx4 v[144:145], off
	v_lshl_add_u64 v[144:145], v[228:229], 0, s[18:19]
	s_mov_b32 m0, s49
	ds_read_b128 v[220:223], v149 offset:55296
	global_load_lds_dwordx4 v[144:145], off
	v_lshl_add_u64 v[144:145], v[230:231], 0, s[18:19]
	s_mov_b32 m0, s50
	ds_read_b128 v[224:227], v149 offset:56320
	global_load_lds_dwordx4 v[144:145], off
	s_waitcnt vmcnt(8)
	s_waitcnt lgkmcnt(0)
	s_barrier
	v_mfma_f32_16x16x32_bf16 v[62:65], v[140:143], v[178:181], v[62:65]
	v_mfma_f32_16x16x32_bf16 v[58:61], v[154:157], v[178:181], v[58:61]
	v_mfma_f32_16x16x32_bf16 v[46:49], v[140:143], v[186:189], v[46:49]
	v_mfma_f32_16x16x32_bf16 v[42:45], v[154:157], v[186:189], v[42:45]
	v_mfma_f32_16x16x32_bf16 v[30:33], v[140:143], v[212:215], v[30:33]
	v_mfma_f32_16x16x32_bf16 v[26:29], v[154:157], v[212:215], v[26:29]
	v_mfma_f32_16x16x32_bf16 v[14:17], v[140:143], v[220:223], v[14:17]
	v_mfma_f32_16x16x32_bf16 v[10:13], v[154:157], v[220:223], v[10:13]
	v_mfma_f32_16x16x32_bf16 v[62:65], v[150:153], v[182:185], v[62:65]
	v_mfma_f32_16x16x32_bf16 v[58:61], v[158:161], v[182:185], v[58:61]
	v_mfma_f32_16x16x32_bf16 v[46:49], v[150:153], v[208:211], v[46:49]
	v_mfma_f32_16x16x32_bf16 v[42:45], v[158:161], v[208:211], v[42:45]
	v_mfma_f32_16x16x32_bf16 v[30:33], v[150:153], v[216:219], v[30:33]
	v_mfma_f32_16x16x32_bf16 v[26:29], v[158:161], v[216:219], v[26:29]
	v_mfma_f32_16x16x32_bf16 v[14:17], v[150:153], v[224:227], v[14:17]
	v_mfma_f32_16x16x32_bf16 v[10:13], v[158:161], v[224:227], v[10:13]
	v_mfma_f32_16x16x32_bf16 v[54:57], v[162:165], v[178:181], v[54:57]
	v_mfma_f32_16x16x32_bf16 v[50:53], v[170:173], v[178:181], v[50:53]
	v_mfma_f32_16x16x32_bf16 v[38:41], v[162:165], v[186:189], v[38:41]
	v_mfma_f32_16x16x32_bf16 v[34:37], v[170:173], v[186:189], v[34:37]
	v_mfma_f32_16x16x32_bf16 v[22:25], v[162:165], v[212:215], v[22:25]
	v_mfma_f32_16x16x32_bf16 v[18:21], v[170:173], v[212:215], v[18:21]
	v_mfma_f32_16x16x32_bf16 v[6:9], v[162:165], v[220:223], v[6:9]
	v_mfma_f32_16x16x32_bf16 v[2:5], v[170:173], v[220:223], v[2:5]
	v_mfma_f32_16x16x32_bf16 v[54:57], v[166:169], v[182:185], v[54:57]
	v_mfma_f32_16x16x32_bf16 v[50:53], v[174:177], v[182:185], v[50:53]
	v_mfma_f32_16x16x32_bf16 v[38:41], v[166:169], v[208:211], v[38:41]
	v_mfma_f32_16x16x32_bf16 v[34:37], v[174:177], v[208:211], v[34:37]
	v_mfma_f32_16x16x32_bf16 v[22:25], v[166:169], v[216:219], v[22:25]
	v_mfma_f32_16x16x32_bf16 v[18:21], v[174:177], v[216:219], v[18:21]
	v_mfma_f32_16x16x32_bf16 v[6:9], v[166:169], v[224:227], v[6:9]
	v_mfma_f32_16x16x32_bf16 v[2:5], v[174:177], v[224:227], v[2:5]
	s_barrier
	s_add_u32 s44, s44, 0x100
	s_addc_u32 s45, s45, 0
	s_add_u32 s80, s80, 0x100
	s_addc_u32 s82, s82, 0
	s_cmp_ge_i32 s83, s26
	s_mov_b32 s46, s83
	s_cbranch_scc0 .LBB0_536
	s_setprio 0
	v_readlane_b32 s82, v254, 45
	v_readlane_b32 s83, v254, 46

; #define PG8_STAGE(bufoff, gbase, voff) do { _Pragma("unroll") for (int _i = 0; _i < 2; ++_i) \
;         __builtin_amdgcn_global_load_lds((const unsigned*)((const char*)(gbase) + (voff)[_i]), (LAS unsigned*)(lds + (bufoff) + ldsw + _i * 8192), 16, 0, 0); } while (0)
; #define PG8_LDA(dst, b, h) do { _Pragma("unroll") for (int m = 0; m < 4; ++m) _Pragma("unroll") for (int k = 0; k < 2; ++k) dst[m][k] = *(const LAS bf16x8*)(lds + PG8_SA(b, h) + aoff + m * 2048 + k * 1024); } while (0)
; #define PG8_LDB(dst, b, h) do { _Pragma("unroll") for (int n = 0; n < 2; ++n) _Pragma("unroll") for (int k = 0; k < 2; ++k) dst[n][k] = *(const LAS bf16x8*)(lds + PG8_SB(b, h) + boff + n * 2048 + k * 1024); } while (0)
; #define PG8_WAIT_V(n) asm volatile("s_waitcnt vmcnt(" #n ")" ::: "memory")
; #define PG8_WAIT_L(n) asm volatile("s_waitcnt lgkmcnt(" #n ")" ::: "memory")
; #define PG8_BAR __builtin_amdgcn_s_barrier()
; #define PG8_SCHED __builtin_amdgcn_sched_barrier(0)
; template <class Epi, class Sched>
; __device__ __forceinline__ void gemm_phase(LAS unsigned char* lds, const Gemm g, const Sched& S, const Epi& E) {
;     ...
;         const bool has_next = S.next(ui + 1, nxt);
;         const char* nA = has_next ? (const char*)g.A + nxt.offA : cA; const char* nB = has_next ? (const char*)g.Bt + nxt.offB : cB;
;         for (int t = 0; t < nt; t += 2) {
;             const bool last = (t == nt - 2);
;             const char* a1 = cA + (size_t)(t + 1) * kstep;
;             const char* a2 = last ? nA : cA + (size_t)(t + 2) * kstep; const char* b2 = last ? nB : cB + (size_t)(t + 2) * kstep;
;             const char* a3 = a2 + kstep; const char* b3 = b2 + kstep;
;             if constexpr (Epi::MIDK) { if (t == (nt >> 1)) { int fr_ = fr, fq_ = fq; asm volatile("" : "+v"(fr_), "+v"(fq_)); E.mid(acc, cur, wr, wc, fr_, fq_); } }
;             PG8_LDB(B0, 0, 0); PG8_LDB(B1, 0, 1); PG8_SCHED; PG8_LDA(At, 0, 0); PG8_STAGE(PG8_SA(1, 1), a1 + hsA, voffA);
;             PG8_WAIT_V(8); PG8_WAIT_L(0); PG8_BAR; PG8_MMA(0, 0, At, B0); PG8_MMA(0, 1, At, B1); PG8_BAR; PG8_SCHED;
;             PG8_LDA(At, 0, 1); PG8_STAGE(PG8_SB(0, 0), b2, voffB); PG8_STAGE(PG8_SB(0, 1), b2 + hsB, voffB); PG8_STAGE(PG8_SA(0, 0), a2, voffA);
;             PG8_WAIT_V(8); PG8_WAIT_L(0); PG8_BAR; PG8_MMA(1, 0, At, B0); PG8_MMA(1, 1, At, B1); PG8_BAR; PG8_SCHED;
.Lnp_637:
.LBB0_637:
	s_add_i32 s0, s46, 2
	s_add_u32 s44, s42, 0x100
	s_addc_u32 s45, s43, 0
	s_add_u32 s1, s77, s42
	s_addc_u32 s22, s78, s43
	s_cmp_eq_u32 s56, s46
	s_cselect_b32 s48, 0, s44
	s_cselect_b32 s23, 0, s45
	s_cselect_b32 s46, s76, s1
	s_cselect_b32 s47, s73, s22
	s_add_u32 s48, s58, s48
	s_addc_u32 s49, s59, s23
	s_add_i32 s1, 0, 0x10000
	v_add_u32_e32 v0, s1, v152
	s_add_i32 s22, 0, 0x14000
	ds_read_b128 v[142:145], v0
	ds_read_b128 v[146:149], v0 offset:1024
	ds_read_b128 v[154:157], v0 offset:2048
	ds_read_b128 v[158:161], v0 offset:3072
	v_add_u32_e32 v0, s22, v152
	ds_read_b128 v[162:165], v0
	ds_read_b128 v[166:169], v0 offset:1024
	ds_read_b128 v[170:173], v0 offset:2048
	ds_read_b128 v[174:177], v0 offset:3072
	v_lshl_add_u64 v[190:191], v[138:139], 0, s[42:43]
	s_add_i32 m0, s11, 0xc000
	ds_read_b128 v[178:181], v153
	ds_read_b128 v[182:185], v153 offset:1024
	ds_read_b128 v[186:189], v153 offset:2048
	ds_read_b128 v[208:211], v153 offset:3072
	ds_read_b128 v[212:215], v153 offset:4096
	ds_read_b128 v[216:219], v153 offset:5120
	ds_read_b128 v[220:223], v153 offset:6144
	global_load_lds_dwordx4 v[190:191], off
	v_lshl_add_u64 v[190:191], v[140:141], 0, s[42:43]
	s_add_i32 m0, s11, 0xe000
	ds_read_b128 v[224:227], v153 offset:7168
	global_load_lds_dwordx4 v[190:191], off
	s_waitcnt vmcnt(8)
	s_waitcnt lgkmcnt(0)
	s_barrier
	v_mfma_f32_16x16x32_bf16 v[126:129], v[142:145], v[178:181], v[126:129]
	v_mfma_f32_16x16x32_bf16 v[118:121], v[154:157], v[178:181], v[118:121]
	v_mfma_f32_16x16x32_bf16 v[94:97], v[142:145], v[186:189], v[94:97]
	v_mfma_f32_16x16x32_bf16 v[86:89], v[154:157], v[186:189], v[86:89]
	v_mfma_f32_16x16x32_bf16 v[62:65], v[142:145], v[212:215], v[62:65]
	v_mfma_f32_16x16x32_bf16 v[54:57], v[154:157], v[212:215], v[54:57]
	v_mfma_f32_16x16x32_bf16 v[30:33], v[142:145], v[220:223], v[30:33]
	v_mfma_f32_16x16x32_bf16 v[22:25], v[154:157], v[220:223], v[22:25]
	v_mfma_f32_16x16x32_bf16 v[126:129], v[146:149], v[182:185], v[126:129]
	v_mfma_f32_16x16x32_bf16 v[118:121], v[158:161], v[182:185], v[118:121]
	v_mfma_f32_16x16x32_bf16 v[94:97], v[146:149], v[208:211], v[94:97]
	v_mfma_f32_16x16x32_bf16 v[86:89], v[158:161], v[208:211], v[86:89]
	v_mfma_f32_16x16x32_bf16 v[62:65], v[146:149], v[216:219], v[62:65]
	v_mfma_f32_16x16x32_bf16 v[54:57], v[158:161], v[216:219], v[54:57]
	v_mfma_f32_16x16x32_bf16 v[30:33], v[146:149], v[224:227], v[30:33]
	v_mfma_f32_16x16x32_bf16 v[22:25], v[158:161], v[224:227], v[22:25]
	v_mfma_f32_16x16x32_bf16 v[110:113], v[162:165], v[178:181], v[110:113]
	v_mfma_f32_16x16x32_bf16 v[102:105], v[170:173], v[178:181], v[102:105]
	v_mfma_f32_16x16x32_bf16 v[78:81], v[162:165], v[186:189], v[78:81]
	v_mfma_f32_16x16x32_bf16 v[70:73], v[170:173], v[186:189], v[70:73]
	v_mfma_f32_16x16x32_bf16 v[46:49], v[162:165], v[212:215], v[46:49]
	v_mfma_f32_16x16x32_bf16 v[38:41], v[170:173], v[212:215], v[38:41]
	v_mfma_f32_16x16x32_bf16 v[14:17], v[162:165], v[220:223], v[14:17]
	v_mfma_f32_16x16x32_bf16 v[6:9], v[170:173], v[220:223], v[6:9]
	v_mfma_f32_16x16x32_bf16 v[110:113], v[166:169], v[182:185], v[110:113]
	v_mfma_f32_16x16x32_bf16 v[102:105], v[174:177], v[182:185], v[102:105]
	v_mfma_f32_16x16x32_bf16 v[78:81], v[166:169], v[208:211], v[78:81]
	v_mfma_f32_16x16x32_bf16 v[70:73], v[174:177], v[208:211], v[70:73]
	v_mfma_f32_16x16x32_bf16 v[46:49], v[166:169], v[216:219], v[46:49]
	v_mfma_f32_16x16x32_bf16 v[38:41], v[174:177], v[216:219], v[38:41]
	v_mfma_f32_16x16x32_bf16 v[14:17], v[166:169], v[224:227], v[14:17]
	v_mfma_f32_16x16x32_bf16 v[6:9], v[174:177], v[224:227], v[6:9]
	s_barrier
	s_add_i32 s1, s1, s7
	v_lshl_add_u64 v[190:191], s[46:47], 0, v[134:135]
	s_mov_b32 m0, s1
	ds_read_b128 v[178:181], v153 offset:16384
	ds_read_b128 v[182:185], v153 offset:17408
	ds_read_b128 v[186:189], v153 offset:18432
	ds_read_b128 v[208:211], v153 offset:19456
	ds_read_b128 v[212:215], v153 offset:20480
	global_load_lds_dwordx4 v[190:191], off
	s_add_i32 m0, s1, 0x2000
	s_add_u32 s42, s46, 0x10000
	v_lshl_add_u64 v[228:229], s[46:47], 0, v[130:131]
	s_addc_u32 s43, s47, 0
	s_add_i32 s1, s22, s7
	global_load_lds_dwordx4 v[228:229], off
	v_lshl_add_u64 v[230:231], s[42:43], 0, v[134:135]
	s_mov_b32 m0, s1
	v_lshl_add_u64 v[232:233], s[48:49], 0, v[132:133]
	global_load_lds_dwordx4 v[230:231], off
	v_lshl_add_u64 v[230:231], s[42:43], 0, v[130:131]
	s_add_i32 m0, s1, 0x2000
	ds_read_b128 v[216:219], v153 offset:21504
	global_load_lds_dwordx4 v[230:231], off
	v_lshl_add_u64 v[230:231], s[48:49], 0, v[136:137]
	s_mov_b32 m0, s11
	ds_read_b128 v[220:223], v153 offset:22528
	global_load_lds_dwordx4 v[230:231], off
	s_mov_b32 m0, s12
	ds_read_b128 v[224:227], v153 offset:23552
	global_load_lds_dwordx4 v[232:233], off
	s_waitcnt vmcnt(8)
	s_waitcnt lgkmcnt(0)
	s_barrier
; #define PG8_STAGE(bufoff, gbase, voff) do { _Pragma("unroll") for (int _i = 0; _i < 2; ++_i) \
;         __builtin_amdgcn_global_load_lds((const unsigned*)((const char*)(gbase) + (voff)[_i]), (LAS unsigned*)(lds + (bufoff) + ldsw + _i * 8192), 16, 0, 0); } while (0)
; #define PG8_LDA(dst, b, h) do { _Pragma("unroll") for (int m = 0; m < 4; ++m) _Pragma("unroll") for (int k = 0; k < 2; ++k) dst[m][k] = *(const LAS bf16x8*)(lds + PG8_SA(b, h) + aoff + m * 2048 + k * 1024); } while (0)
; #define PG8_LDB(dst, b, h) do { _Pragma("unroll") for (int n = 0; n < 2; ++n) _Pragma("unroll") for (int k = 0; k < 2; ++k) dst[n][k] = *(const LAS bf16x8*)(lds + PG8_SB(b, h) + boff + n * 2048 + k * 1024); } while (0)
; #define PG8_MMA(ai, bj, At, Bt) do { __builtin_amdgcn_s_setprio(1); _Pragma("unroll") for (int m = 0; m < 4; ++m) _Pragma("unroll") for (int n = 0; n < 2; ++n) _Pragma("unroll") for (int k = 0; k < 2; ++k) \
;         acc[ai][bj][m][n] = __builtin_amdgcn_mfma_f32_16x16x32_bf16(Bt[n][k], At[m][k], acc[ai][bj][m][n], 0, 0, 0); __builtin_amdgcn_s_setprio(0); } while (0)
; #define PG8_WAIT_V(n) asm volatile("s_waitcnt vmcnt(" #n ")" ::: "memory")
; #define PG8_WAIT_L(n) asm volatile("s_waitcnt lgkmcnt(" #n ")" ::: "memory")
; #define PG8_BAR __builtin_amdgcn_s_barrier()
; #define PG8_SCHED __builtin_amdgcn_sched_barrier(0)
; template <class Epi, class Sched>
; __device__ __forceinline__ void gemm_phase(LAS unsigned char* lds, const Gemm g, const Sched& S, const Epi& E) {
;     ...
;             PG8_LDA(At, 0, 1); PG8_STAGE(PG8_SB(0, 0), b2, voffB); PG8_STAGE(PG8_SB(0, 1), b2 + hsB, voffB); PG8_STAGE(PG8_SA(0, 0), a2, voffA);
;             PG8_WAIT_V(8); PG8_WAIT_L(0); PG8_BAR; PG8_MMA(1, 0, At, B0); PG8_MMA(1, 1, At, B1); PG8_BAR; PG8_SCHED;
;             PG8_LDB(B0, 1, 0); PG8_LDB(B1, 1, 1); PG8_SCHED; PG8_LDA(At, 1, 0); PG8_STAGE(PG8_SA(0, 1), a2 + hsA, voffA);
;             PG8_WAIT_V(8); PG8_WAIT_L(0); PG8_BAR; PG8_MMA(0, 0, At, B0); PG8_MMA(0, 1, At, B1); PG8_BAR; PG8_SCHED;
	v_mfma_f32_16x16x32_bf16 v[122:125], v[142:145], v[178:181], v[122:125]
	v_mfma_f32_16x16x32_bf16 v[114:117], v[154:157], v[178:181], v[114:117]
	v_mfma_f32_16x16x32_bf16 v[90:93], v[142:145], v[186:189], v[90:93]
	v_mfma_f32_16x16x32_bf16 v[82:85], v[154:157], v[186:189], v[82:85]
	v_mfma_f32_16x16x32_bf16 v[58:61], v[142:145], v[212:215], v[58:61]
	v_mfma_f32_16x16x32_bf16 v[50:53], v[154:157], v[212:215], v[50:53]
	v_mfma_f32_16x16x32_bf16 v[26:29], v[142:145], v[220:223], v[26:29]
	v_mfma_f32_16x16x32_bf16 v[18:21], v[154:157], v[220:223], v[18:21]
	v_mfma_f32_16x16x32_bf16 v[122:125], v[146:149], v[182:185], v[122:125]
	v_mfma_f32_16x16x32_bf16 v[114:117], v[158:161], v[182:185], v[114:117]
	v_mfma_f32_16x16x32_bf16 v[90:93], v[146:149], v[208:211], v[90:93]
	v_mfma_f32_16x16x32_bf16 v[82:85], v[158:161], v[208:211], v[82:85]
	v_mfma_f32_16x16x32_bf16 v[58:61], v[146:149], v[216:219], v[58:61]
	v_mfma_f32_16x16x32_bf16 v[50:53], v[158:161], v[216:219], v[50:53]
	v_mfma_f32_16x16x32_bf16 v[26:29], v[146:149], v[224:227], v[26:29]
	v_mfma_f32_16x16x32_bf16 v[18:21], v[158:161], v[224:227], v[18:21]
	v_mfma_f32_16x16x32_bf16 v[106:109], v[162:165], v[178:181], v[106:109]
	v_mfma_f32_16x16x32_bf16 v[98:101], v[170:173], v[178:181], v[98:101]
	v_mfma_f32_16x16x32_bf16 v[74:77], v[162:165], v[186:189], v[74:77]
	v_mfma_f32_16x16x32_bf16 v[66:69], v[170:173], v[186:189], v[66:69]
	v_mfma_f32_16x16x32_bf16 v[42:45], v[162:165], v[212:215], v[42:45]
	v_mfma_f32_16x16x32_bf16 v[34:37], v[170:173], v[212:215], v[34:37]
	v_mfma_f32_16x16x32_bf16 v[10:13], v[162:165], v[220:223], v[10:13]
	v_mfma_f32_16x16x32_bf16 v[2:5], v[170:173], v[220:223], v[2:5]
	v_mfma_f32_16x16x32_bf16 v[106:109], v[166:169], v[182:185], v[106:109]
	v_mfma_f32_16x16x32_bf16 v[98:101], v[174:177], v[182:185], v[98:101]
	v_mfma_f32_16x16x32_bf16 v[74:77], v[166:169], v[208:211], v[74:77]
	v_mfma_f32_16x16x32_bf16 v[66:69], v[174:177], v[208:211], v[66:69]
	v_mfma_f32_16x16x32_bf16 v[42:45], v[166:169], v[216:219], v[42:45]
	v_mfma_f32_16x16x32_bf16 v[34:37], v[174:177], v[216:219], v[34:37]
	v_mfma_f32_16x16x32_bf16 v[10:13], v[166:169], v[224:227], v[10:13]
	v_mfma_f32_16x16x32_bf16 v[2:5], v[174:177], v[224:227], v[2:5]
	s_barrier
	s_add_i32 s1, 0, 0x18000
	v_add_u32_e32 v0, s1, v152
	s_add_i32 s22, 0, 0x1c000
	ds_read_b128 v[142:145], v0
	ds_read_b128 v[146:149], v0 offset:1024
	ds_read_b128 v[154:157], v0 offset:2048
	ds_read_b128 v[158:161], v0 offset:3072
	v_add_u32_e32 v0, s22, v152
	ds_read_b128 v[162:165], v0
	ds_read_b128 v[166:169], v0 offset:1024
	ds_read_b128 v[170:173], v0 offset:2048
	ds_read_b128 v[174:177], v0 offset:3072
	s_add_u32 s42, s48, 0x10000
	s_addc_u32 s43, s49, 0
	s_mov_b32 m0, s16
	v_lshl_add_u64 v[238:239], s[42:43], 0, v[136:137]
	ds_read_b128 v[178:181], v153 offset:32768
	ds_read_b128 v[182:185], v153 offset:33792
	ds_read_b128 v[186:189], v153 offset:34816
	ds_read_b128 v[208:211], v153 offset:35840
	ds_read_b128 v[212:215], v153 offset:36864
	ds_read_b128 v[216:219], v153 offset:37888
	ds_read_b128 v[220:223], v153 offset:38912
	global_load_lds_dwordx4 v[238:239], off
	v_lshl_add_u64 v[238:239], s[42:43], 0, v[132:133]
	s_mov_b32 m0, s24
	ds_read_b128 v[224:227], v153 offset:39936
	global_load_lds_dwordx4 v[238:239], off
	s_waitcnt vmcnt(8)
	s_waitcnt lgkmcnt(0)
	s_barrier
	v_mfma_f32_16x16x32_bf16 v[126:129], v[142:145], v[178:181], v[126:129]
	v_mfma_f32_16x16x32_bf16 v[118:121], v[154:157], v[178:181], v[118:121]
	v_mfma_f32_16x16x32_bf16 v[94:97], v[142:145], v[186:189], v[94:97]
	v_mfma_f32_16x16x32_bf16 v[86:89], v[154:157], v[186:189], v[86:89]
	v_mfma_f32_16x16x32_bf16 v[62:65], v[142:145], v[212:215], v[62:65]
	v_mfma_f32_16x16x32_bf16 v[54:57], v[154:157], v[212:215], v[54:57]
	v_mfma_f32_16x16x32_bf16 v[30:33], v[142:145], v[220:223], v[30:33]
	v_mfma_f32_16x16x32_bf16 v[22:25], v[154:157], v[220:223], v[22:25]
	v_mfma_f32_16x16x32_bf16 v[126:129], v[146:149], v[182:185], v[126:129]
	v_mfma_f32_16x16x32_bf16 v[118:121], v[158:161], v[182:185], v[118:121]
	v_mfma_f32_16x16x32_bf16 v[94:97], v[146:149], v[208:211], v[94:97]
	v_mfma_f32_16x16x32_bf16 v[86:89], v[158:161], v[208:211], v[86:89]
	v_mfma_f32_16x16x32_bf16 v[62:65], v[146:149], v[216:219], v[62:65]
	v_mfma_f32_16x16x32_bf16 v[54:57], v[158:161], v[216:219], v[54:57]
	v_mfma_f32_16x16x32_bf16 v[30:33], v[146:149], v[224:227], v[30:33]
	v_mfma_f32_16x16x32_bf16 v[22:25], v[158:161], v[224:227], v[22:25]
	v_mfma_f32_16x16x32_bf16 v[110:113], v[162:165], v[178:181], v[110:113]
	v_mfma_f32_16x16x32_bf16 v[102:105], v[170:173], v[178:181], v[102:105]
	v_mfma_f32_16x16x32_bf16 v[78:81], v[162:165], v[186:189], v[78:81]
	v_mfma_f32_16x16x32_bf16 v[70:73], v[170:173], v[186:189], v[70:73]
	v_mfma_f32_16x16x32_bf16 v[46:49], v[162:165], v[212:215], v[46:49]
	v_mfma_f32_16x16x32_bf16 v[38:41], v[170:173], v[212:215], v[38:41]
	v_mfma_f32_16x16x32_bf16 v[14:17], v[162:165], v[220:223], v[14:17]
	v_mfma_f32_16x16x32_bf16 v[6:9], v[170:173], v[220:223], v[6:9]
	v_mfma_f32_16x16x32_bf16 v[110:113], v[166:169], v[182:185], v[110:113]
	v_mfma_f32_16x16x32_bf16 v[102:105], v[174:177], v[182:185], v[102:105]
	v_mfma_f32_16x16x32_bf16 v[78:81], v[166:169], v[208:211], v[78:81]
	v_mfma_f32_16x16x32_bf16 v[70:73], v[174:177], v[208:211], v[70:73]
	v_mfma_f32_16x16x32_bf16 v[46:49], v[166:169], v[216:219], v[46:49]
	v_mfma_f32_16x16x32_bf16 v[38:41], v[174:177], v[216:219], v[38:41]
	v_mfma_f32_16x16x32_bf16 v[14:17], v[166:169], v[224:227], v[14:17]
	v_mfma_f32_16x16x32_bf16 v[6:9], v[174:177], v[224:227], v[6:9]
	s_barrier
; #define PG8_STAGE(bufoff, gbase, voff) do { _Pragma("unroll") for (int _i = 0; _i < 2; ++_i) \
;         __builtin_amdgcn_global_load_lds((const unsigned*)((const char*)(gbase) + (voff)[_i]), (LAS unsigned*)(lds + (bufoff) + ldsw + _i * 8192), 16, 0, 0); } while (0)
; #define PG8_LDA(dst, b, h) do { _Pragma("unroll") for (int m = 0; m < 4; ++m) _Pragma("unroll") for (int k = 0; k < 2; ++k) dst[m][k] = *(const LAS bf16x8*)(lds + PG8_SA(b, h) + aoff + m * 2048 + k * 1024); } while (0)
; #define PG8_MMA(ai, bj, At, Bt) do { __builtin_amdgcn_s_setprio(1); _Pragma("unroll") for (int m = 0; m < 4; ++m) _Pragma("unroll") for (int n = 0; n < 2; ++n) _Pragma("unroll") for (int k = 0; k < 2; ++k) \
;         acc[ai][bj][m][n] = __builtin_amdgcn_mfma_f32_16x16x32_bf16(Bt[n][k], At[m][k], acc[ai][bj][m][n], 0, 0, 0); __builtin_amdgcn_s_setprio(0); } while (0)
; #define PG8_WAIT_V(n) asm volatile("s_waitcnt vmcnt(" #n ")" ::: "memory")
; #define PG8_WAIT_L(n) asm volatile("s_waitcnt lgkmcnt(" #n ")" ::: "memory")
; #define PG8_BAR __builtin_amdgcn_s_barrier()
; #define PG8_SCHED __builtin_amdgcn_sched_barrier(0)
; template <class Epi, class Sched>
; __device__ __forceinline__ void gemm_phase(LAS unsigned char* lds, const Gemm g, const Sched& S, const Epi& E) {
;     ...
;             PG8_LDA(At, 1, 1); PG8_STAGE(PG8_SB(1, 0), b3, voffB); PG8_STAGE(PG8_SB(1, 1), b3 + hsB, voffB); PG8_STAGE(PG8_SA(1, 0), a3, voffA);
;             PG8_WAIT_V(8); PG8_WAIT_L(0); PG8_BAR; PG8_MMA(1, 0, At, B0); PG8_MMA(1, 1, At, B1); PG8_BAR; PG8_SCHED;
;         }
	s_add_i32 s1, s1, s7
	v_lshl_add_u64 v[190:191], v[190:191], 0, s[18:19]
	s_mov_b32 m0, s1
	ds_read_b128 v[178:181], v153 offset:49152
	ds_read_b128 v[182:185], v153 offset:50176
	ds_read_b128 v[186:189], v153 offset:51200
	ds_read_b128 v[208:211], v153 offset:52224
	global_load_lds_dwordx4 v[190:191], off
	s_add_i32 m0, s1, 0x2000
	s_add_u32 s42, s46, 0x10080
	v_lshl_add_u64 v[190:191], v[228:229], 0, s[18:19]
	s_addc_u32 s43, s47, 0
	s_add_i32 s1, s22, s7
	global_load_lds_dwordx4 v[190:191], off
	v_lshl_add_u64 v[190:191], s[42:43], 0, v[134:135]
	s_mov_b32 m0, s1
	ds_read_b128 v[212:215], v153 offset:53248
	global_load_lds_dwordx4 v[190:191], off
	v_lshl_add_u64 v[190:191], s[42:43], 0, v[130:131]
	s_add_i32 m0, s1, 0x2000
	ds_read_b128 v[216:219], v153 offset:54272
	global_load_lds_dwordx4 v[190:191], off
	v_lshl_add_u64 v[190:191], v[230:231], 0, s[18:19]
	s_mov_b32 m0, s51
	ds_read_b128 v[220:223], v153 offset:55296
	global_load_lds_dwordx4 v[190:191], off
	v_lshl_add_u64 v[190:191], v[232:233], 0, s[18:19]
	s_mov_b32 m0, s52
	ds_read_b128 v[224:227], v153 offset:56320
	global_load_lds_dwordx4 v[190:191], off
	s_waitcnt vmcnt(8)
	s_waitcnt lgkmcnt(0)
	s_barrier
	v_mfma_f32_16x16x32_bf16 v[122:125], v[142:145], v[178:181], v[122:125]
	v_mfma_f32_16x16x32_bf16 v[114:117], v[154:157], v[178:181], v[114:117]
	v_mfma_f32_16x16x32_bf16 v[90:93], v[142:145], v[186:189], v[90:93]
	v_mfma_f32_16x16x32_bf16 v[82:85], v[154:157], v[186:189], v[82:85]
	v_mfma_f32_16x16x32_bf16 v[58:61], v[142:145], v[212:215], v[58:61]
	v_mfma_f32_16x16x32_bf16 v[50:53], v[154:157], v[212:215], v[50:53]
	v_mfma_f32_16x16x32_bf16 v[26:29], v[142:145], v[220:223], v[26:29]
	v_mfma_f32_16x16x32_bf16 v[18:21], v[154:157], v[220:223], v[18:21]
	v_mfma_f32_16x16x32_bf16 v[122:125], v[146:149], v[182:185], v[122:125]
	v_mfma_f32_16x16x32_bf16 v[114:117], v[158:161], v[182:185], v[114:117]
	v_mfma_f32_16x16x32_bf16 v[90:93], v[146:149], v[208:211], v[90:93]
	v_mfma_f32_16x16x32_bf16 v[82:85], v[158:161], v[208:211], v[82:85]
	v_mfma_f32_16x16x32_bf16 v[58:61], v[146:149], v[216:219], v[58:61]
	v_mfma_f32_16x16x32_bf16 v[50:53], v[158:161], v[216:219], v[50:53]
	v_mfma_f32_16x16x32_bf16 v[26:29], v[146:149], v[224:227], v[26:29]
	v_mfma_f32_16x16x32_bf16 v[18:21], v[158:161], v[224:227], v[18:21]
	v_mfma_f32_16x16x32_bf16 v[106:109], v[162:165], v[178:181], v[106:109]
	v_mfma_f32_16x16x32_bf16 v[98:101], v[170:173], v[178:181], v[98:101]
	v_mfma_f32_16x16x32_bf16 v[74:77], v[162:165], v[186:189], v[74:77]
	v_mfma_f32_16x16x32_bf16 v[66:69], v[170:173], v[186:189], v[66:69]
	v_mfma_f32_16x16x32_bf16 v[42:45], v[162:165], v[212:215], v[42:45]
	v_mfma_f32_16x16x32_bf16 v[34:37], v[170:173], v[212:215], v[34:37]
	v_mfma_f32_16x16x32_bf16 v[10:13], v[162:165], v[220:223], v[10:13]
	v_mfma_f32_16x16x32_bf16 v[2:5], v[170:173], v[220:223], v[2:5]
	v_mfma_f32_16x16x32_bf16 v[106:109], v[166:169], v[182:185], v[106:109]
	v_mfma_f32_16x16x32_bf16 v[98:101], v[174:177], v[182:185], v[98:101]
	v_mfma_f32_16x16x32_bf16 v[74:77], v[166:169], v[208:211], v[74:77]
	v_mfma_f32_16x16x32_bf16 v[66:69], v[174:177], v[208:211], v[66:69]
	v_mfma_f32_16x16x32_bf16 v[42:45], v[166:169], v[216:219], v[42:45]
	v_mfma_f32_16x16x32_bf16 v[34:37], v[174:177], v[216:219], v[34:37]
	v_mfma_f32_16x16x32_bf16 v[10:13], v[166:169], v[224:227], v[10:13]
	v_mfma_f32_16x16x32_bf16 v[2:5], v[174:177], v[224:227], v[2:5]
	s_barrier
	s_cmp_ge_i32 s0, s26
	s_mov_b64 s[42:43], s[44:45]
	s_mov_b32 s46, s0
	s_cbranch_scc0 .LBB0_637
	s_setprio 0

; #define PG8_STAGE(bufoff, gbase, voff) do { _Pragma("unroll") for (int _i = 0; _i < 2; ++_i) \
;         __builtin_amdgcn_global_load_lds((const unsigned*)((const char*)(gbase) + (voff)[_i]), (LAS unsigned*)(lds + (bufoff) + ldsw + _i * 8192), 16, 0, 0); } while (0)
; #define PG8_LDA(dst, b, h) do { _Pragma("unroll") for (int m = 0; m < 4; ++m) _Pragma("unroll") for (int k = 0; k < 2; ++k) dst[m][k] = *(const LAS bf16x8*)(lds + PG8_SA(b, h) + aoff + m * 2048 + k * 1024); } while (0)
; #define PG8_LDB(dst, b, h) do { _Pragma("unroll") for (int n = 0; n < 2; ++n) _Pragma("unroll") for (int k = 0; k < 2; ++k) dst[n][k] = *(const LAS bf16x8*)(lds + PG8_SB(b, h) + boff + n * 2048 + k * 1024); } while (0)
; #define PG8_MMA(ai, bj, At, Bt) do { __builtin_amdgcn_s_setprio(1); _Pragma("unroll") for (int m = 0; m < 4; ++m) _Pragma("unroll") for (int n = 0; n < 2; ++n) _Pragma("unroll") for (int k = 0; k < 2; ++k) \
;         acc[ai][bj][m][n] = __builtin_amdgcn_mfma_f32_16x16x32_bf16(Bt[n][k], At[m][k], acc[ai][bj][m][n], 0, 0, 0); __builtin_amdgcn_s_setprio(0); } while (0)
; #define PG8_WAIT_V(n) asm volatile("s_waitcnt vmcnt(" #n ")" ::: "memory")
; #define PG8_BAR __builtin_amdgcn_s_barrier()
; template <class Epi, class Sched>
; __device__ __forceinline__ void gemm_phase(LAS unsigned char* lds, const Gemm g, const Sched& S, const Epi& E) {
;     ...
;         for (int t = 0; t < nt; t += 2) {
;             const bool last = (t == nt - 2);
;             const char* a1 = cA + (size_t)(t + 1) * kstep;
;             const char* a2 = last ? nA : cA + (size_t)(t + 2) * kstep; const char* b2 = last ? nB : cB + (size_t)(t + 2) * kstep;
;             const char* a3 = a2 + kstep; const char* b3 = b2 + kstep;
;             if constexpr (Epi::MIDK) { if (t == (nt >> 1)) { int fr_ = fr, fq_ = fq; asm volatile("" : "+v"(fr_), "+v"(fq_)); E.mid(acc, cur, wr, wc, fr_, fq_); } }
;             PG8_LDB(B0, 0, 0); PG8_LDB(B1, 0, 1); PG8_SCHED; PG8_LDA(At, 0, 0); PG8_STAGE(PG8_SA(1, 1), a1 + hsA, voffA);
;             PG8_WAIT_V(8); PG8_WAIT_L(0); PG8_BAR; PG8_MMA(0, 0, At, B0); PG8_MMA(0, 1, At, B1); PG8_BAR; PG8_SCHED;
;             PG8_LDA(At, 0, 1); PG8_STAGE(PG8_SB(0, 0), b2, voffB); PG8_STAGE(PG8_SB(0, 1), b2 + hsB, voffB); PG8_STAGE(PG8_SA(0, 0), a2, voffA);
;             PG8_WAIT_V(8); PG8_WAIT_L(0); PG8_BAR; PG8_MMA(1, 0, At, B0); PG8_MMA(1, 1, At, B1); PG8_BAR; PG8_SCHED;
.Lnp_660:
.LBB0_660:
	s_add_i32 s0, s40, 2
	s_add_u32 s1, s36, 0xfffc0080
	s_addc_u32 s41, s37, -1
	s_add_i32 s74, 0, 0x10000
	s_cmp_eq_u32 s11, s40
	s_cselect_b32 s85, s47, s41
	s_cselect_b32 s84, s49, s1
	s_cselect_b32 s41, s83, s96
	s_cselect_b32 s40, vcc_lo, vcc_hi
	s_add_i32 s1, 0, 0x14000
	v_add_u32_e32 v154, s74, v165
	v_add_u32_e32 v162, s1, v165
	ds_read_b128 v[142:145], v154
	ds_read_b128 v[146:149], v154 offset:1024
	ds_read_b128 v[150:153], v154 offset:2048
	ds_read_b128 v[154:157], v154 offset:3072
	ds_read_b128 v[158:161], v162
	ds_read_b128 v[168:171], v162 offset:1024
	ds_read_b128 v[172:175], v162 offset:2048
	ds_read_b128 v[176:179], v162 offset:3072
	v_lshl_add_u64 v[228:229], s[36:37], 0, v[138:139]
	s_add_i32 m0, s16, 0xc000
	ds_read_b128 v[180:183], v166
	ds_read_b128 v[184:187], v166 offset:1024
	ds_read_b128 v[188:191], v166 offset:2048
	ds_read_b128 v[208:211], v166 offset:3072
	ds_read_b128 v[212:215], v166 offset:4096
	ds_read_b128 v[216:219], v166 offset:5120
	ds_read_b128 v[220:223], v166 offset:6144
	global_load_lds_dwordx4 v[228:229], off
	v_lshl_add_u64 v[228:229], s[36:37], 0, v[140:141]
	s_add_i32 m0, s16, 0xe000
	ds_read_b128 v[224:227], v166 offset:7168
	global_load_lds_dwordx4 v[228:229], off
	s_waitcnt vmcnt(8)
	s_waitcnt lgkmcnt(0)
	s_barrier
	v_mfma_f32_16x16x32_bf16 v[122:125], v[142:145], v[180:183], v[122:125]
	v_mfma_f32_16x16x32_bf16 v[114:117], v[150:153], v[180:183], v[114:117]
	v_mfma_f32_16x16x32_bf16 v[110:113], v[142:145], v[188:191], v[110:113]
	v_mfma_f32_16x16x32_bf16 v[98:101], v[150:153], v[188:191], v[98:101]
	v_mfma_f32_16x16x32_bf16 v[94:97], v[142:145], v[212:215], v[94:97]
	v_mfma_f32_16x16x32_bf16 v[82:85], v[150:153], v[212:215], v[82:85]
	v_mfma_f32_16x16x32_bf16 v[78:81], v[142:145], v[220:223], v[78:81]
	v_mfma_f32_16x16x32_bf16 v[66:69], v[150:153], v[220:223], v[66:69]
	v_mfma_f32_16x16x32_bf16 v[122:125], v[146:149], v[184:187], v[122:125]
	v_mfma_f32_16x16x32_bf16 v[114:117], v[154:157], v[184:187], v[114:117]
	v_mfma_f32_16x16x32_bf16 v[110:113], v[146:149], v[208:211], v[110:113]
	v_mfma_f32_16x16x32_bf16 v[98:101], v[154:157], v[208:211], v[98:101]
	v_mfma_f32_16x16x32_bf16 v[94:97], v[146:149], v[216:219], v[94:97]
	v_mfma_f32_16x16x32_bf16 v[82:85], v[154:157], v[216:219], v[82:85]
	v_mfma_f32_16x16x32_bf16 v[78:81], v[146:149], v[224:227], v[78:81]
	v_mfma_f32_16x16x32_bf16 v[66:69], v[154:157], v[224:227], v[66:69]
	v_mfma_f32_16x16x32_bf16 v[126:129], v[158:161], v[180:183], v[126:129]
	v_mfma_f32_16x16x32_bf16 v[118:121], v[172:175], v[180:183], v[118:121]
	v_mfma_f32_16x16x32_bf16 v[106:109], v[158:161], v[188:191], v[106:109]
	v_mfma_f32_16x16x32_bf16 v[102:105], v[172:175], v[188:191], v[102:105]
	v_mfma_f32_16x16x32_bf16 v[90:93], v[158:161], v[212:215], v[90:93]
	v_mfma_f32_16x16x32_bf16 v[86:89], v[172:175], v[212:215], v[86:89]
	v_mfma_f32_16x16x32_bf16 v[74:77], v[158:161], v[220:223], v[74:77]
	v_mfma_f32_16x16x32_bf16 v[70:73], v[172:175], v[220:223], v[70:73]
	v_mfma_f32_16x16x32_bf16 v[126:129], v[168:171], v[184:187], v[126:129]
	v_mfma_f32_16x16x32_bf16 v[118:121], v[176:179], v[184:187], v[118:121]
	v_mfma_f32_16x16x32_bf16 v[106:109], v[168:171], v[208:211], v[106:109]
	v_mfma_f32_16x16x32_bf16 v[102:105], v[176:179], v[208:211], v[102:105]
	v_mfma_f32_16x16x32_bf16 v[90:93], v[168:171], v[216:219], v[90:93]
	v_mfma_f32_16x16x32_bf16 v[86:89], v[176:179], v[216:219], v[86:89]
	v_mfma_f32_16x16x32_bf16 v[74:77], v[168:171], v[224:227], v[74:77]
	v_mfma_f32_16x16x32_bf16 v[70:73], v[176:179], v[224:227], v[70:73]
	s_barrier
	s_add_i32 s74, s74, s12
	v_lshl_add_u64 v[228:229], s[40:41], 0, v[0:1]
	s_mov_b32 m0, s74
	ds_read_b128 v[180:183], v166 offset:16384
	ds_read_b128 v[184:187], v166 offset:17408
	ds_read_b128 v[188:191], v166 offset:18432
	ds_read_b128 v[208:211], v166 offset:19456
	ds_read_b128 v[212:215], v166 offset:20480
	global_load_lds_dwordx4 v[228:229], off
	s_add_i32 m0, s74, 0x2000
	s_add_u32 s74, s40, 0x40000
	v_lshl_add_u64 v[230:231], s[40:41], 0, v[130:131]
	s_addc_u32 s75, s41, 0
	s_add_i32 s1, s1, s12
	global_load_lds_dwordx4 v[230:231], off
	v_lshl_add_u64 v[232:233], s[74:75], 0, v[0:1]
	s_mov_b32 m0, s1
	v_lshl_add_u64 v[238:239], s[84:85], 0, v[132:133]
	global_load_lds_dwordx4 v[232:233], off
	v_lshl_add_u64 v[232:233], s[74:75], 0, v[130:131]
	s_add_i32 m0, s1, 0x2000
	ds_read_b128 v[216:219], v166 offset:21504
	global_load_lds_dwordx4 v[232:233], off
	v_lshl_add_u64 v[232:233], s[84:85], 0, v[134:135]
	s_mov_b32 m0, s16
	ds_read_b128 v[220:223], v166 offset:22528
	global_load_lds_dwordx4 v[232:233], off
	s_mov_b32 m0, s52
	ds_read_b128 v[224:227], v166 offset:23552
	global_load_lds_dwordx4 v[238:239], off
	s_waitcnt vmcnt(8)
	s_waitcnt lgkmcnt(0)
	s_barrier
; #define PG8_STAGE(bufoff, gbase, voff) do { _Pragma("unroll") for (int _i = 0; _i < 2; ++_i) \
;         __builtin_amdgcn_global_load_lds((const unsigned*)((const char*)(gbase) + (voff)[_i]), (LAS unsigned*)(lds + (bufoff) + ldsw + _i * 8192), 16, 0, 0); } while (0)
; #define PG8_LDA(dst, b, h) do { _Pragma("unroll") for (int m = 0; m < 4; ++m) _Pragma("unroll") for (int k = 0; k < 2; ++k) dst[m][k] = *(const LAS bf16x8*)(lds + PG8_SA(b, h) + aoff + m * 2048 + k * 1024); } while (0)
; #define PG8_LDB(dst, b, h) do { _Pragma("unroll") for (int n = 0; n < 2; ++n) _Pragma("unroll") for (int k = 0; k < 2; ++k) dst[n][k] = *(const LAS bf16x8*)(lds + PG8_SB(b, h) + boff + n * 2048 + k * 1024); } while (0)
; #define PG8_MMA(ai, bj, At, Bt) do { __builtin_amdgcn_s_setprio(1); _Pragma("unroll") for (int m = 0; m < 4; ++m) _Pragma("unroll") for (int n = 0; n < 2; ++n) _Pragma("unroll") for (int k = 0; k < 2; ++k) \
;         acc[ai][bj][m][n] = __builtin_amdgcn_mfma_f32_16x16x32_bf16(Bt[n][k], At[m][k], acc[ai][bj][m][n], 0, 0, 0); __builtin_amdgcn_s_setprio(0); } while (0)
; #define PG8_WAIT_V(n) asm volatile("s_waitcnt vmcnt(" #n ")" ::: "memory")
; #define PG8_WAIT_L(n) asm volatile("s_waitcnt lgkmcnt(" #n ")" ::: "memory")
; #define PG8_BAR __builtin_amdgcn_s_barrier()
; #define PG8_SCHED __builtin_amdgcn_sched_barrier(0)
; template <class Epi, class Sched>
; __device__ __forceinline__ void gemm_phase(LAS unsigned char* lds, const Gemm g, const Sched& S, const Epi& E) {
;     ...
;             PG8_LDA(At, 0, 1); PG8_STAGE(PG8_SB(0, 0), b2, voffB); PG8_STAGE(PG8_SB(0, 1), b2 + hsB, voffB); PG8_STAGE(PG8_SA(0, 0), a2, voffA);
;             PG8_WAIT_V(8); PG8_WAIT_L(0); PG8_BAR; PG8_MMA(1, 0, At, B0); PG8_MMA(1, 1, At, B1); PG8_BAR; PG8_SCHED;
;             PG8_LDB(B0, 1, 0); PG8_LDB(B1, 1, 1); PG8_SCHED; PG8_LDA(At, 1, 0); PG8_STAGE(PG8_SA(0, 1), a2 + hsA, voffA);
;             PG8_WAIT_V(8); PG8_WAIT_L(0); PG8_BAR; PG8_MMA(0, 0, At, B0); PG8_MMA(0, 1, At, B1); PG8_BAR; PG8_SCHED;
	v_mfma_f32_16x16x32_bf16 v[62:65], v[142:145], v[180:183], v[62:65]
	v_mfma_f32_16x16x32_bf16 v[50:53], v[150:153], v[180:183], v[50:53]
	v_mfma_f32_16x16x32_bf16 v[46:49], v[142:145], v[188:191], v[46:49]
	v_mfma_f32_16x16x32_bf16 v[34:37], v[150:153], v[188:191], v[34:37]
	v_mfma_f32_16x16x32_bf16 v[30:33], v[142:145], v[212:215], v[30:33]
	v_mfma_f32_16x16x32_bf16 v[18:21], v[150:153], v[212:215], v[18:21]
	v_mfma_f32_16x16x32_bf16 v[10:13], v[142:145], v[220:223], v[10:13]
	v_mfma_f32_16x16x32_bf16 v[2:5], v[150:153], v[220:223], v[2:5]
	v_mfma_f32_16x16x32_bf16 v[62:65], v[146:149], v[184:187], v[62:65]
	v_mfma_f32_16x16x32_bf16 v[50:53], v[154:157], v[184:187], v[50:53]
	v_mfma_f32_16x16x32_bf16 v[46:49], v[146:149], v[208:211], v[46:49]
	v_mfma_f32_16x16x32_bf16 v[34:37], v[154:157], v[208:211], v[34:37]
	v_mfma_f32_16x16x32_bf16 v[30:33], v[146:149], v[216:219], v[30:33]
	v_mfma_f32_16x16x32_bf16 v[18:21], v[154:157], v[216:219], v[18:21]
	v_mfma_f32_16x16x32_bf16 v[10:13], v[146:149], v[224:227], v[10:13]
	v_mfma_f32_16x16x32_bf16 v[2:5], v[154:157], v[224:227], v[2:5]
	v_mfma_f32_16x16x32_bf16 v[58:61], v[158:161], v[180:183], v[58:61]
	v_mfma_f32_16x16x32_bf16 v[54:57], v[172:175], v[180:183], v[54:57]
	v_mfma_f32_16x16x32_bf16 v[42:45], v[158:161], v[188:191], v[42:45]
	v_mfma_f32_16x16x32_bf16 v[38:41], v[172:175], v[188:191], v[38:41]
	v_mfma_f32_16x16x32_bf16 v[26:29], v[158:161], v[212:215], v[26:29]
	v_mfma_f32_16x16x32_bf16 v[22:25], v[172:175], v[212:215], v[22:25]
	v_mfma_f32_16x16x32_bf16 v[14:17], v[158:161], v[220:223], v[14:17]
	v_mfma_f32_16x16x32_bf16 v[6:9], v[172:175], v[220:223], v[6:9]
	v_mfma_f32_16x16x32_bf16 v[58:61], v[168:171], v[184:187], v[58:61]
	v_mfma_f32_16x16x32_bf16 v[54:57], v[176:179], v[184:187], v[54:57]
	v_mfma_f32_16x16x32_bf16 v[42:45], v[168:171], v[208:211], v[42:45]
	v_mfma_f32_16x16x32_bf16 v[38:41], v[176:179], v[208:211], v[38:41]
	v_mfma_f32_16x16x32_bf16 v[26:29], v[168:171], v[216:219], v[26:29]
	v_mfma_f32_16x16x32_bf16 v[22:25], v[176:179], v[216:219], v[22:25]
	v_mfma_f32_16x16x32_bf16 v[14:17], v[168:171], v[224:227], v[14:17]
	v_mfma_f32_16x16x32_bf16 v[6:9], v[176:179], v[224:227], v[6:9]
	s_barrier
	s_add_i32 s1, 0, 0x18000
	s_add_i32 s22, 0, 0x1c000
	v_add_u32_e32 v154, s1, v165
	v_add_u32_e32 v162, s22, v165
	ds_read_b128 v[142:145], v154
	ds_read_b128 v[146:149], v154 offset:1024
	ds_read_b128 v[150:153], v154 offset:2048
	ds_read_b128 v[154:157], v154 offset:3072
	ds_read_b128 v[158:161], v162
	ds_read_b128 v[168:171], v162 offset:1024
	ds_read_b128 v[172:175], v162 offset:2048
	ds_read_b128 v[176:179], v162 offset:3072
	s_add_u32 s74, s84, 0x40000
	s_addc_u32 s75, s85, 0
	s_mov_b32 m0, s64
	v_lshl_add_u64 v[240:241], s[74:75], 0, v[134:135]
	ds_read_b128 v[180:183], v166 offset:32768
	ds_read_b128 v[184:187], v166 offset:33792
	ds_read_b128 v[188:191], v166 offset:34816
	ds_read_b128 v[208:211], v166 offset:35840
	ds_read_b128 v[212:215], v166 offset:36864
	ds_read_b128 v[216:219], v166 offset:37888
	ds_read_b128 v[220:223], v166 offset:38912
	global_load_lds_dwordx4 v[240:241], off
	v_lshl_add_u64 v[240:241], s[74:75], 0, v[132:133]
	s_mov_b32 m0, s78
	ds_read_b128 v[224:227], v166 offset:39936
	global_load_lds_dwordx4 v[240:241], off
	s_waitcnt vmcnt(8)
	s_waitcnt lgkmcnt(0)
	s_barrier
	v_mfma_f32_16x16x32_bf16 v[122:125], v[142:145], v[180:183], v[122:125]
	v_mfma_f32_16x16x32_bf16 v[114:117], v[150:153], v[180:183], v[114:117]
	v_mfma_f32_16x16x32_bf16 v[110:113], v[142:145], v[188:191], v[110:113]
	v_mfma_f32_16x16x32_bf16 v[98:101], v[150:153], v[188:191], v[98:101]
	v_mfma_f32_16x16x32_bf16 v[94:97], v[142:145], v[212:215], v[94:97]
	v_mfma_f32_16x16x32_bf16 v[82:85], v[150:153], v[212:215], v[82:85]
	v_mfma_f32_16x16x32_bf16 v[78:81], v[142:145], v[220:223], v[78:81]
	v_mfma_f32_16x16x32_bf16 v[66:69], v[150:153], v[220:223], v[66:69]
	v_mfma_f32_16x16x32_bf16 v[122:125], v[146:149], v[184:187], v[122:125]
	v_mfma_f32_16x16x32_bf16 v[114:117], v[154:157], v[184:187], v[114:117]
	v_mfma_f32_16x16x32_bf16 v[110:113], v[146:149], v[208:211], v[110:113]
	v_mfma_f32_16x16x32_bf16 v[98:101], v[154:157], v[208:211], v[98:101]
	v_mfma_f32_16x16x32_bf16 v[94:97], v[146:149], v[216:219], v[94:97]
	v_mfma_f32_16x16x32_bf16 v[82:85], v[154:157], v[216:219], v[82:85]
	v_mfma_f32_16x16x32_bf16 v[78:81], v[146:149], v[224:227], v[78:81]
	v_mfma_f32_16x16x32_bf16 v[66:69], v[154:157], v[224:227], v[66:69]
	v_mfma_f32_16x16x32_bf16 v[126:129], v[158:161], v[180:183], v[126:129]
	v_mfma_f32_16x16x32_bf16 v[118:121], v[172:175], v[180:183], v[118:121]
	v_mfma_f32_16x16x32_bf16 v[106:109], v[158:161], v[188:191], v[106:109]
	v_mfma_f32_16x16x32_bf16 v[102:105], v[172:175], v[188:191], v[102:105]
	v_mfma_f32_16x16x32_bf16 v[90:93], v[158:161], v[212:215], v[90:93]
	v_mfma_f32_16x16x32_bf16 v[86:89], v[172:175], v[212:215], v[86:89]
	v_mfma_f32_16x16x32_bf16 v[74:77], v[158:161], v[220:223], v[74:77]
	v_mfma_f32_16x16x32_bf16 v[70:73], v[172:175], v[220:223], v[70:73]
	v_mfma_f32_16x16x32_bf16 v[126:129], v[168:171], v[184:187], v[126:129]
	v_mfma_f32_16x16x32_bf16 v[118:121], v[176:179], v[184:187], v[118:121]
	v_mfma_f32_16x16x32_bf16 v[106:109], v[168:171], v[208:211], v[106:109]
	v_mfma_f32_16x16x32_bf16 v[102:105], v[176:179], v[208:211], v[102:105]
	v_mfma_f32_16x16x32_bf16 v[90:93], v[168:171], v[216:219], v[90:93]
	v_mfma_f32_16x16x32_bf16 v[86:89], v[176:179], v[216:219], v[86:89]
	v_mfma_f32_16x16x32_bf16 v[74:77], v[168:171], v[224:227], v[74:77]
	v_mfma_f32_16x16x32_bf16 v[70:73], v[176:179], v[224:227], v[70:73]
	s_barrier
; #define PG8_STAGE(bufoff, gbase, voff) do { _Pragma("unroll") for (int _i = 0; _i < 2; ++_i) \
;         __builtin_amdgcn_global_load_lds((const unsigned*)((const char*)(gbase) + (voff)[_i]), (LAS unsigned*)(lds + (bufoff) + ldsw + _i * 8192), 16, 0, 0); } while (0)
; #define PG8_LDA(dst, b, h) do { _Pragma("unroll") for (int m = 0; m < 4; ++m) _Pragma("unroll") for (int k = 0; k < 2; ++k) dst[m][k] = *(const LAS bf16x8*)(lds + PG8_SA(b, h) + aoff + m * 2048 + k * 1024); } while (0)
; #define PG8_MMA(ai, bj, At, Bt) do { __builtin_amdgcn_s_setprio(1); _Pragma("unroll") for (int m = 0; m < 4; ++m) _Pragma("unroll") for (int n = 0; n < 2; ++n) _Pragma("unroll") for (int k = 0; k < 2; ++k) \
;         acc[ai][bj][m][n] = __builtin_amdgcn_mfma_f32_16x16x32_bf16(Bt[n][k], At[m][k], acc[ai][bj][m][n], 0, 0, 0); __builtin_amdgcn_s_setprio(0); } while (0)
; #define PG8_WAIT_V(n) asm volatile("s_waitcnt vmcnt(" #n ")" ::: "memory")
; #define PG8_WAIT_L(n) asm volatile("s_waitcnt lgkmcnt(" #n ")" ::: "memory")
; #define PG8_BAR __builtin_amdgcn_s_barrier()
; #define PG8_SCHED __builtin_amdgcn_sched_barrier(0)
; template <class Epi, class Sched>
; __device__ __forceinline__ void gemm_phase(LAS unsigned char* lds, const Gemm g, const Sched& S, const Epi& E) {
;     ...
;             PG8_LDA(At, 1, 1); PG8_STAGE(PG8_SB(1, 0), b3, voffB); PG8_STAGE(PG8_SB(1, 1), b3 + hsB, voffB); PG8_STAGE(PG8_SA(1, 0), a3, voffA);
;             PG8_WAIT_V(8); PG8_WAIT_L(0); PG8_BAR; PG8_MMA(1, 0, At, B0); PG8_MMA(1, 1, At, B1); PG8_BAR; PG8_SCHED;
;         }
	s_add_i32 s1, s1, s12
	v_lshl_add_u64 v[228:229], v[228:229], 0, s[18:19]
	s_mov_b32 m0, s1
	ds_read_b128 v[180:183], v166 offset:49152
	ds_read_b128 v[184:187], v166 offset:50176
	ds_read_b128 v[188:191], v166 offset:51200
	ds_read_b128 v[208:211], v166 offset:52224
	global_load_lds_dwordx4 v[228:229], off
	s_add_i32 m0, s1, 0x2000
	s_add_u32 s40, s40, 0x40080
	v_lshl_add_u64 v[228:229], v[230:231], 0, s[18:19]
	s_addc_u32 s41, s41, 0
	s_add_i32 s1, s22, s12
	global_load_lds_dwordx4 v[228:229], off
	v_lshl_add_u64 v[228:229], s[40:41], 0, v[0:1]
	s_mov_b32 m0, s1
	ds_read_b128 v[212:215], v166 offset:53248
	global_load_lds_dwordx4 v[228:229], off
	v_lshl_add_u64 v[228:229], s[40:41], 0, v[130:131]
	s_add_i32 m0, s1, 0x2000
	ds_read_b128 v[216:219], v166 offset:54272
	global_load_lds_dwordx4 v[228:229], off
	v_lshl_add_u64 v[228:229], v[232:233], 0, s[18:19]
	s_mov_b32 m0, s26
	ds_read_b128 v[220:223], v166 offset:55296
	global_load_lds_dwordx4 v[228:229], off
	v_lshl_add_u64 v[228:229], v[238:239], 0, s[18:19]
	s_mov_b32 m0, s57
	ds_read_b128 v[224:227], v166 offset:56320
	global_load_lds_dwordx4 v[228:229], off
	s_waitcnt vmcnt(8)
	s_waitcnt lgkmcnt(0)
	s_barrier
	v_mfma_f32_16x16x32_bf16 v[62:65], v[142:145], v[180:183], v[62:65]
	v_mfma_f32_16x16x32_bf16 v[50:53], v[150:153], v[180:183], v[50:53]
	v_mfma_f32_16x16x32_bf16 v[46:49], v[142:145], v[188:191], v[46:49]
	v_mfma_f32_16x16x32_bf16 v[34:37], v[150:153], v[188:191], v[34:37]
	v_mfma_f32_16x16x32_bf16 v[30:33], v[142:145], v[212:215], v[30:33]
	v_mfma_f32_16x16x32_bf16 v[18:21], v[150:153], v[212:215], v[18:21]
	v_mfma_f32_16x16x32_bf16 v[10:13], v[142:145], v[220:223], v[10:13]
	v_mfma_f32_16x16x32_bf16 v[2:5], v[150:153], v[220:223], v[2:5]
	v_mfma_f32_16x16x32_bf16 v[62:65], v[146:149], v[184:187], v[62:65]
	v_mfma_f32_16x16x32_bf16 v[50:53], v[154:157], v[184:187], v[50:53]
	v_mfma_f32_16x16x32_bf16 v[46:49], v[146:149], v[208:211], v[46:49]
	v_mfma_f32_16x16x32_bf16 v[34:37], v[154:157], v[208:211], v[34:37]
	v_mfma_f32_16x16x32_bf16 v[30:33], v[146:149], v[216:219], v[30:33]
	v_mfma_f32_16x16x32_bf16 v[18:21], v[154:157], v[216:219], v[18:21]
	v_mfma_f32_16x16x32_bf16 v[10:13], v[146:149], v[224:227], v[10:13]
	v_mfma_f32_16x16x32_bf16 v[2:5], v[154:157], v[224:227], v[2:5]
	v_mfma_f32_16x16x32_bf16 v[58:61], v[158:161], v[180:183], v[58:61]
	v_mfma_f32_16x16x32_bf16 v[54:57], v[172:175], v[180:183], v[54:57]
	v_mfma_f32_16x16x32_bf16 v[42:45], v[158:161], v[188:191], v[42:45]
	v_mfma_f32_16x16x32_bf16 v[38:41], v[172:175], v[188:191], v[38:41]
	v_mfma_f32_16x16x32_bf16 v[26:29], v[158:161], v[212:215], v[26:29]
	v_mfma_f32_16x16x32_bf16 v[22:25], v[172:175], v[212:215], v[22:25]
	v_mfma_f32_16x16x32_bf16 v[14:17], v[158:161], v[220:223], v[14:17]
	v_mfma_f32_16x16x32_bf16 v[6:9], v[172:175], v[220:223], v[6:9]
	v_mfma_f32_16x16x32_bf16 v[58:61], v[168:171], v[184:187], v[58:61]
	v_mfma_f32_16x16x32_bf16 v[54:57], v[176:179], v[184:187], v[54:57]
	v_mfma_f32_16x16x32_bf16 v[42:45], v[168:171], v[208:211], v[42:45]
	v_mfma_f32_16x16x32_bf16 v[38:41], v[176:179], v[208:211], v[38:41]
	v_mfma_f32_16x16x32_bf16 v[26:29], v[168:171], v[216:219], v[26:29]
	v_mfma_f32_16x16x32_bf16 v[22:25], v[176:179], v[216:219], v[22:25]
	v_mfma_f32_16x16x32_bf16 v[14:17], v[168:171], v[224:227], v[14:17]
	v_mfma_f32_16x16x32_bf16 v[6:9], v[176:179], v[224:227], v[6:9]
	s_barrier
	s_add_u32 s36, s36, 0x100
	s_addc_u32 s37, s37, 0
	s_add_u32 vcc_hi, vcc_hi, 0x100
	s_addc_u32 s96, s96, 0
	s_cmp_ge_i32 s0, s56
	s_mov_b32 s40, s0
	s_cbranch_scc0 .LBB0_660
	s_setprio 0
	v_readlane_b32 s96, v250, 43

; #define PG8_STAGE(bufoff, gbase, voff) do { _Pragma("unroll") for (int _i = 0; _i < 2; ++_i) \
;         __builtin_amdgcn_global_load_lds((const unsigned*)((const char*)(gbase) + (voff)[_i]), (LAS unsigned*)(lds + (bufoff) + ldsw + _i * 8192), 16, 0, 0); } while (0)
; #define PG8_LDA(dst, b, h) do { _Pragma("unroll") for (int m = 0; m < 4; ++m) _Pragma("unroll") for (int k = 0; k < 2; ++k) dst[m][k] = *(const LAS bf16x8*)(lds + PG8_SA(b, h) + aoff + m * 2048 + k * 1024); } while (0)
; #define PG8_LDB(dst, b, h) do { _Pragma("unroll") for (int n = 0; n < 2; ++n) _Pragma("unroll") for (int k = 0; k < 2; ++k) dst[n][k] = *(const LAS bf16x8*)(lds + PG8_SB(b, h) + boff + n * 2048 + k * 1024); } while (0)
; #define PG8_MMA(ai, bj, At, Bt) do { __builtin_amdgcn_s_setprio(1); _Pragma("unroll") for (int m = 0; m < 4; ++m) _Pragma("unroll") for (int n = 0; n < 2; ++n) _Pragma("unroll") for (int k = 0; k < 2; ++k) \
;         acc[ai][bj][m][n] = __builtin_amdgcn_mfma_f32_16x16x32_bf16(Bt[n][k], At[m][k], acc[ai][bj][m][n], 0, 0, 0); __builtin_amdgcn_s_setprio(0); } while (0)
; #define PG8_WAIT_V(n) asm volatile("s_waitcnt vmcnt(" #n ")" ::: "memory")
; #define PG8_BAR __builtin_amdgcn_s_barrier()
; template <class Epi, class Sched>
; __device__ __forceinline__ void gemm_phase(LAS unsigned char* lds, const Gemm g, const Sched& S, const Epi& E) {
;     ...
;         for (int t = 0; t < nt; t += 2) {
;             const bool last = (t == nt - 2);
;             const char* a1 = cA + (size_t)(t + 1) * kstep;
;             const char* a2 = last ? nA : cA + (size_t)(t + 2) * kstep; const char* b2 = last ? nB : cB + (size_t)(t + 2) * kstep;
;             const char* a3 = a2 + kstep; const char* b3 = b2 + kstep;
;             if constexpr (Epi::MIDK) { if (t == (nt >> 1)) { int fr_ = fr, fq_ = fq; asm volatile("" : "+v"(fr_), "+v"(fq_)); E.mid(acc, cur, wr, wc, fr_, fq_); } }
;             PG8_LDB(B0, 0, 0); PG8_LDB(B1, 0, 1); PG8_SCHED; PG8_LDA(At, 0, 0); PG8_STAGE(PG8_SA(1, 1), a1 + hsA, voffA);
;             PG8_WAIT_V(8); PG8_WAIT_L(0); PG8_BAR; PG8_MMA(0, 0, At, B0); PG8_MMA(0, 1, At, B1); PG8_BAR; PG8_SCHED;
;             PG8_LDA(At, 0, 1); PG8_STAGE(PG8_SB(0, 0), b2, voffB); PG8_STAGE(PG8_SB(0, 1), b2 + hsB, voffB); PG8_STAGE(PG8_SA(0, 0), a2, voffA);
;             PG8_WAIT_V(8); PG8_WAIT_L(0); PG8_BAR; PG8_MMA(1, 0, At, B0); PG8_MMA(1, 1, At, B1); PG8_BAR; PG8_SCHED;
.Lnp_763:
.LBB0_763:
	s_add_i32 s73, s46, 2
	s_add_u32 s44, s42, 0x100
	s_addc_u32 s45, s43, 0
	s_add_u32 s47, s57, s42
	s_addc_u32 s74, s64, s43
	s_cmp_eq_u32 s49, s46
	s_cselect_b32 s46, 0, s44
	s_cselect_b32 s75, 0, s45
	s_cselect_b32 s76, s56, s47
	s_cselect_b32 s77, s52, s74
	s_add_u32 s46, s22, s46
	s_addc_u32 s47, s23, s75
	s_add_i32 s74, 0, 0x10000
	v_add_u32_e32 v0, s74, v144
	s_add_i32 s75, 0, 0x14000
	ds_read_b128 v[146:149], v0
	ds_read_b128 v[150:153], v0 offset:1024
	ds_read_b128 v[154:157], v0 offset:2048
	ds_read_b128 v[158:161], v0 offset:3072
	v_add_u32_e32 v0, s75, v144
	ds_read_b128 v[162:165], v0
	ds_read_b128 v[166:169], v0 offset:1024
	ds_read_b128 v[170:173], v0 offset:2048
	ds_read_b128 v[174:177], v0 offset:3072
	v_lshl_add_u64 v[190:191], v[138:139], 0, s[42:43]
	s_add_i32 m0, s11, 0xc000
	ds_read_b128 v[178:181], v145
	ds_read_b128 v[182:185], v145 offset:1024
	ds_read_b128 v[186:189], v145 offset:2048
	ds_read_b128 v[208:211], v145 offset:3072
	ds_read_b128 v[212:215], v145 offset:4096
	ds_read_b128 v[216:219], v145 offset:5120
	ds_read_b128 v[220:223], v145 offset:6144
	global_load_lds_dwordx4 v[190:191], off
	v_lshl_add_u64 v[190:191], v[140:141], 0, s[42:43]
	s_add_i32 m0, s11, 0xe000
	ds_read_b128 v[224:227], v145 offset:7168
	global_load_lds_dwordx4 v[190:191], off
	s_waitcnt vmcnt(8)
	s_waitcnt lgkmcnt(0)
	s_barrier
	v_mfma_f32_16x16x32_bf16 v[122:125], v[146:149], v[178:181], v[122:125]
	v_mfma_f32_16x16x32_bf16 v[126:129], v[154:157], v[178:181], v[126:129]
	v_mfma_f32_16x16x32_bf16 v[110:113], v[146:149], v[186:189], v[110:113]
	v_mfma_f32_16x16x32_bf16 v[106:109], v[154:157], v[186:189], v[106:109]
	v_mfma_f32_16x16x32_bf16 v[94:97], v[146:149], v[212:215], v[94:97]
	v_mfma_f32_16x16x32_bf16 v[90:93], v[154:157], v[212:215], v[90:93]
	v_mfma_f32_16x16x32_bf16 v[78:81], v[146:149], v[220:223], v[78:81]
	v_mfma_f32_16x16x32_bf16 v[74:77], v[154:157], v[220:223], v[74:77]
	v_mfma_f32_16x16x32_bf16 v[122:125], v[150:153], v[182:185], v[122:125]
	v_mfma_f32_16x16x32_bf16 v[126:129], v[158:161], v[182:185], v[126:129]
	v_mfma_f32_16x16x32_bf16 v[110:113], v[150:153], v[208:211], v[110:113]
	v_mfma_f32_16x16x32_bf16 v[106:109], v[158:161], v[208:211], v[106:109]
	v_mfma_f32_16x16x32_bf16 v[94:97], v[150:153], v[216:219], v[94:97]
	v_mfma_f32_16x16x32_bf16 v[90:93], v[158:161], v[216:219], v[90:93]
	v_mfma_f32_16x16x32_bf16 v[78:81], v[150:153], v[224:227], v[78:81]
	v_mfma_f32_16x16x32_bf16 v[74:77], v[158:161], v[224:227], v[74:77]
	v_mfma_f32_16x16x32_bf16 v[118:121], v[162:165], v[178:181], v[118:121]
	v_mfma_f32_16x16x32_bf16 v[114:117], v[170:173], v[178:181], v[114:117]
	v_mfma_f32_16x16x32_bf16 v[102:105], v[162:165], v[186:189], v[102:105]
	v_mfma_f32_16x16x32_bf16 v[98:101], v[170:173], v[186:189], v[98:101]
	v_mfma_f32_16x16x32_bf16 v[86:89], v[162:165], v[212:215], v[86:89]
	v_mfma_f32_16x16x32_bf16 v[82:85], v[170:173], v[212:215], v[82:85]
	v_mfma_f32_16x16x32_bf16 v[70:73], v[162:165], v[220:223], v[70:73]
	v_mfma_f32_16x16x32_bf16 v[66:69], v[170:173], v[220:223], v[66:69]
	v_mfma_f32_16x16x32_bf16 v[118:121], v[166:169], v[182:185], v[118:121]
	v_mfma_f32_16x16x32_bf16 v[114:117], v[174:177], v[182:185], v[114:117]
	v_mfma_f32_16x16x32_bf16 v[102:105], v[166:169], v[208:211], v[102:105]
	v_mfma_f32_16x16x32_bf16 v[98:101], v[174:177], v[208:211], v[98:101]
	v_mfma_f32_16x16x32_bf16 v[86:89], v[166:169], v[216:219], v[86:89]
	v_mfma_f32_16x16x32_bf16 v[82:85], v[174:177], v[216:219], v[82:85]
	v_mfma_f32_16x16x32_bf16 v[70:73], v[166:169], v[224:227], v[70:73]
	v_mfma_f32_16x16x32_bf16 v[66:69], v[174:177], v[224:227], v[66:69]
	s_barrier
	s_add_i32 s42, s74, s7
	v_lshl_add_u64 v[190:191], s[76:77], 0, v[134:135]
	s_mov_b32 m0, s42
	ds_read_b128 v[178:181], v145 offset:16384
	ds_read_b128 v[182:185], v145 offset:17408
	ds_read_b128 v[186:189], v145 offset:18432
	ds_read_b128 v[208:211], v145 offset:19456
	ds_read_b128 v[212:215], v145 offset:20480
	ds_read_b128 v[216:219], v145 offset:21504
	ds_read_b128 v[220:223], v145 offset:22528
	global_load_lds_dwordx4 v[190:191], off
	s_add_i32 m0, s42, 0x2000
	s_add_u32 s42, s76, s78
	v_lshl_add_u64 v[228:229], s[76:77], 0, v[130:131]
	s_addc_u32 s43, s77, 0
	s_add_i32 s74, s75, s7
	global_load_lds_dwordx4 v[228:229], off
	v_lshl_add_u64 v[230:231], s[42:43], 0, v[134:135]
	s_mov_b32 m0, s74
	v_lshl_add_u64 v[232:233], s[42:43], 0, v[130:131]
	global_load_lds_dwordx4 v[230:231], off
	s_add_i32 m0, s74, 0x2000
	v_lshl_add_u64 v[238:239], s[46:47], 0, v[136:137]
	global_load_lds_dwordx4 v[232:233], off
	s_mov_b32 m0, s11
	v_lshl_add_u64 v[240:241], s[46:47], 0, v[132:133]
	global_load_lds_dwordx4 v[238:239], off
	s_mov_b32 m0, s10
	ds_read_b128 v[224:227], v145 offset:23552
	global_load_lds_dwordx4 v[240:241], off
	s_waitcnt vmcnt(8)
	s_waitcnt lgkmcnt(0)
	s_barrier
; #define PG8_STAGE(bufoff, gbase, voff) do { _Pragma("unroll") for (int _i = 0; _i < 2; ++_i) \
;         __builtin_amdgcn_global_load_lds((const unsigned*)((const char*)(gbase) + (voff)[_i]), (LAS unsigned*)(lds + (bufoff) + ldsw + _i * 8192), 16, 0, 0); } while (0)
; #define PG8_LDA(dst, b, h) do { _Pragma("unroll") for (int m = 0; m < 4; ++m) _Pragma("unroll") for (int k = 0; k < 2; ++k) dst[m][k] = *(const LAS bf16x8*)(lds + PG8_SA(b, h) + aoff + m * 2048 + k * 1024); } while (0)
; #define PG8_LDB(dst, b, h) do { _Pragma("unroll") for (int n = 0; n < 2; ++n) _Pragma("unroll") for (int k = 0; k < 2; ++k) dst[n][k] = *(const LAS bf16x8*)(lds + PG8_SB(b, h) + boff + n * 2048 + k * 1024); } while (0)
; #define PG8_MMA(ai, bj, At, Bt) do { __builtin_amdgcn_s_setprio(1); _Pragma("unroll") for (int m = 0; m < 4; ++m) _Pragma("unroll") for (int n = 0; n < 2; ++n) _Pragma("unroll") for (int k = 0; k < 2; ++k) \
;         acc[ai][bj][m][n] = __builtin_amdgcn_mfma_f32_16x16x32_bf16(Bt[n][k], At[m][k], acc[ai][bj][m][n], 0, 0, 0); __builtin_amdgcn_s_setprio(0); } while (0)
; #define PG8_WAIT_V(n) asm volatile("s_waitcnt vmcnt(" #n ")" ::: "memory")
; #define PG8_WAIT_L(n) asm volatile("s_waitcnt lgkmcnt(" #n ")" ::: "memory")
; #define PG8_BAR __builtin_amdgcn_s_barrier()
; #define PG8_SCHED __builtin_amdgcn_sched_barrier(0)
; template <class Epi, class Sched>
; __device__ __forceinline__ void gemm_phase(LAS unsigned char* lds, const Gemm g, const Sched& S, const Epi& E) {
;     ...
;             PG8_LDA(At, 0, 1); PG8_STAGE(PG8_SB(0, 0), b2, voffB); PG8_STAGE(PG8_SB(0, 1), b2 + hsB, voffB); PG8_STAGE(PG8_SA(0, 0), a2, voffA);
;             PG8_WAIT_V(8); PG8_WAIT_L(0); PG8_BAR; PG8_MMA(1, 0, At, B0); PG8_MMA(1, 1, At, B1); PG8_BAR; PG8_SCHED;
;             PG8_LDB(B0, 1, 0); PG8_LDB(B1, 1, 1); PG8_SCHED; PG8_LDA(At, 1, 0); PG8_STAGE(PG8_SA(0, 1), a2 + hsA, voffA);
;             PG8_WAIT_V(8); PG8_WAIT_L(0); PG8_BAR; PG8_MMA(0, 0, At, B0); PG8_MMA(0, 1, At, B1); PG8_BAR; PG8_SCHED;
	v_mfma_f32_16x16x32_bf16 v[62:65], v[146:149], v[178:181], v[62:65]
	v_mfma_f32_16x16x32_bf16 v[58:61], v[154:157], v[178:181], v[58:61]
	v_mfma_f32_16x16x32_bf16 v[46:49], v[146:149], v[186:189], v[46:49]
	v_mfma_f32_16x16x32_bf16 v[42:45], v[154:157], v[186:189], v[42:45]
	v_mfma_f32_16x16x32_bf16 v[30:33], v[146:149], v[212:215], v[30:33]
	v_mfma_f32_16x16x32_bf16 v[26:29], v[154:157], v[212:215], v[26:29]
	v_mfma_f32_16x16x32_bf16 v[14:17], v[146:149], v[220:223], v[14:17]
	v_mfma_f32_16x16x32_bf16 v[10:13], v[154:157], v[220:223], v[10:13]
	v_mfma_f32_16x16x32_bf16 v[62:65], v[150:153], v[182:185], v[62:65]
	v_mfma_f32_16x16x32_bf16 v[58:61], v[158:161], v[182:185], v[58:61]
	v_mfma_f32_16x16x32_bf16 v[46:49], v[150:153], v[208:211], v[46:49]
	v_mfma_f32_16x16x32_bf16 v[42:45], v[158:161], v[208:211], v[42:45]
	v_mfma_f32_16x16x32_bf16 v[30:33], v[150:153], v[216:219], v[30:33]
	v_mfma_f32_16x16x32_bf16 v[26:29], v[158:161], v[216:219], v[26:29]
	v_mfma_f32_16x16x32_bf16 v[14:17], v[150:153], v[224:227], v[14:17]
	v_mfma_f32_16x16x32_bf16 v[10:13], v[158:161], v[224:227], v[10:13]
	v_mfma_f32_16x16x32_bf16 v[54:57], v[162:165], v[178:181], v[54:57]
	v_mfma_f32_16x16x32_bf16 v[50:53], v[170:173], v[178:181], v[50:53]
	v_mfma_f32_16x16x32_bf16 v[38:41], v[162:165], v[186:189], v[38:41]
	v_mfma_f32_16x16x32_bf16 v[34:37], v[170:173], v[186:189], v[34:37]
	v_mfma_f32_16x16x32_bf16 v[22:25], v[162:165], v[212:215], v[22:25]
	v_mfma_f32_16x16x32_bf16 v[18:21], v[170:173], v[212:215], v[18:21]
	v_mfma_f32_16x16x32_bf16 v[6:9], v[162:165], v[220:223], v[6:9]
	v_mfma_f32_16x16x32_bf16 v[2:5], v[170:173], v[220:223], v[2:5]
	v_mfma_f32_16x16x32_bf16 v[54:57], v[166:169], v[182:185], v[54:57]
	v_mfma_f32_16x16x32_bf16 v[50:53], v[174:177], v[182:185], v[50:53]
	v_mfma_f32_16x16x32_bf16 v[38:41], v[166:169], v[208:211], v[38:41]
	v_mfma_f32_16x16x32_bf16 v[34:37], v[174:177], v[208:211], v[34:37]
	v_mfma_f32_16x16x32_bf16 v[22:25], v[166:169], v[216:219], v[22:25]
	v_mfma_f32_16x16x32_bf16 v[18:21], v[174:177], v[216:219], v[18:21]
	v_mfma_f32_16x16x32_bf16 v[6:9], v[166:169], v[224:227], v[6:9]
	v_mfma_f32_16x16x32_bf16 v[2:5], v[174:177], v[224:227], v[2:5]
	s_barrier
	s_add_i32 s74, 0, 0x18000
	v_add_u32_e32 v0, s74, v144
	s_add_i32 s75, 0, 0x1c000
	ds_read_b128 v[146:149], v0
	ds_read_b128 v[150:153], v0 offset:1024
	ds_read_b128 v[154:157], v0 offset:2048
	ds_read_b128 v[158:161], v0 offset:3072
	v_add_u32_e32 v0, s75, v144
	ds_read_b128 v[162:165], v0
	ds_read_b128 v[166:169], v0 offset:1024
	ds_read_b128 v[170:173], v0 offset:2048
	ds_read_b128 v[174:177], v0 offset:3072
	s_add_u32 s42, s46, 0x20000
	s_addc_u32 s43, s47, 0
	s_mov_b32 m0, s12
	v_lshl_add_u64 v[242:243], s[42:43], 0, v[136:137]
	ds_read_b128 v[178:181], v145 offset:32768
	ds_read_b128 v[182:185], v145 offset:33792
	ds_read_b128 v[186:189], v145 offset:34816
	ds_read_b128 v[208:211], v145 offset:35840
	ds_read_b128 v[212:215], v145 offset:36864
	ds_read_b128 v[216:219], v145 offset:37888
	ds_read_b128 v[220:223], v145 offset:38912
	global_load_lds_dwordx4 v[242:243], off
	v_lshl_add_u64 v[242:243], s[42:43], 0, v[132:133]
	s_mov_b32 m0, s16
	ds_read_b128 v[224:227], v145 offset:39936
	global_load_lds_dwordx4 v[242:243], off
	s_waitcnt vmcnt(8)
	s_waitcnt lgkmcnt(0)
	s_barrier
	v_mfma_f32_16x16x32_bf16 v[122:125], v[146:149], v[178:181], v[122:125]
	v_mfma_f32_16x16x32_bf16 v[126:129], v[154:157], v[178:181], v[126:129]
	v_mfma_f32_16x16x32_bf16 v[110:113], v[146:149], v[186:189], v[110:113]
	v_mfma_f32_16x16x32_bf16 v[106:109], v[154:157], v[186:189], v[106:109]
	v_mfma_f32_16x16x32_bf16 v[94:97], v[146:149], v[212:215], v[94:97]
	v_mfma_f32_16x16x32_bf16 v[90:93], v[154:157], v[212:215], v[90:93]
	v_mfma_f32_16x16x32_bf16 v[78:81], v[146:149], v[220:223], v[78:81]
	v_mfma_f32_16x16x32_bf16 v[74:77], v[154:157], v[220:223], v[74:77]
	v_mfma_f32_16x16x32_bf16 v[122:125], v[150:153], v[182:185], v[122:125]
	v_mfma_f32_16x16x32_bf16 v[126:129], v[158:161], v[182:185], v[126:129]
	v_mfma_f32_16x16x32_bf16 v[110:113], v[150:153], v[208:211], v[110:113]
	v_mfma_f32_16x16x32_bf16 v[106:109], v[158:161], v[208:211], v[106:109]
	v_mfma_f32_16x16x32_bf16 v[94:97], v[150:153], v[216:219], v[94:97]
	v_mfma_f32_16x16x32_bf16 v[90:93], v[158:161], v[216:219], v[90:93]
	v_mfma_f32_16x16x32_bf16 v[78:81], v[150:153], v[224:227], v[78:81]
	v_mfma_f32_16x16x32_bf16 v[74:77], v[158:161], v[224:227], v[74:77]
	v_mfma_f32_16x16x32_bf16 v[118:121], v[162:165], v[178:181], v[118:121]
	v_mfma_f32_16x16x32_bf16 v[114:117], v[170:173], v[178:181], v[114:117]
	v_mfma_f32_16x16x32_bf16 v[102:105], v[162:165], v[186:189], v[102:105]
	v_mfma_f32_16x16x32_bf16 v[98:101], v[170:173], v[186:189], v[98:101]
	v_mfma_f32_16x16x32_bf16 v[86:89], v[162:165], v[212:215], v[86:89]
	v_mfma_f32_16x16x32_bf16 v[82:85], v[170:173], v[212:215], v[82:85]
	v_mfma_f32_16x16x32_bf16 v[70:73], v[162:165], v[220:223], v[70:73]
	v_mfma_f32_16x16x32_bf16 v[66:69], v[170:173], v[220:223], v[66:69]
	v_mfma_f32_16x16x32_bf16 v[118:121], v[166:169], v[182:185], v[118:121]
	v_mfma_f32_16x16x32_bf16 v[114:117], v[174:177], v[182:185], v[114:117]
	v_mfma_f32_16x16x32_bf16 v[102:105], v[166:169], v[208:211], v[102:105]
	v_mfma_f32_16x16x32_bf16 v[98:101], v[174:177], v[208:211], v[98:101]
	v_mfma_f32_16x16x32_bf16 v[86:89], v[166:169], v[216:219], v[86:89]
	v_mfma_f32_16x16x32_bf16 v[82:85], v[174:177], v[216:219], v[82:85]
	v_mfma_f32_16x16x32_bf16 v[70:73], v[166:169], v[224:227], v[70:73]
	v_mfma_f32_16x16x32_bf16 v[66:69], v[174:177], v[224:227], v[66:69]
	s_barrier
; #define PG8_STAGE(bufoff, gbase, voff) do { _Pragma("unroll") for (int _i = 0; _i < 2; ++_i) \
;         __builtin_amdgcn_global_load_lds((const unsigned*)((const char*)(gbase) + (voff)[_i]), (LAS unsigned*)(lds + (bufoff) + ldsw + _i * 8192), 16, 0, 0); } while (0)
; #define PG8_LDA(dst, b, h) do { _Pragma("unroll") for (int m = 0; m < 4; ++m) _Pragma("unroll") for (int k = 0; k < 2; ++k) dst[m][k] = *(const LAS bf16x8*)(lds + PG8_SA(b, h) + aoff + m * 2048 + k * 1024); } while (0)
; #define PG8_MMA(ai, bj, At, Bt) do { __builtin_amdgcn_s_setprio(1); _Pragma("unroll") for (int m = 0; m < 4; ++m) _Pragma("unroll") for (int n = 0; n < 2; ++n) _Pragma("unroll") for (int k = 0; k < 2; ++k) \
;         acc[ai][bj][m][n] = __builtin_amdgcn_mfma_f32_16x16x32_bf16(Bt[n][k], At[m][k], acc[ai][bj][m][n], 0, 0, 0); __builtin_amdgcn_s_setprio(0); } while (0)
; #define PG8_WAIT_V(n) asm volatile("s_waitcnt vmcnt(" #n ")" ::: "memory")
; #define PG8_WAIT_L(n) asm volatile("s_waitcnt lgkmcnt(" #n ")" ::: "memory")
; #define PG8_BAR __builtin_amdgcn_s_barrier()
; #define PG8_SCHED __builtin_amdgcn_sched_barrier(0)
; template <class Epi, class Sched>
; __device__ __forceinline__ void gemm_phase(LAS unsigned char* lds, const Gemm g, const Sched& S, const Epi& E) {
;     ...
;             PG8_LDA(At, 1, 1); PG8_STAGE(PG8_SB(1, 0), b3, voffB); PG8_STAGE(PG8_SB(1, 1), b3 + hsB, voffB); PG8_STAGE(PG8_SA(1, 0), a3, voffA);
;             PG8_WAIT_V(8); PG8_WAIT_L(0); PG8_BAR; PG8_MMA(1, 0, At, B0); PG8_MMA(1, 1, At, B1); PG8_BAR; PG8_SCHED;
;         }
	s_add_i32 s42, s74, s7
	v_lshl_add_u64 v[190:191], v[190:191], 0, s[18:19]
	s_mov_b32 m0, s42
	ds_read_b128 v[178:181], v145 offset:49152
	ds_read_b128 v[182:185], v145 offset:50176
	ds_read_b128 v[186:189], v145 offset:51200
	ds_read_b128 v[208:211], v145 offset:52224
	global_load_lds_dwordx4 v[190:191], off
	v_lshl_add_u64 v[190:191], v[228:229], 0, s[18:19]
	s_add_i32 m0, s42, 0x2000
	s_add_i32 s42, s75, s7
	global_load_lds_dwordx4 v[190:191], off
	v_lshl_add_u64 v[190:191], v[230:231], 0, s[18:19]
	s_mov_b32 m0, s42
	ds_read_b128 v[212:215], v145 offset:53248
	global_load_lds_dwordx4 v[190:191], off
	v_lshl_add_u64 v[190:191], v[232:233], 0, s[18:19]
	s_add_i32 m0, s42, 0x2000
	ds_read_b128 v[216:219], v145 offset:54272
	global_load_lds_dwordx4 v[190:191], off
	v_lshl_add_u64 v[190:191], v[238:239], 0, s[18:19]
	s_mov_b32 m0, s30
	ds_read_b128 v[220:223], v145 offset:55296
	global_load_lds_dwordx4 v[190:191], off
	v_lshl_add_u64 v[190:191], v[240:241], 0, s[18:19]
	s_mov_b32 m0, s48
	ds_read_b128 v[224:227], v145 offset:56320
	global_load_lds_dwordx4 v[190:191], off
	s_waitcnt vmcnt(8)
	s_waitcnt lgkmcnt(0)
	s_barrier
	v_mfma_f32_16x16x32_bf16 v[62:65], v[146:149], v[178:181], v[62:65]
	v_mfma_f32_16x16x32_bf16 v[58:61], v[154:157], v[178:181], v[58:61]
	v_mfma_f32_16x16x32_bf16 v[46:49], v[146:149], v[186:189], v[46:49]
	v_mfma_f32_16x16x32_bf16 v[42:45], v[154:157], v[186:189], v[42:45]
	v_mfma_f32_16x16x32_bf16 v[30:33], v[146:149], v[212:215], v[30:33]
	v_mfma_f32_16x16x32_bf16 v[26:29], v[154:157], v[212:215], v[26:29]
	v_mfma_f32_16x16x32_bf16 v[14:17], v[146:149], v[220:223], v[14:17]
	v_mfma_f32_16x16x32_bf16 v[10:13], v[154:157], v[220:223], v[10:13]
	v_mfma_f32_16x16x32_bf16 v[62:65], v[150:153], v[182:185], v[62:65]
	v_mfma_f32_16x16x32_bf16 v[58:61], v[158:161], v[182:185], v[58:61]
	v_mfma_f32_16x16x32_bf16 v[46:49], v[150:153], v[208:211], v[46:49]
	v_mfma_f32_16x16x32_bf16 v[42:45], v[158:161], v[208:211], v[42:45]
	v_mfma_f32_16x16x32_bf16 v[30:33], v[150:153], v[216:219], v[30:33]
	v_mfma_f32_16x16x32_bf16 v[26:29], v[158:161], v[216:219], v[26:29]
	v_mfma_f32_16x16x32_bf16 v[14:17], v[150:153], v[224:227], v[14:17]
	v_mfma_f32_16x16x32_bf16 v[10:13], v[158:161], v[224:227], v[10:13]
	v_mfma_f32_16x16x32_bf16 v[54:57], v[162:165], v[178:181], v[54:57]
	v_mfma_f32_16x16x32_bf16 v[50:53], v[170:173], v[178:181], v[50:53]
	v_mfma_f32_16x16x32_bf16 v[38:41], v[162:165], v[186:189], v[38:41]
	v_mfma_f32_16x16x32_bf16 v[34:37], v[170:173], v[186:189], v[34:37]
	v_mfma_f32_16x16x32_bf16 v[22:25], v[162:165], v[212:215], v[22:25]
	v_mfma_f32_16x16x32_bf16 v[18:21], v[170:173], v[212:215], v[18:21]
	v_mfma_f32_16x16x32_bf16 v[6:9], v[162:165], v[220:223], v[6:9]
	v_mfma_f32_16x16x32_bf16 v[2:5], v[170:173], v[220:223], v[2:5]
	v_mfma_f32_16x16x32_bf16 v[54:57], v[166:169], v[182:185], v[54:57]
	v_mfma_f32_16x16x32_bf16 v[50:53], v[174:177], v[182:185], v[50:53]
	v_mfma_f32_16x16x32_bf16 v[38:41], v[166:169], v[208:211], v[38:41]
	v_mfma_f32_16x16x32_bf16 v[34:37], v[174:177], v[208:211], v[34:37]
	v_mfma_f32_16x16x32_bf16 v[22:25], v[166:169], v[216:219], v[22:25]
	v_mfma_f32_16x16x32_bf16 v[18:21], v[174:177], v[216:219], v[18:21]
	v_mfma_f32_16x16x32_bf16 v[6:9], v[166:169], v[224:227], v[6:9]
	v_mfma_f32_16x16x32_bf16 v[2:5], v[174:177], v[224:227], v[2:5]
	s_barrier
	s_cmp_ge_i32 s73, s24
	s_mov_b64 s[42:43], s[44:45]
	s_mov_b32 s46, s73
	s_cbranch_scc0 .LBB0_763
	s_setprio 0

; #define PG8_STAGE(bufoff, gbase, voff) do { _Pragma("unroll") for (int _i = 0; _i < 2; ++_i) \
;         __builtin_amdgcn_global_load_lds((const unsigned*)((const char*)(gbase) + (voff)[_i]), (LAS unsigned*)(lds + (bufoff) + ldsw + _i * 8192), 16, 0, 0); } while (0)
; #define PG8_LDA(dst, b, h) do { _Pragma("unroll") for (int m = 0; m < 4; ++m) _Pragma("unroll") for (int k = 0; k < 2; ++k) dst[m][k] = *(const LAS bf16x8*)(lds + PG8_SA(b, h) + aoff + m * 2048 + k * 1024); } while (0)
; #define PG8_LDB(dst, b, h) do { _Pragma("unroll") for (int n = 0; n < 2; ++n) _Pragma("unroll") for (int k = 0; k < 2; ++k) dst[n][k] = *(const LAS bf16x8*)(lds + PG8_SB(b, h) + boff + n * 2048 + k * 1024); } while (0)
; #define PG8_MMA(ai, bj, At, Bt) do { __builtin_amdgcn_s_setprio(1); _Pragma("unroll") for (int m = 0; m < 4; ++m) _Pragma("unroll") for (int n = 0; n < 2; ++n) _Pragma("unroll") for (int k = 0; k < 2; ++k) \
;         acc[ai][bj][m][n] = __builtin_amdgcn_mfma_f32_16x16x32_bf16(Bt[n][k], At[m][k], acc[ai][bj][m][n], 0, 0, 0); __builtin_amdgcn_s_setprio(0); } while (0)
; #define PG8_WAIT_V(n) asm volatile("s_waitcnt vmcnt(" #n ")" ::: "memory")
; #define PG8_BAR __builtin_amdgcn_s_barrier()
; template <class Epi, class Sched>
; __device__ __forceinline__ void gemm_phase(LAS unsigned char* lds, const Gemm g, const Sched& S, const Epi& E) {
;     ...
;         for (int t = 0; t < nt; t += 2) {
;             const bool last = (t == nt - 2);
;             const char* a1 = cA + (size_t)(t + 1) * kstep;
;             const char* a2 = last ? nA : cA + (size_t)(t + 2) * kstep; const char* b2 = last ? nB : cB + (size_t)(t + 2) * kstep;
;             const char* a3 = a2 + kstep; const char* b3 = b2 + kstep;
;             if constexpr (Epi::MIDK) { if (t == (nt >> 1)) { int fr_ = fr, fq_ = fq; asm volatile("" : "+v"(fr_), "+v"(fq_)); E.mid(acc, cur, wr, wc, fr_, fq_); } }
;             PG8_LDB(B0, 0, 0); PG8_LDB(B1, 0, 1); PG8_SCHED; PG8_LDA(At, 0, 0); PG8_STAGE(PG8_SA(1, 1), a1 + hsA, voffA);
;             PG8_WAIT_V(8); PG8_WAIT_L(0); PG8_BAR; PG8_MMA(0, 0, At, B0); PG8_MMA(0, 1, At, B1); PG8_BAR; PG8_SCHED;
;             PG8_LDA(At, 0, 1); PG8_STAGE(PG8_SB(0, 0), b2, voffB); PG8_STAGE(PG8_SB(0, 1), b2 + hsB, voffB); PG8_STAGE(PG8_SA(0, 0), a2, voffA);
;             PG8_WAIT_V(8); PG8_WAIT_L(0); PG8_BAR; PG8_MMA(1, 0, At, B0); PG8_MMA(1, 1, At, B1); PG8_BAR; PG8_SCHED;
.LBB0_837:
	s_add_i32 s96, s76, 2
	s_add_u32 s74, s50, 0xfffc0080
	s_addc_u32 s75, s51, -1
	s_cmp_eq_u32 s64, s76
	s_cselect_b32 s85, s10, s75
	s_cselect_b32 s84, s35, s74
	s_cselect_b32 s77, s41, s1
	s_cselect_b32 s76, s83, s0
	s_add_i32 s74, 0, 0x10000
	v_add_u32_e32 v0, s74, v206
	s_add_i32 s75, 0, 0x14000
	ds_read_b128 v[132:135], v0
	ds_read_b128 v[136:139], v0 offset:1024
	ds_read_b128 v[140:143], v0 offset:2048
	ds_read_b128 v[144:147], v0 offset:3072
	v_add_u32_e32 v0, s75, v206
	ds_read_b128 v[148:151], v0
	ds_read_b128 v[152:155], v0 offset:1024
	ds_read_b128 v[156:159], v0 offset:2048
	ds_read_b128 v[160:163], v0 offset:3072
	v_lshl_add_u64 v[2:3], s[50:51], 0, v[216:217]
	s_add_i32 m0, s11, 0xc000
	ds_read_b128 v[164:167], v238
	ds_read_b128 v[168:171], v238 offset:1024
	ds_read_b128 v[172:175], v238 offset:2048
	ds_read_b128 v[176:179], v238 offset:3072
	ds_read_b128 v[180:183], v238 offset:4096
	ds_read_b128 v[184:187], v238 offset:5120
	ds_read_b128 v[188:191], v238 offset:6144
	global_load_lds_dwordx4 v[2:3], off
	v_lshl_add_u64 v[2:3], s[50:51], 0, v[218:219]
	s_add_i32 m0, s11, 0xe000
	ds_read_b128 v[220:223], v238 offset:7168
	global_load_lds_dwordx4 v[2:3], off
	s_waitcnt vmcnt(8)
	s_waitcnt lgkmcnt(0)
	s_barrier
	v_mfma_f32_16x16x32_bf16 v[124:127], v[132:135], v[164:167], v[124:127]
	v_mfma_f32_16x16x32_bf16 v[128:131], v[140:143], v[164:167], v[128:131]
	v_mfma_f32_16x16x32_bf16 v[112:115], v[132:135], v[172:175], v[112:115]
	v_mfma_f32_16x16x32_bf16 v[108:111], v[140:143], v[172:175], v[108:111]
	v_mfma_f32_16x16x32_bf16 v[96:99], v[132:135], v[180:183], v[96:99]
	v_mfma_f32_16x16x32_bf16 v[92:95], v[140:143], v[180:183], v[92:95]
	v_mfma_f32_16x16x32_bf16 v[80:83], v[132:135], v[188:191], v[80:83]
	v_mfma_f32_16x16x32_bf16 v[76:79], v[140:143], v[188:191], v[76:79]
	v_mfma_f32_16x16x32_bf16 v[124:127], v[136:139], v[168:171], v[124:127]
	v_mfma_f32_16x16x32_bf16 v[128:131], v[144:147], v[168:171], v[128:131]
	v_mfma_f32_16x16x32_bf16 v[112:115], v[136:139], v[176:179], v[112:115]
	v_mfma_f32_16x16x32_bf16 v[108:111], v[144:147], v[176:179], v[108:111]
	v_mfma_f32_16x16x32_bf16 v[96:99], v[136:139], v[184:187], v[96:99]
	v_mfma_f32_16x16x32_bf16 v[92:95], v[144:147], v[184:187], v[92:95]
	v_mfma_f32_16x16x32_bf16 v[80:83], v[136:139], v[220:223], v[80:83]
	v_mfma_f32_16x16x32_bf16 v[76:79], v[144:147], v[220:223], v[76:79]
	v_mfma_f32_16x16x32_bf16 v[116:119], v[148:151], v[164:167], v[116:119]
	v_mfma_f32_16x16x32_bf16 v[120:123], v[156:159], v[164:167], v[120:123]
	v_mfma_f32_16x16x32_bf16 v[104:107], v[148:151], v[172:175], v[104:107]
	v_mfma_f32_16x16x32_bf16 v[100:103], v[156:159], v[172:175], v[100:103]
	v_mfma_f32_16x16x32_bf16 v[88:91], v[148:151], v[180:183], v[88:91]
	v_mfma_f32_16x16x32_bf16 v[84:87], v[156:159], v[180:183], v[84:87]
	v_mfma_f32_16x16x32_bf16 v[72:75], v[148:151], v[188:191], v[72:75]
	v_mfma_f32_16x16x32_bf16 v[68:71], v[156:159], v[188:191], v[68:71]
	v_mfma_f32_16x16x32_bf16 v[116:119], v[152:155], v[168:171], v[116:119]
	v_mfma_f32_16x16x32_bf16 v[120:123], v[160:163], v[168:171], v[120:123]
	v_mfma_f32_16x16x32_bf16 v[104:107], v[152:155], v[176:179], v[104:107]
	v_mfma_f32_16x16x32_bf16 v[100:103], v[160:163], v[176:179], v[100:103]
	v_mfma_f32_16x16x32_bf16 v[88:91], v[152:155], v[184:187], v[88:91]
	v_mfma_f32_16x16x32_bf16 v[84:87], v[160:163], v[184:187], v[84:87]
	v_mfma_f32_16x16x32_bf16 v[72:75], v[152:155], v[220:223], v[72:75]
	v_mfma_f32_16x16x32_bf16 v[68:71], v[160:163], v[220:223], v[68:71]
	s_barrier
	s_add_i32 s74, s74, s7
	v_lshl_add_u64 v[224:225], s[76:77], 0, v[212:213]
	s_mov_b32 m0, s74
	ds_read_b128 v[164:167], v238 offset:16384
	ds_read_b128 v[168:171], v238 offset:17408
	ds_read_b128 v[172:175], v238 offset:18432
	ds_read_b128 v[176:179], v238 offset:19456
	ds_read_b128 v[180:183], v238 offset:20480
	ds_read_b128 v[184:187], v238 offset:21504
	global_load_lds_dwordx4 v[224:225], off
	s_add_i32 m0, s74, 0x2000
	s_add_u32 vcc_lo, s76, 0x40000
	v_lshl_add_u64 v[226:227], s[76:77], 0, v[208:209]
	s_addc_u32 vcc_hi, s77, 0
	s_add_i32 s74, s75, s7
	global_load_lds_dwordx4 v[226:227], off
	v_lshl_add_u64 v[2:3], vcc, 0, v[212:213]
	s_mov_b32 m0, s74
	v_lshl_add_u64 v[228:229], s[84:85], 0, v[214:215]
	global_load_lds_dwordx4 v[2:3], off
	v_lshl_add_u64 v[2:3], vcc, 0, v[208:209]
	s_add_i32 m0, s74, 0x2000
	v_lshl_add_u64 v[230:231], s[84:85], 0, v[210:211]
	global_load_lds_dwordx4 v[2:3], off
	s_mov_b32 m0, s11
	ds_read_b128 v[188:191], v238 offset:22528
	global_load_lds_dwordx4 v[228:229], off
	s_mov_b32 m0, s12
	ds_read_b128 v[220:223], v238 offset:23552
	global_load_lds_dwordx4 v[230:231], off
	s_waitcnt vmcnt(8)
	s_waitcnt lgkmcnt(0)
	s_barrier
; #define PG8_STAGE(bufoff, gbase, voff) do { _Pragma("unroll") for (int _i = 0; _i < 2; ++_i) \
;         __builtin_amdgcn_global_load_lds((const unsigned*)((const char*)(gbase) + (voff)[_i]), (LAS unsigned*)(lds + (bufoff) + ldsw + _i * 8192), 16, 0, 0); } while (0)
; #define PG8_LDA(dst, b, h) do { _Pragma("unroll") for (int m = 0; m < 4; ++m) _Pragma("unroll") for (int k = 0; k < 2; ++k) dst[m][k] = *(const LAS bf16x8*)(lds + PG8_SA(b, h) + aoff + m * 2048 + k * 1024); } while (0)
; #define PG8_LDB(dst, b, h) do { _Pragma("unroll") for (int n = 0; n < 2; ++n) _Pragma("unroll") for (int k = 0; k < 2; ++k) dst[n][k] = *(const LAS bf16x8*)(lds + PG8_SB(b, h) + boff + n * 2048 + k * 1024); } while (0)
; #define PG8_MMA(ai, bj, At, Bt) do { __builtin_amdgcn_s_setprio(1); _Pragma("unroll") for (int m = 0; m < 4; ++m) _Pragma("unroll") for (int n = 0; n < 2; ++n) _Pragma("unroll") for (int k = 0; k < 2; ++k) \
;         acc[ai][bj][m][n] = __builtin_amdgcn_mfma_f32_16x16x32_bf16(Bt[n][k], At[m][k], acc[ai][bj][m][n], 0, 0, 0); __builtin_amdgcn_s_setprio(0); } while (0)
; #define PG8_WAIT_V(n) asm volatile("s_waitcnt vmcnt(" #n ")" ::: "memory")
; #define PG8_WAIT_L(n) asm volatile("s_waitcnt lgkmcnt(" #n ")" ::: "memory")
; #define PG8_BAR __builtin_amdgcn_s_barrier()
; #define PG8_SCHED __builtin_amdgcn_sched_barrier(0)
; template <class Epi, class Sched>
; __device__ __forceinline__ void gemm_phase(LAS unsigned char* lds, const Gemm g, const Sched& S, const Epi& E) {
;     ...
;             PG8_LDA(At, 0, 1); PG8_STAGE(PG8_SB(0, 0), b2, voffB); PG8_STAGE(PG8_SB(0, 1), b2 + hsB, voffB); PG8_STAGE(PG8_SA(0, 0), a2, voffA);
;             PG8_WAIT_V(8); PG8_WAIT_L(0); PG8_BAR; PG8_MMA(1, 0, At, B0); PG8_MMA(1, 1, At, B1); PG8_BAR; PG8_SCHED;
;             PG8_LDB(B0, 1, 0); PG8_LDB(B1, 1, 1); PG8_SCHED; PG8_LDA(At, 1, 0); PG8_STAGE(PG8_SA(0, 1), a2 + hsA, voffA);
;             PG8_WAIT_V(8); PG8_WAIT_L(0); PG8_BAR; PG8_MMA(0, 0, At, B0); PG8_MMA(0, 1, At, B1); PG8_BAR; PG8_SCHED;
	v_mfma_f32_16x16x32_bf16 v[64:67], v[132:135], v[164:167], v[64:67]
	v_mfma_f32_16x16x32_bf16 v[60:63], v[140:143], v[164:167], v[60:63]
	v_mfma_f32_16x16x32_bf16 v[48:51], v[132:135], v[172:175], v[48:51]
	v_mfma_f32_16x16x32_bf16 v[44:47], v[140:143], v[172:175], v[44:47]
	v_mfma_f32_16x16x32_bf16 v[32:35], v[132:135], v[180:183], v[32:35]
	v_mfma_f32_16x16x32_bf16 v[28:31], v[140:143], v[180:183], v[28:31]
	v_mfma_f32_16x16x32_bf16 v[16:19], v[132:135], v[188:191], v[16:19]
	v_mfma_f32_16x16x32_bf16 v[12:15], v[140:143], v[188:191], v[12:15]
	v_mfma_f32_16x16x32_bf16 v[64:67], v[136:139], v[168:171], v[64:67]
	v_mfma_f32_16x16x32_bf16 v[60:63], v[144:147], v[168:171], v[60:63]
	v_mfma_f32_16x16x32_bf16 v[48:51], v[136:139], v[176:179], v[48:51]
	v_mfma_f32_16x16x32_bf16 v[44:47], v[144:147], v[176:179], v[44:47]
	v_mfma_f32_16x16x32_bf16 v[32:35], v[136:139], v[184:187], v[32:35]
	v_mfma_f32_16x16x32_bf16 v[28:31], v[144:147], v[184:187], v[28:31]
	v_mfma_f32_16x16x32_bf16 v[16:19], v[136:139], v[220:223], v[16:19]
	v_mfma_f32_16x16x32_bf16 v[12:15], v[144:147], v[220:223], v[12:15]
	v_mfma_f32_16x16x32_bf16 v[56:59], v[148:151], v[164:167], v[56:59]
	v_mfma_f32_16x16x32_bf16 v[52:55], v[156:159], v[164:167], v[52:55]
	v_mfma_f32_16x16x32_bf16 v[40:43], v[148:151], v[172:175], v[40:43]
	v_mfma_f32_16x16x32_bf16 v[36:39], v[156:159], v[172:175], v[36:39]
	v_mfma_f32_16x16x32_bf16 v[24:27], v[148:151], v[180:183], v[24:27]
	v_mfma_f32_16x16x32_bf16 v[20:23], v[156:159], v[180:183], v[20:23]
	v_mfma_f32_16x16x32_bf16 v[8:11], v[148:151], v[188:191], v[8:11]
	v_mfma_f32_16x16x32_bf16 v[2:5], v[156:159], v[188:191], v[4:7]
	v_mfma_f32_16x16x32_bf16 v[56:59], v[152:155], v[168:171], v[56:59]
	v_mfma_f32_16x16x32_bf16 v[52:55], v[160:163], v[168:171], v[52:55]
	v_mfma_f32_16x16x32_bf16 v[40:43], v[152:155], v[176:179], v[40:43]
	v_mfma_f32_16x16x32_bf16 v[36:39], v[160:163], v[176:179], v[36:39]
	v_mfma_f32_16x16x32_bf16 v[24:27], v[152:155], v[184:187], v[24:27]
	v_mfma_f32_16x16x32_bf16 v[20:23], v[160:163], v[184:187], v[20:23]
	v_mfma_f32_16x16x32_bf16 v[8:11], v[152:155], v[220:223], v[8:11]
	v_mfma_f32_16x16x32_bf16 v[2:5], v[160:163], v[220:223], v[2:5]
	s_barrier
	s_add_i32 s74, 0, 0x18000
	v_add_u32_e32 v0, s74, v206
	s_add_i32 s75, 0, 0x1c000
	ds_read_b128 v[132:135], v0
	ds_read_b128 v[136:139], v0 offset:1024
	ds_read_b128 v[140:143], v0 offset:2048
	ds_read_b128 v[144:147], v0 offset:3072
	v_add_u32_e32 v0, s75, v206
	ds_read_b128 v[148:151], v0
	ds_read_b128 v[152:155], v0 offset:1024
	ds_read_b128 v[156:159], v0 offset:2048
	ds_read_b128 v[160:163], v0 offset:3072
	s_add_u32 s84, s84, 0x40000
	s_addc_u32 s85, s85, 0
	s_mov_b32 m0, s16
	v_lshl_add_u64 v[6:7], s[84:85], 0, v[214:215]
	ds_read_b128 v[164:167], v238 offset:32768
	ds_read_b128 v[168:171], v238 offset:33792
	ds_read_b128 v[172:175], v238 offset:34816
	ds_read_b128 v[176:179], v238 offset:35840
	ds_read_b128 v[180:183], v238 offset:36864
	ds_read_b128 v[184:187], v238 offset:37888
	ds_read_b128 v[188:191], v238 offset:38912
	global_load_lds_dwordx4 v[6:7], off
	v_lshl_add_u64 v[6:7], s[84:85], 0, v[210:211]
	s_mov_b32 m0, s24
	ds_read_b128 v[220:223], v238 offset:39936
	global_load_lds_dwordx4 v[6:7], off
	s_waitcnt vmcnt(8)
	s_waitcnt lgkmcnt(0)
	s_barrier
	v_mfma_f32_16x16x32_bf16 v[124:127], v[132:135], v[164:167], v[124:127]
	v_mfma_f32_16x16x32_bf16 v[128:131], v[140:143], v[164:167], v[128:131]
	v_mfma_f32_16x16x32_bf16 v[112:115], v[132:135], v[172:175], v[112:115]
	v_mfma_f32_16x16x32_bf16 v[108:111], v[140:143], v[172:175], v[108:111]
	v_mfma_f32_16x16x32_bf16 v[96:99], v[132:135], v[180:183], v[96:99]
	v_mfma_f32_16x16x32_bf16 v[92:95], v[140:143], v[180:183], v[92:95]
	v_mfma_f32_16x16x32_bf16 v[80:83], v[132:135], v[188:191], v[80:83]
	v_mfma_f32_16x16x32_bf16 v[76:79], v[140:143], v[188:191], v[76:79]
	v_mfma_f32_16x16x32_bf16 v[124:127], v[136:139], v[168:171], v[124:127]
	v_mfma_f32_16x16x32_bf16 v[128:131], v[144:147], v[168:171], v[128:131]
	v_mfma_f32_16x16x32_bf16 v[112:115], v[136:139], v[176:179], v[112:115]
	v_mfma_f32_16x16x32_bf16 v[108:111], v[144:147], v[176:179], v[108:111]
	v_mfma_f32_16x16x32_bf16 v[96:99], v[136:139], v[184:187], v[96:99]
	v_mfma_f32_16x16x32_bf16 v[92:95], v[144:147], v[184:187], v[92:95]
	v_mfma_f32_16x16x32_bf16 v[80:83], v[136:139], v[220:223], v[80:83]
	v_mfma_f32_16x16x32_bf16 v[76:79], v[144:147], v[220:223], v[76:79]
	v_mfma_f32_16x16x32_bf16 v[116:119], v[148:151], v[164:167], v[116:119]
	v_mfma_f32_16x16x32_bf16 v[120:123], v[156:159], v[164:167], v[120:123]
	v_mfma_f32_16x16x32_bf16 v[104:107], v[148:151], v[172:175], v[104:107]
	v_mfma_f32_16x16x32_bf16 v[100:103], v[156:159], v[172:175], v[100:103]
	v_mfma_f32_16x16x32_bf16 v[88:91], v[148:151], v[180:183], v[88:91]
	v_mfma_f32_16x16x32_bf16 v[84:87], v[156:159], v[180:183], v[84:87]
	v_mfma_f32_16x16x32_bf16 v[72:75], v[148:151], v[188:191], v[72:75]
	v_mfma_f32_16x16x32_bf16 v[68:71], v[156:159], v[188:191], v[68:71]
	v_mfma_f32_16x16x32_bf16 v[116:119], v[152:155], v[168:171], v[116:119]
	v_mfma_f32_16x16x32_bf16 v[120:123], v[160:163], v[168:171], v[120:123]
	v_mfma_f32_16x16x32_bf16 v[104:107], v[152:155], v[176:179], v[104:107]
	v_mfma_f32_16x16x32_bf16 v[100:103], v[160:163], v[176:179], v[100:103]
	v_mfma_f32_16x16x32_bf16 v[88:91], v[152:155], v[184:187], v[88:91]
	v_mfma_f32_16x16x32_bf16 v[84:87], v[160:163], v[184:187], v[84:87]
	v_mfma_f32_16x16x32_bf16 v[72:75], v[152:155], v[220:223], v[72:75]
	v_mfma_f32_16x16x32_bf16 v[68:71], v[160:163], v[220:223], v[68:71]
	s_barrier
; #define PG8_STAGE(bufoff, gbase, voff) do { _Pragma("unroll") for (int _i = 0; _i < 2; ++_i) \
;         __builtin_amdgcn_global_load_lds((const unsigned*)((const char*)(gbase) + (voff)[_i]), (LAS unsigned*)(lds + (bufoff) + ldsw + _i * 8192), 16, 0, 0); } while (0)
; #define PG8_LDA(dst, b, h) do { _Pragma("unroll") for (int m = 0; m < 4; ++m) _Pragma("unroll") for (int k = 0; k < 2; ++k) dst[m][k] = *(const LAS bf16x8*)(lds + PG8_SA(b, h) + aoff + m * 2048 + k * 1024); } while (0)
; #define PG8_LDB(dst, b, h) do { _Pragma("unroll") for (int n = 0; n < 2; ++n) _Pragma("unroll") for (int k = 0; k < 2; ++k) dst[n][k] = *(const LAS bf16x8*)(lds + PG8_SB(b, h) + boff + n * 2048 + k * 1024); } while (0)
; #define PG8_WAIT_V(n) asm volatile("s_waitcnt vmcnt(" #n ")" ::: "memory")
; #define PG8_WAIT_L(n) asm volatile("s_waitcnt lgkmcnt(" #n ")" ::: "memory")
; #define PG8_BAR __builtin_amdgcn_s_barrier()
; #define PG8_SCHED __builtin_amdgcn_sched_barrier(0)
; template <class Epi, class Sched>
; __device__ __forceinline__ void gemm_phase(LAS unsigned char* lds, const Gemm g, const Sched& S, const Epi& E) {
;     ...
;             if constexpr (Epi::MIDK) { if (t == (nt >> 1)) { int fr_ = fr, fq_ = fq; asm volatile("" : "+v"(fr_), "+v"(fq_)); E.mid(acc, cur, wr, wc, fr_, fq_); } }
;             PG8_LDB(B0, 0, 0); PG8_LDB(B1, 0, 1); PG8_SCHED; PG8_LDA(At, 0, 0); PG8_STAGE(PG8_SA(1, 1), a1 + hsA, voffA);
;             PG8_WAIT_V(8); PG8_WAIT_L(0); PG8_BAR; PG8_MMA(0, 0, At, B0); PG8_MMA(0, 1, At, B1); PG8_BAR; PG8_SCHED;
;             PG8_LDA(At, 0, 1); PG8_STAGE(PG8_SB(0, 0), b2, voffB); PG8_STAGE(PG8_SB(0, 1), b2 + hsB, voffB); PG8_STAGE(PG8_SA(0, 0), a2, voffA);
;             PG8_WAIT_V(8); PG8_WAIT_L(0); PG8_BAR; PG8_MMA(1, 0, At, B0); PG8_MMA(1, 1, At, B1); PG8_BAR; PG8_SCHED;
;             PG8_LDB(B0, 1, 0); PG8_LDB(B1, 1, 1); PG8_SCHED; PG8_LDA(At, 1, 0); PG8_STAGE(PG8_SA(0, 1), a2 + hsA, voffA);
;             PG8_WAIT_V(8); PG8_WAIT_L(0); PG8_BAR; PG8_MMA(0, 0, At, B0); PG8_MMA(0, 1, At, B1); PG8_BAR; PG8_SCHED;
;             PG8_LDA(At, 1, 1); PG8_STAGE(PG8_SB(1, 0), b3, voffB); PG8_STAGE(PG8_SB(1, 1), b3 + hsB, voffB); PG8_STAGE(PG8_SA(1, 0), a3, voffA);
;             PG8_WAIT_V(8); PG8_WAIT_L(0); PG8_BAR; PG8_MMA(1, 0, At, B0); PG8_MMA(1, 1, At, B1); PG8_BAR; PG8_SCHED;
;         }
	s_add_i32 s74, s74, s7
	v_lshl_add_u64 v[6:7], v[224:225], 0, s[18:19]
	s_mov_b32 m0, s74
	ds_read_b128 v[164:167], v238 offset:49152
	ds_read_b128 v[168:171], v238 offset:50176
	ds_read_b128 v[172:175], v238 offset:51200
	ds_read_b128 v[176:179], v238 offset:52224
	global_load_lds_dwordx4 v[6:7], off
	s_add_i32 m0, s74, 0x2000
	s_add_u32 s76, s76, 0x40080
	v_lshl_add_u64 v[6:7], v[226:227], 0, s[18:19]
	s_addc_u32 s77, s77, 0
	s_add_i32 s74, s75, s7
	global_load_lds_dwordx4 v[6:7], off
	v_lshl_add_u64 v[6:7], s[76:77], 0, v[212:213]
	s_mov_b32 m0, s74
	ds_read_b128 v[180:183], v238 offset:53248
	global_load_lds_dwordx4 v[6:7], off
	v_lshl_add_u64 v[6:7], s[76:77], 0, v[208:209]
	s_add_i32 m0, s74, 0x2000
	ds_read_b128 v[184:187], v238 offset:54272
	global_load_lds_dwordx4 v[6:7], off
	v_lshl_add_u64 v[6:7], v[228:229], 0, s[18:19]
	s_mov_b32 m0, s56
	ds_read_b128 v[188:191], v238 offset:55296
	global_load_lds_dwordx4 v[6:7], off
	v_lshl_add_u64 v[6:7], v[230:231], 0, s[18:19]
	s_mov_b32 m0, s57
	ds_read_b128 v[220:223], v238 offset:56320
	global_load_lds_dwordx4 v[6:7], off
	s_waitcnt vmcnt(8)
	s_waitcnt lgkmcnt(0)
	s_barrier
	v_mfma_f32_16x16x32_bf16 v[64:67], v[132:135], v[164:167], v[64:67]
	v_mfma_f32_16x16x32_bf16 v[60:63], v[140:143], v[164:167], v[60:63]
	v_mfma_f32_16x16x32_bf16 v[48:51], v[132:135], v[172:175], v[48:51]
	v_mfma_f32_16x16x32_bf16 v[44:47], v[140:143], v[172:175], v[44:47]
	v_mfma_f32_16x16x32_bf16 v[32:35], v[132:135], v[180:183], v[32:35]
	v_mfma_f32_16x16x32_bf16 v[28:31], v[140:143], v[180:183], v[28:31]
	v_mfma_f32_16x16x32_bf16 v[16:19], v[132:135], v[188:191], v[16:19]
	v_mfma_f32_16x16x32_bf16 v[12:15], v[140:143], v[188:191], v[12:15]
	v_mfma_f32_16x16x32_bf16 v[64:67], v[136:139], v[168:171], v[64:67]
	v_mfma_f32_16x16x32_bf16 v[60:63], v[144:147], v[168:171], v[60:63]
	v_mfma_f32_16x16x32_bf16 v[48:51], v[136:139], v[176:179], v[48:51]
	v_mfma_f32_16x16x32_bf16 v[44:47], v[144:147], v[176:179], v[44:47]
	v_mfma_f32_16x16x32_bf16 v[32:35], v[136:139], v[184:187], v[32:35]
	v_mfma_f32_16x16x32_bf16 v[28:31], v[144:147], v[184:187], v[28:31]
	v_mfma_f32_16x16x32_bf16 v[16:19], v[136:139], v[220:223], v[16:19]
	v_mfma_f32_16x16x32_bf16 v[12:15], v[144:147], v[220:223], v[12:15]
	v_mfma_f32_16x16x32_bf16 v[56:59], v[148:151], v[164:167], v[56:59]
	v_mfma_f32_16x16x32_bf16 v[52:55], v[156:159], v[164:167], v[52:55]
	v_mfma_f32_16x16x32_bf16 v[40:43], v[148:151], v[172:175], v[40:43]
	v_mfma_f32_16x16x32_bf16 v[36:39], v[156:159], v[172:175], v[36:39]
	v_mfma_f32_16x16x32_bf16 v[24:27], v[148:151], v[180:183], v[24:27]
	v_mfma_f32_16x16x32_bf16 v[20:23], v[156:159], v[180:183], v[20:23]
	v_mfma_f32_16x16x32_bf16 v[6:9], v[148:151], v[188:191], v[8:11]
	v_mfma_f32_16x16x32_bf16 v[2:5], v[156:159], v[188:191], v[2:5]
	v_mfma_f32_16x16x32_bf16 v[56:59], v[152:155], v[168:171], v[56:59]
	v_mfma_f32_16x16x32_bf16 v[52:55], v[160:163], v[168:171], v[52:55]
	v_mfma_f32_16x16x32_bf16 v[40:43], v[152:155], v[176:179], v[40:43]
	v_mfma_f32_16x16x32_bf16 v[36:39], v[160:163], v[176:179], v[36:39]
	v_mfma_f32_16x16x32_bf16 v[24:27], v[152:155], v[184:187], v[24:27]
	v_mfma_f32_16x16x32_bf16 v[20:23], v[160:163], v[184:187], v[20:23]
	v_mfma_f32_16x16x32_bf16 v[8:11], v[152:155], v[220:223], v[6:9]
	v_mfma_f32_16x16x32_bf16 v[4:7], v[160:163], v[220:223], v[2:5]
	s_barrier
	s_add_u32 s50, s50, 0x100
	s_addc_u32 s51, s51, 0
	s_add_u32 s0, s0, 0x100
	s_addc_u32 s1, s1, 0
	s_cmp_ge_i32 s96, s26
	s_cbranch_scc1 .LBB0_839
	s_mov_b32 s76, s96
	s_cmp_lg_u32 s73, s76
	s_cbranch_scc0 .LBB0_836
	s_branch .LBB0_837

; #define PG8_STAGE(bufoff, gbase, voff) do { _Pragma("unroll") for (int _i = 0; _i < 2; ++_i) \
;         __builtin_amdgcn_global_load_lds((const unsigned*)((const char*)(gbase) + (voff)[_i]), (LAS unsigned*)(lds + (bufoff) + ldsw + _i * 8192), 16, 0, 0); } while (0)
; #define PG8_LDA(dst, b, h) do { _Pragma("unroll") for (int m = 0; m < 4; ++m) _Pragma("unroll") for (int k = 0; k < 2; ++k) dst[m][k] = *(const LAS bf16x8*)(lds + PG8_SA(b, h) + aoff + m * 2048 + k * 1024); } while (0)
; #define PG8_LDB(dst, b, h) do { _Pragma("unroll") for (int n = 0; n < 2; ++n) _Pragma("unroll") for (int k = 0; k < 2; ++k) dst[n][k] = *(const LAS bf16x8*)(lds + PG8_SB(b, h) + boff + n * 2048 + k * 1024); } while (0)
; #define PG8_MMA(ai, bj, At, Bt) do { __builtin_amdgcn_s_setprio(1); _Pragma("unroll") for (int m = 0; m < 4; ++m) _Pragma("unroll") for (int n = 0; n < 2; ++n) _Pragma("unroll") for (int k = 0; k < 2; ++k) \
;         acc[ai][bj][m][n] = __builtin_amdgcn_mfma_f32_16x16x32_bf16(Bt[n][k], At[m][k], acc[ai][bj][m][n], 0, 0, 0); __builtin_amdgcn_s_setprio(0); } while (0)
; #define PG8_WAIT_V(n) asm volatile("s_waitcnt vmcnt(" #n ")" ::: "memory")
; #define PG8_BAR __builtin_amdgcn_s_barrier()
; template <class Epi, class Sched>
; __device__ __forceinline__ void gemm_phase(LAS unsigned char* lds, const Gemm g, const Sched& S, const Epi& E) {
;     ...
;         for (int t = 0; t < nt; t += 2) {
;             const bool last = (t == nt - 2);
;             const char* a1 = cA + (size_t)(t + 1) * kstep;
;             const char* a2 = last ? nA : cA + (size_t)(t + 2) * kstep; const char* b2 = last ? nB : cB + (size_t)(t + 2) * kstep;
;             const char* a3 = a2 + kstep; const char* b3 = b2 + kstep;
;             if constexpr (Epi::MIDK) { if (t == (nt >> 1)) { int fr_ = fr, fq_ = fq; asm volatile("" : "+v"(fr_), "+v"(fq_)); E.mid(acc, cur, wr, wc, fr_, fq_); } }
;             PG8_LDB(B0, 0, 0); PG8_LDB(B1, 0, 1); PG8_SCHED; PG8_LDA(At, 0, 0); PG8_STAGE(PG8_SA(1, 1), a1 + hsA, voffA);
;             PG8_WAIT_V(8); PG8_WAIT_L(0); PG8_BAR; PG8_MMA(0, 0, At, B0); PG8_MMA(0, 1, At, B1); PG8_BAR; PG8_SCHED;
;             PG8_LDA(At, 0, 1); PG8_STAGE(PG8_SB(0, 0), b2, voffB); PG8_STAGE(PG8_SB(0, 1), b2 + hsB, voffB); PG8_STAGE(PG8_SA(0, 0), a2, voffA);
;             PG8_WAIT_V(8); PG8_WAIT_L(0); PG8_BAR; PG8_MMA(1, 0, At, B0); PG8_MMA(1, 1, At, B1); PG8_BAR; PG8_SCHED;
.Lnp_912:
.LBB0_912:
	s_add_i32 s96, s50, 2
	s_add_u32 s51, s0, 0xfffc0080
	s_addc_u32 s74, s1, -1
	s_add_i32 s75, 0, 0x10000
	s_cmp_eq_u32 s73, s50
	s_cselect_b32 s77, s39, s74
	s_cselect_b32 s76, s41, s51
	s_cselect_b32 s51, s82, s85
	s_cselect_b32 s50, s83, s84
	s_add_i32 s74, 0, 0x14000
	v_add_u32_e32 v142, s75, v184
	v_add_u32_e32 v168, s74, v184
	ds_read_b128 v[130:133], v142
	ds_read_b128 v[134:137], v142 offset:1024
	ds_read_b128 v[138:141], v142 offset:2048
	ds_read_b128 v[142:145], v142 offset:3072
	ds_read_b128 v[146:149], v168
	ds_read_b128 v[150:153], v168 offset:1024
	ds_read_b128 v[164:167], v168 offset:2048
	ds_read_b128 v[168:171], v168 offset:3072
	v_lshl_add_u64 v[180:181], s[0:1], 0, v[160:161]
	s_add_i32 m0, s11, 0xc000
	ds_read_b128 v[172:175], v185
	ds_read_b128 v[176:179], v185 offset:1024
	ds_read_b128 v[186:189], v185 offset:2048
	ds_read_b128 v[208:211], v185 offset:3072
	ds_read_b128 v[212:215], v185 offset:4096
	ds_read_b128 v[216:219], v185 offset:5120
	ds_read_b128 v[220:223], v185 offset:6144
	global_load_lds_dwordx4 v[180:181], off
	v_lshl_add_u64 v[180:181], s[0:1], 0, v[162:163]
	s_add_i32 m0, s11, 0xe000
	ds_read_b128 v[224:227], v185 offset:7168
	global_load_lds_dwordx4 v[180:181], off
	s_waitcnt vmcnt(8)
	s_waitcnt lgkmcnt(0)
	s_barrier
	v_mfma_f32_16x16x32_bf16 v[122:125], v[130:133], v[172:175], v[122:125]
	v_mfma_f32_16x16x32_bf16 v[126:129], v[138:141], v[172:175], v[126:129]
	v_mfma_f32_16x16x32_bf16 v[110:113], v[130:133], v[186:189], v[110:113]
	v_mfma_f32_16x16x32_bf16 v[106:109], v[138:141], v[186:189], v[106:109]
	v_mfma_f32_16x16x32_bf16 v[94:97], v[130:133], v[212:215], v[94:97]
	v_mfma_f32_16x16x32_bf16 v[90:93], v[138:141], v[212:215], v[90:93]
	v_mfma_f32_16x16x32_bf16 v[78:81], v[130:133], v[220:223], v[78:81]
	v_mfma_f32_16x16x32_bf16 v[74:77], v[138:141], v[220:223], v[74:77]
	v_mfma_f32_16x16x32_bf16 v[122:125], v[134:137], v[176:179], v[122:125]
	v_mfma_f32_16x16x32_bf16 v[126:129], v[142:145], v[176:179], v[126:129]
	v_mfma_f32_16x16x32_bf16 v[110:113], v[134:137], v[208:211], v[110:113]
	v_mfma_f32_16x16x32_bf16 v[106:109], v[142:145], v[208:211], v[106:109]
	v_mfma_f32_16x16x32_bf16 v[94:97], v[134:137], v[216:219], v[94:97]
	v_mfma_f32_16x16x32_bf16 v[90:93], v[142:145], v[216:219], v[90:93]
	v_mfma_f32_16x16x32_bf16 v[78:81], v[134:137], v[224:227], v[78:81]
	v_mfma_f32_16x16x32_bf16 v[74:77], v[142:145], v[224:227], v[74:77]
	v_mfma_f32_16x16x32_bf16 v[118:121], v[146:149], v[172:175], v[118:121]
	v_mfma_f32_16x16x32_bf16 v[114:117], v[164:167], v[172:175], v[114:117]
	v_mfma_f32_16x16x32_bf16 v[102:105], v[146:149], v[186:189], v[102:105]
	v_mfma_f32_16x16x32_bf16 v[98:101], v[164:167], v[186:189], v[98:101]
	v_mfma_f32_16x16x32_bf16 v[86:89], v[146:149], v[212:215], v[86:89]
	v_mfma_f32_16x16x32_bf16 v[82:85], v[164:167], v[212:215], v[82:85]
	v_mfma_f32_16x16x32_bf16 v[70:73], v[146:149], v[220:223], v[70:73]
	v_mfma_f32_16x16x32_bf16 v[66:69], v[164:167], v[220:223], v[66:69]
	v_mfma_f32_16x16x32_bf16 v[118:121], v[150:153], v[176:179], v[118:121]
	v_mfma_f32_16x16x32_bf16 v[114:117], v[168:171], v[176:179], v[114:117]
	v_mfma_f32_16x16x32_bf16 v[102:105], v[150:153], v[208:211], v[102:105]
	v_mfma_f32_16x16x32_bf16 v[98:101], v[168:171], v[208:211], v[98:101]
	v_mfma_f32_16x16x32_bf16 v[86:89], v[150:153], v[216:219], v[86:89]
	v_mfma_f32_16x16x32_bf16 v[82:85], v[168:171], v[216:219], v[82:85]
	v_mfma_f32_16x16x32_bf16 v[70:73], v[150:153], v[224:227], v[70:73]
	v_mfma_f32_16x16x32_bf16 v[66:69], v[168:171], v[224:227], v[66:69]
	s_barrier
	s_add_i32 s75, s75, s7
	v_lshl_add_u64 v[180:181], s[50:51], 0, v[0:1]
	s_mov_b32 m0, s75
	ds_read_b128 v[172:175], v185 offset:16384
	ds_read_b128 v[176:179], v185 offset:17408
	ds_read_b128 v[186:189], v185 offset:18432
	ds_read_b128 v[208:211], v185 offset:19456
	ds_read_b128 v[212:215], v185 offset:20480
	global_load_lds_dwordx4 v[180:181], off
	s_add_i32 m0, s75, 0x2000
	s_add_u32 vcc_lo, s50, 0x40000
	v_lshl_add_u64 v[190:191], s[50:51], 0, v[154:155]
	s_addc_u32 vcc_hi, s51, 0
	s_add_i32 s74, s74, s7
	global_load_lds_dwordx4 v[190:191], off
	v_lshl_add_u64 v[228:229], vcc, 0, v[0:1]
	s_mov_b32 m0, s74
	v_lshl_add_u64 v[230:231], s[76:77], 0, v[156:157]
	global_load_lds_dwordx4 v[228:229], off
	v_lshl_add_u64 v[228:229], vcc, 0, v[154:155]
	s_add_i32 m0, s74, 0x2000
	ds_read_b128 v[216:219], v185 offset:21504
	global_load_lds_dwordx4 v[228:229], off
	v_lshl_add_u64 v[228:229], s[76:77], 0, v[158:159]
	s_mov_b32 m0, s11
	ds_read_b128 v[220:223], v185 offset:22528
	global_load_lds_dwordx4 v[228:229], off
	s_mov_b32 m0, s12
	ds_read_b128 v[224:227], v185 offset:23552
	global_load_lds_dwordx4 v[230:231], off
	s_waitcnt vmcnt(8)
	s_waitcnt lgkmcnt(0)
	s_barrier
; #define PG8_STAGE(bufoff, gbase, voff) do { _Pragma("unroll") for (int _i = 0; _i < 2; ++_i) \
;         __builtin_amdgcn_global_load_lds((const unsigned*)((const char*)(gbase) + (voff)[_i]), (LAS unsigned*)(lds + (bufoff) + ldsw + _i * 8192), 16, 0, 0); } while (0)
; #define PG8_LDA(dst, b, h) do { _Pragma("unroll") for (int m = 0; m < 4; ++m) _Pragma("unroll") for (int k = 0; k < 2; ++k) dst[m][k] = *(const LAS bf16x8*)(lds + PG8_SA(b, h) + aoff + m * 2048 + k * 1024); } while (0)
; #define PG8_LDB(dst, b, h) do { _Pragma("unroll") for (int n = 0; n < 2; ++n) _Pragma("unroll") for (int k = 0; k < 2; ++k) dst[n][k] = *(const LAS bf16x8*)(lds + PG8_SB(b, h) + boff + n * 2048 + k * 1024); } while (0)
; #define PG8_MMA(ai, bj, At, Bt) do { __builtin_amdgcn_s_setprio(1); _Pragma("unroll") for (int m = 0; m < 4; ++m) _Pragma("unroll") for (int n = 0; n < 2; ++n) _Pragma("unroll") for (int k = 0; k < 2; ++k) \
;         acc[ai][bj][m][n] = __builtin_amdgcn_mfma_f32_16x16x32_bf16(Bt[n][k], At[m][k], acc[ai][bj][m][n], 0, 0, 0); __builtin_amdgcn_s_setprio(0); } while (0)
; #define PG8_WAIT_V(n) asm volatile("s_waitcnt vmcnt(" #n ")" ::: "memory")
; #define PG8_WAIT_L(n) asm volatile("s_waitcnt lgkmcnt(" #n ")" ::: "memory")
; #define PG8_BAR __builtin_amdgcn_s_barrier()
; #define PG8_SCHED __builtin_amdgcn_sched_barrier(0)
; template <class Epi, class Sched>
; __device__ __forceinline__ void gemm_phase(LAS unsigned char* lds, const Gemm g, const Sched& S, const Epi& E) {
;     ...
;             PG8_LDA(At, 0, 1); PG8_STAGE(PG8_SB(0, 0), b2, voffB); PG8_STAGE(PG8_SB(0, 1), b2 + hsB, voffB); PG8_STAGE(PG8_SA(0, 0), a2, voffA);
;             PG8_WAIT_V(8); PG8_WAIT_L(0); PG8_BAR; PG8_MMA(1, 0, At, B0); PG8_MMA(1, 1, At, B1); PG8_BAR; PG8_SCHED;
;             PG8_LDB(B0, 1, 0); PG8_LDB(B1, 1, 1); PG8_SCHED; PG8_LDA(At, 1, 0); PG8_STAGE(PG8_SA(0, 1), a2 + hsA, voffA);
;             PG8_WAIT_V(8); PG8_WAIT_L(0); PG8_BAR; PG8_MMA(0, 0, At, B0); PG8_MMA(0, 1, At, B1); PG8_BAR; PG8_SCHED;
	v_mfma_f32_16x16x32_bf16 v[62:65], v[130:133], v[172:175], v[62:65]
	v_mfma_f32_16x16x32_bf16 v[58:61], v[138:141], v[172:175], v[58:61]
	v_mfma_f32_16x16x32_bf16 v[46:49], v[130:133], v[186:189], v[46:49]
	v_mfma_f32_16x16x32_bf16 v[42:45], v[138:141], v[186:189], v[42:45]
	v_mfma_f32_16x16x32_bf16 v[30:33], v[130:133], v[212:215], v[30:33]
	v_mfma_f32_16x16x32_bf16 v[26:29], v[138:141], v[212:215], v[26:29]
	v_mfma_f32_16x16x32_bf16 v[14:17], v[130:133], v[220:223], v[14:17]
	v_mfma_f32_16x16x32_bf16 v[10:13], v[138:141], v[220:223], v[10:13]
	v_mfma_f32_16x16x32_bf16 v[62:65], v[134:137], v[176:179], v[62:65]
	v_mfma_f32_16x16x32_bf16 v[58:61], v[142:145], v[176:179], v[58:61]
	v_mfma_f32_16x16x32_bf16 v[46:49], v[134:137], v[208:211], v[46:49]
	v_mfma_f32_16x16x32_bf16 v[42:45], v[142:145], v[208:211], v[42:45]
	v_mfma_f32_16x16x32_bf16 v[30:33], v[134:137], v[216:219], v[30:33]
	v_mfma_f32_16x16x32_bf16 v[26:29], v[142:145], v[216:219], v[26:29]
	v_mfma_f32_16x16x32_bf16 v[14:17], v[134:137], v[224:227], v[14:17]
	v_mfma_f32_16x16x32_bf16 v[10:13], v[142:145], v[224:227], v[10:13]
	v_mfma_f32_16x16x32_bf16 v[54:57], v[146:149], v[172:175], v[54:57]
	v_mfma_f32_16x16x32_bf16 v[50:53], v[164:167], v[172:175], v[50:53]
	v_mfma_f32_16x16x32_bf16 v[38:41], v[146:149], v[186:189], v[38:41]
	v_mfma_f32_16x16x32_bf16 v[34:37], v[164:167], v[186:189], v[34:37]
	v_mfma_f32_16x16x32_bf16 v[22:25], v[146:149], v[212:215], v[22:25]
	v_mfma_f32_16x16x32_bf16 v[18:21], v[164:167], v[212:215], v[18:21]
	v_mfma_f32_16x16x32_bf16 v[6:9], v[146:149], v[220:223], v[6:9]
	v_mfma_f32_16x16x32_bf16 v[2:5], v[164:167], v[220:223], v[2:5]
	v_mfma_f32_16x16x32_bf16 v[54:57], v[150:153], v[176:179], v[54:57]
	v_mfma_f32_16x16x32_bf16 v[50:53], v[168:171], v[176:179], v[50:53]
	v_mfma_f32_16x16x32_bf16 v[38:41], v[150:153], v[208:211], v[38:41]
	v_mfma_f32_16x16x32_bf16 v[34:37], v[168:171], v[208:211], v[34:37]
	v_mfma_f32_16x16x32_bf16 v[22:25], v[150:153], v[216:219], v[22:25]
	v_mfma_f32_16x16x32_bf16 v[18:21], v[168:171], v[216:219], v[18:21]
	v_mfma_f32_16x16x32_bf16 v[6:9], v[150:153], v[224:227], v[6:9]
	v_mfma_f32_16x16x32_bf16 v[2:5], v[168:171], v[224:227], v[2:5]
	s_barrier
	s_add_i32 s74, 0, 0x18000
	s_add_i32 s75, 0, 0x1c000
	v_add_u32_e32 v142, s74, v184
	v_add_u32_e32 v168, s75, v184
	ds_read_b128 v[130:133], v142
	ds_read_b128 v[134:137], v142 offset:1024
	ds_read_b128 v[138:141], v142 offset:2048
	ds_read_b128 v[142:145], v142 offset:3072
	ds_read_b128 v[146:149], v168
	ds_read_b128 v[150:153], v168 offset:1024
	ds_read_b128 v[164:167], v168 offset:2048
	ds_read_b128 v[168:171], v168 offset:3072
	s_add_u32 s76, s76, 0x40000
	s_addc_u32 s77, s77, 0
	s_mov_b32 m0, s16
	v_lshl_add_u64 v[232:233], s[76:77], 0, v[158:159]
	ds_read_b128 v[172:175], v185 offset:32768
	ds_read_b128 v[176:179], v185 offset:33792
	ds_read_b128 v[186:189], v185 offset:34816
	ds_read_b128 v[208:211], v185 offset:35840
	ds_read_b128 v[212:215], v185 offset:36864
	ds_read_b128 v[216:219], v185 offset:37888
	ds_read_b128 v[220:223], v185 offset:38912
	global_load_lds_dwordx4 v[232:233], off
	v_lshl_add_u64 v[232:233], s[76:77], 0, v[156:157]
	s_mov_b32 m0, s24
	ds_read_b128 v[224:227], v185 offset:39936
	global_load_lds_dwordx4 v[232:233], off
	s_waitcnt vmcnt(8)
	s_waitcnt lgkmcnt(0)
	s_barrier
	v_mfma_f32_16x16x32_bf16 v[122:125], v[130:133], v[172:175], v[122:125]
	v_mfma_f32_16x16x32_bf16 v[126:129], v[138:141], v[172:175], v[126:129]
	v_mfma_f32_16x16x32_bf16 v[110:113], v[130:133], v[186:189], v[110:113]
	v_mfma_f32_16x16x32_bf16 v[106:109], v[138:141], v[186:189], v[106:109]
	v_mfma_f32_16x16x32_bf16 v[94:97], v[130:133], v[212:215], v[94:97]
	v_mfma_f32_16x16x32_bf16 v[90:93], v[138:141], v[212:215], v[90:93]
	v_mfma_f32_16x16x32_bf16 v[78:81], v[130:133], v[220:223], v[78:81]
	v_mfma_f32_16x16x32_bf16 v[74:77], v[138:141], v[220:223], v[74:77]
	v_mfma_f32_16x16x32_bf16 v[122:125], v[134:137], v[176:179], v[122:125]
	v_mfma_f32_16x16x32_bf16 v[126:129], v[142:145], v[176:179], v[126:129]
	v_mfma_f32_16x16x32_bf16 v[110:113], v[134:137], v[208:211], v[110:113]
	v_mfma_f32_16x16x32_bf16 v[106:109], v[142:145], v[208:211], v[106:109]
	v_mfma_f32_16x16x32_bf16 v[94:97], v[134:137], v[216:219], v[94:97]
	v_mfma_f32_16x16x32_bf16 v[90:93], v[142:145], v[216:219], v[90:93]
	v_mfma_f32_16x16x32_bf16 v[78:81], v[134:137], v[224:227], v[78:81]
	v_mfma_f32_16x16x32_bf16 v[74:77], v[142:145], v[224:227], v[74:77]
	v_mfma_f32_16x16x32_bf16 v[118:121], v[146:149], v[172:175], v[118:121]
	v_mfma_f32_16x16x32_bf16 v[114:117], v[164:167], v[172:175], v[114:117]
	v_mfma_f32_16x16x32_bf16 v[102:105], v[146:149], v[186:189], v[102:105]
	v_mfma_f32_16x16x32_bf16 v[98:101], v[164:167], v[186:189], v[98:101]
	v_mfma_f32_16x16x32_bf16 v[86:89], v[146:149], v[212:215], v[86:89]
	v_mfma_f32_16x16x32_bf16 v[82:85], v[164:167], v[212:215], v[82:85]
	v_mfma_f32_16x16x32_bf16 v[70:73], v[146:149], v[220:223], v[70:73]
	v_mfma_f32_16x16x32_bf16 v[66:69], v[164:167], v[220:223], v[66:69]
	v_mfma_f32_16x16x32_bf16 v[118:121], v[150:153], v[176:179], v[118:121]
	v_mfma_f32_16x16x32_bf16 v[114:117], v[168:171], v[176:179], v[114:117]
	v_mfma_f32_16x16x32_bf16 v[102:105], v[150:153], v[208:211], v[102:105]
	v_mfma_f32_16x16x32_bf16 v[98:101], v[168:171], v[208:211], v[98:101]
	v_mfma_f32_16x16x32_bf16 v[86:89], v[150:153], v[216:219], v[86:89]
	v_mfma_f32_16x16x32_bf16 v[82:85], v[168:171], v[216:219], v[82:85]
	v_mfma_f32_16x16x32_bf16 v[70:73], v[150:153], v[224:227], v[70:73]
	v_mfma_f32_16x16x32_bf16 v[66:69], v[168:171], v[224:227], v[66:69]
	s_barrier
; #define PG8_STAGE(bufoff, gbase, voff) do { _Pragma("unroll") for (int _i = 0; _i < 2; ++_i) \
;         __builtin_amdgcn_global_load_lds((const unsigned*)((const char*)(gbase) + (voff)[_i]), (LAS unsigned*)(lds + (bufoff) + ldsw + _i * 8192), 16, 0, 0); } while (0)
; #define PG8_LDA(dst, b, h) do { _Pragma("unroll") for (int m = 0; m < 4; ++m) _Pragma("unroll") for (int k = 0; k < 2; ++k) dst[m][k] = *(const LAS bf16x8*)(lds + PG8_SA(b, h) + aoff + m * 2048 + k * 1024); } while (0)
; #define PG8_MMA(ai, bj, At, Bt) do { __builtin_amdgcn_s_setprio(1); _Pragma("unroll") for (int m = 0; m < 4; ++m) _Pragma("unroll") for (int n = 0; n < 2; ++n) _Pragma("unroll") for (int k = 0; k < 2; ++k) \
;         acc[ai][bj][m][n] = __builtin_amdgcn_mfma_f32_16x16x32_bf16(Bt[n][k], At[m][k], acc[ai][bj][m][n], 0, 0, 0); __builtin_amdgcn_s_setprio(0); } while (0)
; #define PG8_WAIT_V(n) asm volatile("s_waitcnt vmcnt(" #n ")" ::: "memory")
; #define PG8_WAIT_L(n) asm volatile("s_waitcnt lgkmcnt(" #n ")" ::: "memory")
; #define PG8_BAR __builtin_amdgcn_s_barrier()
; #define PG8_SCHED __builtin_amdgcn_sched_barrier(0)
; template <class Epi, class Sched>
; __device__ __forceinline__ void gemm_phase(LAS unsigned char* lds, const Gemm g, const Sched& S, const Epi& E) {
;     ...
;             PG8_LDA(At, 1, 1); PG8_STAGE(PG8_SB(1, 0), b3, voffB); PG8_STAGE(PG8_SB(1, 1), b3 + hsB, voffB); PG8_STAGE(PG8_SA(1, 0), a3, voffA);
;             PG8_WAIT_V(8); PG8_WAIT_L(0); PG8_BAR; PG8_MMA(1, 0, At, B0); PG8_MMA(1, 1, At, B1); PG8_BAR; PG8_SCHED;
;         }
	s_add_i32 s74, s74, s7
	v_lshl_add_u64 v[180:181], v[180:181], 0, s[18:19]
	s_mov_b32 m0, s74
	ds_read_b128 v[172:175], v185 offset:49152
	ds_read_b128 v[176:179], v185 offset:50176
	ds_read_b128 v[186:189], v185 offset:51200
	ds_read_b128 v[208:211], v185 offset:52224
	global_load_lds_dwordx4 v[180:181], off
	s_add_i32 m0, s74, 0x2000
	s_add_u32 s50, s50, 0x40080
	v_lshl_add_u64 v[180:181], v[190:191], 0, s[18:19]
	s_addc_u32 s51, s51, 0
	s_add_i32 s74, s75, s7
	global_load_lds_dwordx4 v[180:181], off
	v_lshl_add_u64 v[180:181], s[50:51], 0, v[0:1]
	s_mov_b32 m0, s74
	ds_read_b128 v[212:215], v185 offset:53248
	global_load_lds_dwordx4 v[180:181], off
	v_lshl_add_u64 v[180:181], s[50:51], 0, v[154:155]
	s_add_i32 m0, s74, 0x2000
	ds_read_b128 v[216:219], v185 offset:54272
	global_load_lds_dwordx4 v[180:181], off
	v_lshl_add_u64 v[180:181], v[228:229], 0, s[18:19]
	s_mov_b32 m0, s57
	ds_read_b128 v[220:223], v185 offset:55296
	global_load_lds_dwordx4 v[180:181], off
	v_lshl_add_u64 v[180:181], v[230:231], 0, s[18:19]
	s_mov_b32 m0, s64
	ds_read_b128 v[224:227], v185 offset:56320
	global_load_lds_dwordx4 v[180:181], off
	s_waitcnt vmcnt(8)
	s_waitcnt lgkmcnt(0)
	s_barrier
	v_mfma_f32_16x16x32_bf16 v[62:65], v[130:133], v[172:175], v[62:65]
	v_mfma_f32_16x16x32_bf16 v[58:61], v[138:141], v[172:175], v[58:61]
	v_mfma_f32_16x16x32_bf16 v[46:49], v[130:133], v[186:189], v[46:49]
	v_mfma_f32_16x16x32_bf16 v[42:45], v[138:141], v[186:189], v[42:45]
	v_mfma_f32_16x16x32_bf16 v[30:33], v[130:133], v[212:215], v[30:33]
	v_mfma_f32_16x16x32_bf16 v[26:29], v[138:141], v[212:215], v[26:29]
	v_mfma_f32_16x16x32_bf16 v[14:17], v[130:133], v[220:223], v[14:17]
	v_mfma_f32_16x16x32_bf16 v[10:13], v[138:141], v[220:223], v[10:13]
	v_mfma_f32_16x16x32_bf16 v[62:65], v[134:137], v[176:179], v[62:65]
	v_mfma_f32_16x16x32_bf16 v[58:61], v[142:145], v[176:179], v[58:61]
	v_mfma_f32_16x16x32_bf16 v[46:49], v[134:137], v[208:211], v[46:49]
	v_mfma_f32_16x16x32_bf16 v[42:45], v[142:145], v[208:211], v[42:45]
	v_mfma_f32_16x16x32_bf16 v[30:33], v[134:137], v[216:219], v[30:33]
	v_mfma_f32_16x16x32_bf16 v[26:29], v[142:145], v[216:219], v[26:29]
	v_mfma_f32_16x16x32_bf16 v[14:17], v[134:137], v[224:227], v[14:17]
	v_mfma_f32_16x16x32_bf16 v[10:13], v[142:145], v[224:227], v[10:13]
	v_mfma_f32_16x16x32_bf16 v[54:57], v[146:149], v[172:175], v[54:57]
	v_mfma_f32_16x16x32_bf16 v[50:53], v[164:167], v[172:175], v[50:53]
	v_mfma_f32_16x16x32_bf16 v[38:41], v[146:149], v[186:189], v[38:41]
	v_mfma_f32_16x16x32_bf16 v[34:37], v[164:167], v[186:189], v[34:37]
	v_mfma_f32_16x16x32_bf16 v[22:25], v[146:149], v[212:215], v[22:25]
	v_mfma_f32_16x16x32_bf16 v[18:21], v[164:167], v[212:215], v[18:21]
	v_mfma_f32_16x16x32_bf16 v[6:9], v[146:149], v[220:223], v[6:9]
	v_mfma_f32_16x16x32_bf16 v[2:5], v[164:167], v[220:223], v[2:5]
	v_mfma_f32_16x16x32_bf16 v[54:57], v[150:153], v[176:179], v[54:57]
	v_mfma_f32_16x16x32_bf16 v[50:53], v[168:171], v[176:179], v[50:53]
	v_mfma_f32_16x16x32_bf16 v[38:41], v[150:153], v[208:211], v[38:41]
	v_mfma_f32_16x16x32_bf16 v[34:37], v[168:171], v[208:211], v[34:37]
	v_mfma_f32_16x16x32_bf16 v[22:25], v[150:153], v[216:219], v[22:25]
	v_mfma_f32_16x16x32_bf16 v[18:21], v[168:171], v[216:219], v[18:21]
	v_mfma_f32_16x16x32_bf16 v[6:9], v[150:153], v[224:227], v[6:9]
	v_mfma_f32_16x16x32_bf16 v[2:5], v[168:171], v[224:227], v[2:5]
	s_barrier
	s_add_u32 s0, s0, 0x100
	s_addc_u32 s1, s1, 0
	s_add_u32 s84, s84, 0x100
	s_addc_u32 s85, s85, 0
	s_cmp_ge_i32 s96, s30
	s_mov_b32 s50, s96
	s_cbranch_scc0 .LBB0_912
	s_setprio 0
	v_readlane_b32 s82, v254, 45
	v_readlane_b32 s83, v254, 46
	v_readlane_b32 s96, v250, 43
